# MFMA issue order inside each K-loop segment changed to a snake so consecutive MFMAs share one operand fragment
# speedup vs baseline: 1.0077x; 1.0063x over previous
; #define PG8_STAGE(bufoff, gbase, voff) do { if constexpr (VAR != 1 && VAR != 3) { _Pragma("unroll") for (int _i = 0; _i < 2; ++_i) \
;         asm volatile("s_mov_b32 m0, %2\n\ts_nop 0\n\tglobal_load_lds_dwordx4 %0, %1" :: "v"((voff)[_i]), "s"((const char*)(gbase)), "s"(ldsbase + (unsigned)((bufoff) + _i * 8192)) : "memory", "m0"); } } while (0)
; #define PG8_LDA(dst, b, h) do { if constexpr (VAR < 2) _Pragma("unroll") for (int m = 0; m < 4; ++m) _Pragma("unroll") for (int k = 0; k < 2; ++k) dst[m][k] = *(const LAS bf16x8*)(lds + PG8_SA(b, h) + aoff + m * 2048 + k * 1024); } while (0)
; #define PG8_LDB(dst, b, h) do { if constexpr (VAR < 2) _Pragma("unroll") for (int n = 0; n < 2; ++n) _Pragma("unroll") for (int k = 0; k < 2; ++k) dst[n][k] = *(const LAS bf16x8*)(lds + PG8_SB(b, h) + boff + n * 2048 + k * 1024); } while (0)
; #define PG8_WAIT_V(n) asm volatile("s_waitcnt vmcnt(" #n ")" ::: "memory")
; #define PG8_WAIT_L(n) asm volatile("s_waitcnt lgkmcnt(" #n ")" ::: "memory")
; #define PG8_BAR do { if constexpr (VAR != 3) __builtin_amdgcn_s_barrier(); } while (0)
; #define PG8_SCHED __builtin_amdgcn_sched_barrier(0)
;     ...
;             PG8_LDB(B0, 0, 0); PG8_LDB(B1, 0, 1); PG8_SCHED; PG8_LDA(At, 0, 0); PG8_STAGE(PG8_SA(1, 1), a1 + hstepA, voffA);
;             PG8_WAIT_V(8); PG8_WAIT_L(0); PG8_BAR; PG8_MMA(0, 0, At, B0); PG8_MMA(0, 1, At, B1); PG8_BAR; PG8_SCHED;
;             PG8_LDA(At, 0, 1); PG8_STAGE(PG8_SB(0, 0), b2, voffB); PG8_STAGE(PG8_SB(0, 1), b2 + hstepB, voffB); PG8_STAGE(PG8_SA(0, 0), a2, voffA);
;             PG8_WAIT_V(8); PG8_WAIT_L(0); PG8_BAR; PG8_MMA(1, 0, At, B0); PG8_MMA(1, 1, At, B1); PG8_BAR; PG8_SCHED;
.LBB0_346:
	ds_read_b128 v[156:159], v151
	ds_read_b128 v[160:163], v151 offset:1024
	ds_read_b128 v[164:167], v151 offset:2048
	ds_read_b128 v[168:171], v151 offset:3072
	ds_read_b128 v[172:175], v152
	ds_read_b128 v[176:179], v152 offset:1024
	ds_read_b128 v[180:183], v152 offset:2048
	ds_read_b128 v[184:187], v152 offset:3072
	s_cmp_eq_u32 vcc_hi, 60
	s_cselect_b32 s96, s15, s66
	s_cselect_b32 s97, s14, s67
	s_cselect_b32 s94, s65, s69
	s_cselect_b32 s95, s63, vcc_lo
	s_add_u32 s92, s96, 0x80
	s_addc_u32 s93, s97, 0
	ds_read_b128 v[188:191], v153
	ds_read_b128 v[192:195], v153 offset:1024
	ds_read_b128 v[196:199], v153 offset:2048
	ds_read_b128 v[200:203], v153 offset:3072
	ds_read_b128 v[204:207], v153 offset:4096
	ds_read_b128 v[208:211], v153 offset:5120
	ds_read_b128 v[212:215], v153 offset:6144
	ds_read_b128 v[216:219], v153 offset:7168
	s_mov_b32 m0, s56
	s_nop 0
	global_load_lds_dwordx4 v1, s[90:91]
	s_nop 0
	s_mov_b32 m0, s57
	s_nop 0
	global_load_lds_dwordx4 v147, s[90:91]
	s_waitcnt vmcnt(8)
	s_waitcnt lgkmcnt(0)
	s_barrier
	s_setprio 1
	s_waitcnt lgkmcnt(7)
	v_mfma_f32_16x16x32_bf16 v[126:129], v[156:159], v[188:191], v[126:129]
	v_mfma_f32_16x16x32_bf16 v[122:125], v[164:167], v[188:191], v[122:125]
	s_waitcnt lgkmcnt(5)
	v_mfma_f32_16x16x32_bf16 v[110:113], v[164:167], v[196:199], v[110:113]
	v_mfma_f32_16x16x32_bf16 v[118:121], v[156:159], v[196:199], v[118:121]
	s_waitcnt lgkmcnt(3)
	v_mfma_f32_16x16x32_bf16 v[102:105], v[156:159], v[204:207], v[102:105]
	v_mfma_f32_16x16x32_bf16 v[94:97], v[164:167], v[204:207], v[94:97]
	s_waitcnt lgkmcnt(1)
	v_mfma_f32_16x16x32_bf16 v[78:81], v[164:167], v[212:215], v[78:81]
	v_mfma_f32_16x16x32_bf16 v[86:89], v[156:159], v[212:215], v[86:89]
	v_mfma_f32_16x16x32_bf16 v[126:129], v[160:163], v[192:195], v[126:129]
	v_mfma_f32_16x16x32_bf16 v[122:125], v[168:171], v[192:195], v[122:125]
	v_mfma_f32_16x16x32_bf16 v[110:113], v[168:171], v[200:203], v[110:113]
	v_mfma_f32_16x16x32_bf16 v[118:121], v[160:163], v[200:203], v[118:121]
	v_mfma_f32_16x16x32_bf16 v[102:105], v[160:163], v[208:211], v[102:105]
	v_mfma_f32_16x16x32_bf16 v[94:97], v[168:171], v[208:211], v[94:97]
	s_waitcnt lgkmcnt(0)
	v_mfma_f32_16x16x32_bf16 v[78:81], v[168:171], v[216:219], v[78:81]
	v_mfma_f32_16x16x32_bf16 v[86:89], v[160:163], v[216:219], v[86:89]
	s_setprio 0
	s_setprio 1
	v_mfma_f32_16x16x32_bf16 v[114:117], v[172:175], v[188:191], v[114:117]
	v_mfma_f32_16x16x32_bf16 v[106:109], v[180:183], v[188:191], v[106:109]
	v_mfma_f32_16x16x32_bf16 v[90:93], v[180:183], v[196:199], v[90:93]
	v_mfma_f32_16x16x32_bf16 v[98:101], v[172:175], v[196:199], v[98:101]
	v_mfma_f32_16x16x32_bf16 v[82:85], v[172:175], v[204:207], v[82:85]
	v_mfma_f32_16x16x32_bf16 v[74:77], v[180:183], v[204:207], v[74:77]
	v_mfma_f32_16x16x32_bf16 v[66:69], v[180:183], v[212:215], v[66:69]
	v_mfma_f32_16x16x32_bf16 v[70:73], v[172:175], v[212:215], v[70:73]
	v_mfma_f32_16x16x32_bf16 v[114:117], v[176:179], v[192:195], v[114:117]
	v_mfma_f32_16x16x32_bf16 v[106:109], v[184:187], v[192:195], v[106:109]
	v_mfma_f32_16x16x32_bf16 v[90:93], v[184:187], v[200:203], v[90:93]
	v_mfma_f32_16x16x32_bf16 v[98:101], v[176:179], v[200:203], v[98:101]
	v_mfma_f32_16x16x32_bf16 v[82:85], v[176:179], v[208:211], v[82:85]
	v_mfma_f32_16x16x32_bf16 v[74:77], v[184:187], v[208:211], v[74:77]
	v_mfma_f32_16x16x32_bf16 v[66:69], v[184:187], v[216:219], v[66:69]
	v_mfma_f32_16x16x32_bf16 v[70:73], v[176:179], v[216:219], v[70:73]
	s_setprio 0
	s_barrier
	ds_read_b128 v[188:191], v153 offset:16384
	ds_read_b128 v[192:195], v153 offset:17408
	ds_read_b128 v[196:199], v153 offset:18432
	ds_read_b128 v[200:203], v153 offset:19456
	ds_read_b128 v[204:207], v153 offset:20480
	ds_read_b128 v[208:211], v153 offset:21504
	ds_read_b128 v[212:215], v153 offset:22528
	ds_read_b128 v[216:219], v153 offset:23552
	s_mov_b32 m0, s25
	s_nop 0
	global_load_lds_dwordx4 v146, s[94:95]
	s_add_u32 s6, s94, 0x100000
	s_mov_b32 m0, s26
	s_nop 0
	global_load_lds_dwordx4 v148, s[94:95]
	s_addc_u32 s7, s95, 0
	s_mov_b32 m0, s27
	s_nop 0
	global_load_lds_dwordx4 v146, s[6:7]
	s_nop 0
	s_mov_b32 m0, s28
	s_nop 0
	global_load_lds_dwordx4 v148, s[6:7]
	s_nop 0
	s_mov_b32 m0, s19
	s_nop 0
	global_load_lds_dwordx4 v1, s[96:97]
	s_nop 0
	s_mov_b32 m0, s29
	s_nop 0
	global_load_lds_dwordx4 v147, s[96:97]
	s_waitcnt vmcnt(8)
	s_waitcnt lgkmcnt(0)
	s_barrier
	s_setprio 1
	s_waitcnt lgkmcnt(7)
	v_mfma_f32_16x16x32_bf16 v[62:65], v[156:159], v[188:191], v[62:65]
	v_mfma_f32_16x16x32_bf16 v[58:61], v[164:167], v[188:191], v[58:61]
	s_waitcnt lgkmcnt(5)
	v_mfma_f32_16x16x32_bf16 v[46:49], v[164:167], v[196:199], v[46:49]
	v_mfma_f32_16x16x32_bf16 v[54:57], v[156:159], v[196:199], v[54:57]
	s_waitcnt lgkmcnt(3)
	v_mfma_f32_16x16x32_bf16 v[38:41], v[156:159], v[204:207], v[38:41]
	v_mfma_f32_16x16x32_bf16 v[30:33], v[164:167], v[204:207], v[30:33]
	s_waitcnt lgkmcnt(1)
	v_mfma_f32_16x16x32_bf16 v[14:17], v[164:167], v[212:215], v[14:17]
	v_mfma_f32_16x16x32_bf16 v[22:25], v[156:159], v[212:215], v[22:25]
	v_mfma_f32_16x16x32_bf16 v[62:65], v[160:163], v[192:195], v[62:65]
	v_mfma_f32_16x16x32_bf16 v[58:61], v[168:171], v[192:195], v[58:61]
	v_mfma_f32_16x16x32_bf16 v[46:49], v[168:171], v[200:203], v[46:49]
	v_mfma_f32_16x16x32_bf16 v[54:57], v[160:163], v[200:203], v[54:57]
	v_mfma_f32_16x16x32_bf16 v[38:41], v[160:163], v[208:211], v[38:41]
	v_mfma_f32_16x16x32_bf16 v[30:33], v[168:171], v[208:211], v[30:33]
	s_waitcnt lgkmcnt(0)
	v_mfma_f32_16x16x32_bf16 v[14:17], v[168:171], v[216:219], v[14:17]
	v_mfma_f32_16x16x32_bf16 v[22:25], v[160:163], v[216:219], v[22:25]
	s_setprio 0
	s_setprio 1
	v_mfma_f32_16x16x32_bf16 v[50:53], v[172:175], v[188:191], v[50:53]
	v_mfma_f32_16x16x32_bf16 v[42:45], v[180:183], v[188:191], v[42:45]
	v_mfma_f32_16x16x32_bf16 v[26:29], v[180:183], v[196:199], v[26:29]
	v_mfma_f32_16x16x32_bf16 v[34:37], v[172:175], v[196:199], v[34:37]
	v_mfma_f32_16x16x32_bf16 v[18:21], v[172:175], v[204:207], v[18:21]
	v_mfma_f32_16x16x32_bf16 v[10:13], v[180:183], v[204:207], v[10:13]
	v_mfma_f32_16x16x32_bf16 v[2:5], v[180:183], v[212:215], v[2:5]
	v_mfma_f32_16x16x32_bf16 v[6:9], v[172:175], v[212:215], v[6:9]
	v_mfma_f32_16x16x32_bf16 v[50:53], v[176:179], v[192:195], v[50:53]
	v_mfma_f32_16x16x32_bf16 v[42:45], v[184:187], v[192:195], v[42:45]
	v_mfma_f32_16x16x32_bf16 v[26:29], v[184:187], v[200:203], v[26:29]
	v_mfma_f32_16x16x32_bf16 v[34:37], v[176:179], v[200:203], v[34:37]
	v_mfma_f32_16x16x32_bf16 v[18:21], v[176:179], v[208:211], v[18:21]
	v_mfma_f32_16x16x32_bf16 v[10:13], v[184:187], v[208:211], v[10:13]
	v_mfma_f32_16x16x32_bf16 v[2:5], v[184:187], v[216:219], v[2:5]
	v_mfma_f32_16x16x32_bf16 v[6:9], v[176:179], v[216:219], v[6:9]
	s_setprio 0
	s_barrier
; #define PG8_STAGE(bufoff, gbase, voff) do { if constexpr (VAR != 1 && VAR != 3) { _Pragma("unroll") for (int _i = 0; _i < 2; ++_i) \
;         asm volatile("s_mov_b32 m0, %2\n\ts_nop 0\n\tglobal_load_lds_dwordx4 %0, %1" :: "v"((voff)[_i]), "s"((const char*)(gbase)), "s"(ldsbase + (unsigned)((bufoff) + _i * 8192)) : "memory", "m0"); } } while (0)
; #define PG8_LDA(dst, b, h) do { if constexpr (VAR < 2) _Pragma("unroll") for (int m = 0; m < 4; ++m) _Pragma("unroll") for (int k = 0; k < 2; ++k) dst[m][k] = *(const LAS bf16x8*)(lds + PG8_SA(b, h) + aoff + m * 2048 + k * 1024); } while (0)
; #define PG8_LDB(dst, b, h) do { if constexpr (VAR < 2) _Pragma("unroll") for (int n = 0; n < 2; ++n) _Pragma("unroll") for (int k = 0; k < 2; ++k) dst[n][k] = *(const LAS bf16x8*)(lds + PG8_SB(b, h) + boff + n * 2048 + k * 1024); } while (0)
; #define PG8_WAIT_V(n) asm volatile("s_waitcnt vmcnt(" #n ")" ::: "memory")
; #define PG8_WAIT_L(n) asm volatile("s_waitcnt lgkmcnt(" #n ")" ::: "memory")
; #define PG8_BAR do { if constexpr (VAR != 3) __builtin_amdgcn_s_barrier(); } while (0)
; #define PG8_SCHED __builtin_amdgcn_sched_barrier(0)
;     ...
;             PG8_LDB(B0, 1, 0); PG8_LDB(B1, 1, 1); PG8_SCHED; PG8_LDA(At, 1, 0); PG8_STAGE(PG8_SA(0, 1), a2 + hstepA, voffA);
;             PG8_WAIT_V(8); PG8_WAIT_L(0); PG8_BAR; PG8_MMA(0, 0, At, B0); PG8_MMA(0, 1, At, B1); PG8_BAR; PG8_SCHED;
;             PG8_LDA(At, 1, 1); PG8_STAGE(PG8_SB(1, 0), b3, voffB); PG8_STAGE(PG8_SB(1, 1), b3 + hstepB, voffB); PG8_STAGE(PG8_SA(1, 0), a3, voffA);
;             PG8_WAIT_V(8); PG8_WAIT_L(0); PG8_BAR; PG8_MMA(1, 0, At, B0); PG8_MMA(1, 1, At, B1); PG8_BAR; PG8_SCHED;
;         }
;         if (wr == 0) PG8_BAR;
	ds_read_b128 v[156:159], v154
	ds_read_b128 v[160:163], v154 offset:1024
	ds_read_b128 v[164:167], v154 offset:2048
	ds_read_b128 v[168:171], v154 offset:3072
	ds_read_b128 v[172:175], v155
	ds_read_b128 v[176:179], v155 offset:1024
	ds_read_b128 v[180:183], v155 offset:2048
	ds_read_b128 v[184:187], v155 offset:3072
	ds_read_b128 v[188:191], v153 offset:32768
	ds_read_b128 v[192:195], v153 offset:33792
	ds_read_b128 v[196:199], v153 offset:34816
	ds_read_b128 v[200:203], v153 offset:35840
	ds_read_b128 v[204:207], v153 offset:36864
	ds_read_b128 v[208:211], v153 offset:37888
	ds_read_b128 v[212:215], v153 offset:38912
	ds_read_b128 v[216:219], v153 offset:39936
	s_add_u32 s6, s96, 0x100000
	s_addc_u32 s7, s97, 0
	s_mov_b32 m0, s30
	s_nop 0
	global_load_lds_dwordx4 v1, s[6:7]
	s_nop 0
	s_mov_b32 m0, s31
	s_nop 0
	global_load_lds_dwordx4 v147, s[6:7]
	s_waitcnt vmcnt(8)
	s_waitcnt lgkmcnt(0)
	s_barrier
	s_setprio 1
	s_waitcnt lgkmcnt(7)
	v_mfma_f32_16x16x32_bf16 v[126:129], v[156:159], v[188:191], v[126:129]
	v_mfma_f32_16x16x32_bf16 v[122:125], v[164:167], v[188:191], v[122:125]
	s_waitcnt lgkmcnt(5)
	v_mfma_f32_16x16x32_bf16 v[110:113], v[164:167], v[196:199], v[110:113]
	v_mfma_f32_16x16x32_bf16 v[118:121], v[156:159], v[196:199], v[118:121]
	s_waitcnt lgkmcnt(3)
	v_mfma_f32_16x16x32_bf16 v[102:105], v[156:159], v[204:207], v[102:105]
	v_mfma_f32_16x16x32_bf16 v[94:97], v[164:167], v[204:207], v[94:97]
	s_waitcnt lgkmcnt(1)
	v_mfma_f32_16x16x32_bf16 v[78:81], v[164:167], v[212:215], v[78:81]
	v_mfma_f32_16x16x32_bf16 v[86:89], v[156:159], v[212:215], v[86:89]
	v_mfma_f32_16x16x32_bf16 v[126:129], v[160:163], v[192:195], v[126:129]
	v_mfma_f32_16x16x32_bf16 v[122:125], v[168:171], v[192:195], v[122:125]
	v_mfma_f32_16x16x32_bf16 v[110:113], v[168:171], v[200:203], v[110:113]
	v_mfma_f32_16x16x32_bf16 v[118:121], v[160:163], v[200:203], v[118:121]
	v_mfma_f32_16x16x32_bf16 v[102:105], v[160:163], v[208:211], v[102:105]
	v_mfma_f32_16x16x32_bf16 v[94:97], v[168:171], v[208:211], v[94:97]
	s_waitcnt lgkmcnt(0)
	v_mfma_f32_16x16x32_bf16 v[78:81], v[168:171], v[216:219], v[78:81]
	v_mfma_f32_16x16x32_bf16 v[86:89], v[160:163], v[216:219], v[86:89]
	s_setprio 0
	s_setprio 1
	v_mfma_f32_16x16x32_bf16 v[114:117], v[172:175], v[188:191], v[114:117]
	v_mfma_f32_16x16x32_bf16 v[106:109], v[180:183], v[188:191], v[106:109]
	v_mfma_f32_16x16x32_bf16 v[90:93], v[180:183], v[196:199], v[90:93]
	v_mfma_f32_16x16x32_bf16 v[98:101], v[172:175], v[196:199], v[98:101]
	v_mfma_f32_16x16x32_bf16 v[82:85], v[172:175], v[204:207], v[82:85]
	v_mfma_f32_16x16x32_bf16 v[74:77], v[180:183], v[204:207], v[74:77]
	v_mfma_f32_16x16x32_bf16 v[66:69], v[180:183], v[212:215], v[66:69]
	v_mfma_f32_16x16x32_bf16 v[70:73], v[172:175], v[212:215], v[70:73]
	v_mfma_f32_16x16x32_bf16 v[114:117], v[176:179], v[192:195], v[114:117]
	v_mfma_f32_16x16x32_bf16 v[106:109], v[184:187], v[192:195], v[106:109]
	v_mfma_f32_16x16x32_bf16 v[90:93], v[184:187], v[200:203], v[90:93]
	v_mfma_f32_16x16x32_bf16 v[98:101], v[176:179], v[200:203], v[98:101]
	v_mfma_f32_16x16x32_bf16 v[82:85], v[176:179], v[208:211], v[82:85]
	v_mfma_f32_16x16x32_bf16 v[74:77], v[184:187], v[208:211], v[74:77]
	v_mfma_f32_16x16x32_bf16 v[66:69], v[184:187], v[216:219], v[66:69]
	v_mfma_f32_16x16x32_bf16 v[70:73], v[176:179], v[216:219], v[70:73]
	s_setprio 0
	s_barrier
	ds_read_b128 v[188:191], v153 offset:49152
	ds_read_b128 v[192:195], v153 offset:50176
	ds_read_b128 v[196:199], v153 offset:51200
	ds_read_b128 v[200:203], v153 offset:52224
	ds_read_b128 v[204:207], v153 offset:53248
	ds_read_b128 v[208:211], v153 offset:54272
	ds_read_b128 v[212:215], v153 offset:55296
	ds_read_b128 v[216:219], v153 offset:56320
	s_add_u32 s6, s94, 0x80
	s_addc_u32 s7, s95, 0
	s_mov_b32 m0, s33
	s_nop 0
	global_load_lds_dwordx4 v146, s[6:7]
	s_nop 0
	s_mov_b32 m0, s35
	s_nop 0
	global_load_lds_dwordx4 v148, s[6:7]
	s_add_u32 s6, s94, 0x100080
	s_addc_u32 s7, s95, 0
	s_mov_b32 m0, s54
	s_nop 0
	global_load_lds_dwordx4 v146, s[6:7]
	s_nop 0
	s_mov_b32 m0, s55
	s_nop 0
	global_load_lds_dwordx4 v148, s[6:7]
	s_nop 0
	s_mov_b32 m0, s52
	s_nop 0
	global_load_lds_dwordx4 v1, s[92:93]
	s_nop 0
	s_mov_b32 m0, s53
	s_nop 0
	global_load_lds_dwordx4 v147, s[92:93]
	s_waitcnt vmcnt(8)
	s_waitcnt lgkmcnt(0)
	s_barrier
	s_setprio 1
	s_waitcnt lgkmcnt(7)
	v_mfma_f32_16x16x32_bf16 v[62:65], v[156:159], v[188:191], v[62:65]
	v_mfma_f32_16x16x32_bf16 v[58:61], v[164:167], v[188:191], v[58:61]
	s_waitcnt lgkmcnt(5)
	v_mfma_f32_16x16x32_bf16 v[46:49], v[164:167], v[196:199], v[46:49]
	v_mfma_f32_16x16x32_bf16 v[54:57], v[156:159], v[196:199], v[54:57]
	s_waitcnt lgkmcnt(3)
	v_mfma_f32_16x16x32_bf16 v[38:41], v[156:159], v[204:207], v[38:41]
	v_mfma_f32_16x16x32_bf16 v[30:33], v[164:167], v[204:207], v[30:33]
	s_waitcnt lgkmcnt(1)
	v_mfma_f32_16x16x32_bf16 v[14:17], v[164:167], v[212:215], v[14:17]
	v_mfma_f32_16x16x32_bf16 v[22:25], v[156:159], v[212:215], v[22:25]
	v_mfma_f32_16x16x32_bf16 v[62:65], v[160:163], v[192:195], v[62:65]
	v_mfma_f32_16x16x32_bf16 v[58:61], v[168:171], v[192:195], v[58:61]
	v_mfma_f32_16x16x32_bf16 v[46:49], v[168:171], v[200:203], v[46:49]
	v_mfma_f32_16x16x32_bf16 v[54:57], v[160:163], v[200:203], v[54:57]
	v_mfma_f32_16x16x32_bf16 v[38:41], v[160:163], v[208:211], v[38:41]
	v_mfma_f32_16x16x32_bf16 v[30:33], v[168:171], v[208:211], v[30:33]
	s_waitcnt lgkmcnt(0)
	v_mfma_f32_16x16x32_bf16 v[14:17], v[168:171], v[216:219], v[14:17]
	v_mfma_f32_16x16x32_bf16 v[22:25], v[160:163], v[216:219], v[22:25]
	s_setprio 0
	s_setprio 1
	v_mfma_f32_16x16x32_bf16 v[50:53], v[172:175], v[188:191], v[50:53]
	v_mfma_f32_16x16x32_bf16 v[42:45], v[180:183], v[188:191], v[42:45]
	v_mfma_f32_16x16x32_bf16 v[26:29], v[180:183], v[196:199], v[26:29]
	v_mfma_f32_16x16x32_bf16 v[34:37], v[172:175], v[196:199], v[34:37]
	v_mfma_f32_16x16x32_bf16 v[18:21], v[172:175], v[204:207], v[18:21]
	v_mfma_f32_16x16x32_bf16 v[10:13], v[180:183], v[204:207], v[10:13]
	v_mfma_f32_16x16x32_bf16 v[2:5], v[180:183], v[212:215], v[2:5]
	v_mfma_f32_16x16x32_bf16 v[6:9], v[172:175], v[212:215], v[6:9]
	v_mfma_f32_16x16x32_bf16 v[50:53], v[176:179], v[192:195], v[50:53]
	v_mfma_f32_16x16x32_bf16 v[42:45], v[184:187], v[192:195], v[42:45]
	v_mfma_f32_16x16x32_bf16 v[26:29], v[184:187], v[200:203], v[26:29]
	v_mfma_f32_16x16x32_bf16 v[34:37], v[176:179], v[200:203], v[34:37]
	v_mfma_f32_16x16x32_bf16 v[18:21], v[176:179], v[208:211], v[18:21]
	v_mfma_f32_16x16x32_bf16 v[10:13], v[184:187], v[208:211], v[10:13]
	v_mfma_f32_16x16x32_bf16 v[2:5], v[184:187], v[216:219], v[2:5]
	v_mfma_f32_16x16x32_bf16 v[6:9], v[176:179], v[216:219], v[6:9]
	s_setprio 0
	s_barrier
	s_add_i32 vcc_hi, vcc_hi, 2
	s_add_u32 s66, s66, 0x100
	s_addc_u32 s67, s67, 0
	s_add_u32 s69, s69, 0x100
	s_addc_u32 vcc_lo, vcc_lo, 0
	s_add_u32 s90, s90, 0x100
	s_addc_u32 s91, s91, 0
	s_cmp_gt_u32 vcc_hi, 61
	s_cbranch_scc0 .LBB0_346
	s_and_b64 vcc, exec, s[4:5]
	s_cbranch_vccz .LBB0_349
	s_barrier

; #define PG8_STAGE(bufoff, gbase, voff) do { if constexpr (VAR != 1 && VAR != 3) { _Pragma("unroll") for (int _i = 0; _i < 2; ++_i) \
;         asm volatile("s_mov_b32 m0, %2\n\ts_nop 0\n\tglobal_load_lds_dwordx4 %0, %1" :: "v"((voff)[_i]), "s"((const char*)(gbase)), "s"(ldsbase + (unsigned)((bufoff) + _i * 8192)) : "memory", "m0"); } } while (0)
; #define PG8_LDA(dst, b, h) do { if constexpr (VAR < 2) _Pragma("unroll") for (int m = 0; m < 4; ++m) _Pragma("unroll") for (int k = 0; k < 2; ++k) dst[m][k] = *(const LAS bf16x8*)(lds + PG8_SA(b, h) + aoff + m * 2048 + k * 1024); } while (0)
; #define PG8_LDB(dst, b, h) do { if constexpr (VAR < 2) _Pragma("unroll") for (int n = 0; n < 2; ++n) _Pragma("unroll") for (int k = 0; k < 2; ++k) dst[n][k] = *(const LAS bf16x8*)(lds + PG8_SB(b, h) + boff + n * 2048 + k * 1024); } while (0)
; #define PG8_WAIT_V(n) asm volatile("s_waitcnt vmcnt(" #n ")" ::: "memory")
; #define PG8_WAIT_L(n) asm volatile("s_waitcnt lgkmcnt(" #n ")" ::: "memory")
; #define PG8_BAR do { if constexpr (VAR != 3) __builtin_amdgcn_s_barrier(); } while (0)
; #define PG8_SCHED __builtin_amdgcn_sched_barrier(0)
;     ...
;             PG8_LDB(B0, 0, 0); PG8_LDB(B1, 0, 1); PG8_SCHED; PG8_LDA(At, 0, 0); PG8_STAGE(PG8_SA(1, 1), a1 + hstepA, voffA);
;             PG8_WAIT_V(8); PG8_WAIT_L(0); PG8_BAR; PG8_MMA(0, 0, At, B0); PG8_MMA(0, 1, At, B1); PG8_BAR; PG8_SCHED;
;             PG8_LDA(At, 0, 1); PG8_STAGE(PG8_SB(0, 0), b2, voffB); PG8_STAGE(PG8_SB(0, 1), b2 + hstepB, voffB); PG8_STAGE(PG8_SA(0, 0), a2, voffA);
;             PG8_WAIT_V(8); PG8_WAIT_L(0); PG8_BAR; PG8_MMA(1, 0, At, B0); PG8_MMA(1, 1, At, B1); PG8_BAR; PG8_SCHED;
.LBB0_539:
	ds_read_b128 v[138:141], v159
	ds_read_b128 v[164:167], v159 offset:1024
	ds_read_b128 v[168:171], v159 offset:2048
	ds_read_b128 v[172:175], v159 offset:3072
	ds_read_b128 v[176:179], v160
	ds_read_b128 v[180:183], v160 offset:1024
	ds_read_b128 v[184:187], v160 offset:2048
	ds_read_b128 v[188:191], v160 offset:3072
	s_cmp_eq_u32 s6, 28
	s_cselect_b32 s94, s15, vcc_lo
	s_cselect_b32 s95, s14, vcc_hi
	s_cselect_b32 s92, s73, s54
	s_cselect_b32 s93, s71, s55
	s_add_u32 s90, s94, 0x80
	s_addc_u32 s91, s95, 0
	ds_read_b128 v[192:195], v161
	ds_read_b128 v[196:199], v161 offset:1024
	ds_read_b128 v[200:203], v161 offset:2048
	ds_read_b128 v[204:207], v161 offset:3072
	ds_read_b128 v[208:211], v161 offset:4096
	ds_read_b128 v[212:215], v161 offset:5120
	ds_read_b128 v[216:219], v161 offset:6144
	ds_read_b128 v[220:223], v161 offset:7168
	s_mov_b32 m0, s57
	s_nop 0
	global_load_lds_dwordx4 v151, s[88:89]
	s_nop 0
	s_mov_b32 m0, s24
	s_nop 0
	global_load_lds_dwordx4 v153, s[88:89]
	s_waitcnt vmcnt(8)
	s_waitcnt lgkmcnt(0)
	s_barrier
	s_setprio 1
	s_waitcnt lgkmcnt(7)
	v_mfma_i32_16x16x64_i8 v[126:129], v[138:141], v[192:195], v[126:129]
	v_mfma_i32_16x16x64_i8 v[118:121], v[168:171], v[192:195], v[118:121]
	s_waitcnt lgkmcnt(5)
	v_mfma_i32_16x16x64_i8 v[102:105], v[168:171], v[200:203], v[102:105]
	v_mfma_i32_16x16x64_i8 v[110:113], v[138:141], v[200:203], v[110:113]
	s_waitcnt lgkmcnt(3)
	v_mfma_i32_16x16x64_i8 v[94:97], v[138:141], v[208:211], v[94:97]
	v_mfma_i32_16x16x64_i8 v[86:89], v[168:171], v[208:211], v[86:89]
	s_waitcnt lgkmcnt(1)
	v_mfma_i32_16x16x64_i8 v[70:73], v[168:171], v[216:219], v[70:73]
	v_mfma_i32_16x16x64_i8 v[78:81], v[138:141], v[216:219], v[78:81]
	v_mfma_i32_16x16x64_i8 v[126:129], v[164:167], v[196:199], v[126:129]
	v_mfma_i32_16x16x64_i8 v[118:121], v[172:175], v[196:199], v[118:121]
	v_mfma_i32_16x16x64_i8 v[102:105], v[172:175], v[204:207], v[102:105]
	v_mfma_i32_16x16x64_i8 v[110:113], v[164:167], v[204:207], v[110:113]
	v_mfma_i32_16x16x64_i8 v[94:97], v[164:167], v[212:215], v[94:97]
	v_mfma_i32_16x16x64_i8 v[86:89], v[172:175], v[212:215], v[86:89]
	s_waitcnt lgkmcnt(0)
	v_mfma_i32_16x16x64_i8 v[70:73], v[172:175], v[220:223], v[70:73]
	v_mfma_i32_16x16x64_i8 v[78:81], v[164:167], v[220:223], v[78:81]
	s_setprio 0
	s_setprio 1
	v_mfma_i32_16x16x64_i8 v[122:125], v[176:179], v[192:195], v[122:125]
	v_mfma_i32_16x16x64_i8 v[114:117], v[184:187], v[192:195], v[114:117]
	v_mfma_i32_16x16x64_i8 v[98:101], v[184:187], v[200:203], v[98:101]
	v_mfma_i32_16x16x64_i8 v[106:109], v[176:179], v[200:203], v[106:109]
	v_mfma_i32_16x16x64_i8 v[90:93], v[176:179], v[208:211], v[90:93]
	v_mfma_i32_16x16x64_i8 v[82:85], v[184:187], v[208:211], v[82:85]
	v_mfma_i32_16x16x64_i8 v[66:69], v[184:187], v[216:219], v[66:69]
	v_mfma_i32_16x16x64_i8 v[74:77], v[176:179], v[216:219], v[74:77]
	v_mfma_i32_16x16x64_i8 v[122:125], v[180:183], v[196:199], v[122:125]
	v_mfma_i32_16x16x64_i8 v[114:117], v[188:191], v[196:199], v[114:117]
	v_mfma_i32_16x16x64_i8 v[98:101], v[188:191], v[204:207], v[98:101]
	v_mfma_i32_16x16x64_i8 v[106:109], v[180:183], v[204:207], v[106:109]
	v_mfma_i32_16x16x64_i8 v[90:93], v[180:183], v[212:215], v[90:93]
	v_mfma_i32_16x16x64_i8 v[82:85], v[188:191], v[212:215], v[82:85]
	v_mfma_i32_16x16x64_i8 v[66:69], v[188:191], v[220:223], v[66:69]
	v_mfma_i32_16x16x64_i8 v[74:77], v[180:183], v[220:223], v[74:77]
	s_setprio 0
	s_barrier
	ds_read_b128 v[192:195], v161 offset:16384
	ds_read_b128 v[196:199], v161 offset:17408
	ds_read_b128 v[200:203], v161 offset:18432
	ds_read_b128 v[204:207], v161 offset:19456
	ds_read_b128 v[208:211], v161 offset:20480
	ds_read_b128 v[212:215], v161 offset:21504
	ds_read_b128 v[216:219], v161 offset:22528
	ds_read_b128 v[220:223], v161 offset:23552
	s_mov_b32 m0, s29
	s_nop 0
	global_load_lds_dwordx4 v152, s[92:93]
	s_add_u32 s10, s92, 0x80000
	s_mov_b32 m0, s30
	s_nop 0
	global_load_lds_dwordx4 v154, s[92:93]
	s_addc_u32 s11, s93, 0
	s_mov_b32 m0, s31
	s_nop 0
	global_load_lds_dwordx4 v152, s[10:11]
	s_nop 0
	s_mov_b32 m0, s33
	s_nop 0
	global_load_lds_dwordx4 v154, s[10:11]
	s_nop 0
	s_mov_b32 m0, s26
	s_nop 0
	global_load_lds_dwordx4 v151, s[94:95]
	s_nop 0
	s_mov_b32 m0, s35
	s_nop 0
	global_load_lds_dwordx4 v153, s[94:95]
	s_waitcnt vmcnt(8)
	s_waitcnt lgkmcnt(0)
	s_barrier
	s_setprio 1
	s_waitcnt lgkmcnt(7)
	v_mfma_i32_16x16x64_i8 v[62:65], v[138:141], v[192:195], v[62:65]
	v_mfma_i32_16x16x64_i8 v[54:57], v[168:171], v[192:195], v[54:57]
	s_waitcnt lgkmcnt(5)
	v_mfma_i32_16x16x64_i8 v[38:41], v[168:171], v[200:203], v[38:41]
	v_mfma_i32_16x16x64_i8 v[46:49], v[138:141], v[200:203], v[46:49]
	s_waitcnt lgkmcnt(3)
	v_mfma_i32_16x16x64_i8 v[30:33], v[138:141], v[208:211], v[30:33]
	v_mfma_i32_16x16x64_i8 v[22:25], v[168:171], v[208:211], v[22:25]
	s_waitcnt lgkmcnt(1)
	v_mfma_i32_16x16x64_i8 v[6:9], v[168:171], v[216:219], v[6:9]
	v_mfma_i32_16x16x64_i8 v[14:17], v[138:141], v[216:219], v[14:17]
	v_mfma_i32_16x16x64_i8 v[62:65], v[164:167], v[196:199], v[62:65]
	v_mfma_i32_16x16x64_i8 v[54:57], v[172:175], v[196:199], v[54:57]
	v_mfma_i32_16x16x64_i8 v[38:41], v[172:175], v[204:207], v[38:41]
	v_mfma_i32_16x16x64_i8 v[46:49], v[164:167], v[204:207], v[46:49]
	v_mfma_i32_16x16x64_i8 v[30:33], v[164:167], v[212:215], v[30:33]
	v_mfma_i32_16x16x64_i8 v[22:25], v[172:175], v[212:215], v[22:25]
	s_waitcnt lgkmcnt(0)
	v_mfma_i32_16x16x64_i8 v[6:9], v[172:175], v[220:223], v[6:9]
	v_mfma_i32_16x16x64_i8 v[14:17], v[164:167], v[220:223], v[14:17]
	s_setprio 0
	s_setprio 1
	v_mfma_i32_16x16x64_i8 v[58:61], v[176:179], v[192:195], v[58:61]
	v_mfma_i32_16x16x64_i8 v[50:53], v[184:187], v[192:195], v[50:53]
	v_mfma_i32_16x16x64_i8 v[34:37], v[184:187], v[200:203], v[34:37]
	v_mfma_i32_16x16x64_i8 v[42:45], v[176:179], v[200:203], v[42:45]
	v_mfma_i32_16x16x64_i8 v[26:29], v[176:179], v[208:211], v[26:29]
	v_mfma_i32_16x16x64_i8 v[18:21], v[184:187], v[208:211], v[18:21]
	v_mfma_i32_16x16x64_i8 v[2:5], v[184:187], v[216:219], v[2:5]
	v_mfma_i32_16x16x64_i8 v[10:13], v[176:179], v[216:219], v[10:13]
	v_mfma_i32_16x16x64_i8 v[58:61], v[180:183], v[196:199], v[58:61]
	v_mfma_i32_16x16x64_i8 v[50:53], v[188:191], v[196:199], v[50:53]
	v_mfma_i32_16x16x64_i8 v[34:37], v[188:191], v[204:207], v[34:37]
	v_mfma_i32_16x16x64_i8 v[42:45], v[180:183], v[204:207], v[42:45]
	v_mfma_i32_16x16x64_i8 v[26:29], v[180:183], v[212:215], v[26:29]
	v_mfma_i32_16x16x64_i8 v[18:21], v[188:191], v[212:215], v[18:21]
	v_mfma_i32_16x16x64_i8 v[2:5], v[188:191], v[220:223], v[2:5]
	v_mfma_i32_16x16x64_i8 v[10:13], v[180:183], v[220:223], v[10:13]
	s_setprio 0
	s_barrier
; #define PG8_STAGE(bufoff, gbase, voff) do { if constexpr (VAR != 1 && VAR != 3) { _Pragma("unroll") for (int _i = 0; _i < 2; ++_i) \
;         asm volatile("s_mov_b32 m0, %2\n\ts_nop 0\n\tglobal_load_lds_dwordx4 %0, %1" :: "v"((voff)[_i]), "s"((const char*)(gbase)), "s"(ldsbase + (unsigned)((bufoff) + _i * 8192)) : "memory", "m0"); } } while (0)
; #define PG8_LDA(dst, b, h) do { if constexpr (VAR < 2) _Pragma("unroll") for (int m = 0; m < 4; ++m) _Pragma("unroll") for (int k = 0; k < 2; ++k) dst[m][k] = *(const LAS bf16x8*)(lds + PG8_SA(b, h) + aoff + m * 2048 + k * 1024); } while (0)
; #define PG8_LDB(dst, b, h) do { if constexpr (VAR < 2) _Pragma("unroll") for (int n = 0; n < 2; ++n) _Pragma("unroll") for (int k = 0; k < 2; ++k) dst[n][k] = *(const LAS bf16x8*)(lds + PG8_SB(b, h) + boff + n * 2048 + k * 1024); } while (0)
; #define PG8_WAIT_V(n) asm volatile("s_waitcnt vmcnt(" #n ")" ::: "memory")
; #define PG8_WAIT_L(n) asm volatile("s_waitcnt lgkmcnt(" #n ")" ::: "memory")
; #define PG8_BAR do { if constexpr (VAR != 3) __builtin_amdgcn_s_barrier(); } while (0)
; #define PG8_SCHED __builtin_amdgcn_sched_barrier(0)
;     ...
;             PG8_LDB(B0, 1, 0); PG8_LDB(B1, 1, 1); PG8_SCHED; PG8_LDA(At, 1, 0); PG8_STAGE(PG8_SA(0, 1), a2 + hstepA, voffA);
;             PG8_WAIT_V(8); PG8_WAIT_L(0); PG8_BAR; PG8_MMA(0, 0, At, B0); PG8_MMA(0, 1, At, B1); PG8_BAR; PG8_SCHED;
;             PG8_LDA(At, 1, 1); PG8_STAGE(PG8_SB(1, 0), b3, voffB); PG8_STAGE(PG8_SB(1, 1), b3 + hstepB, voffB); PG8_STAGE(PG8_SA(1, 0), a3, voffA);
;             PG8_WAIT_V(8); PG8_WAIT_L(0); PG8_BAR; PG8_MMA(1, 0, At, B0); PG8_MMA(1, 1, At, B1); PG8_BAR; PG8_SCHED;
;         }
;         if (wr == 0) PG8_BAR;
	ds_read_b128 v[138:141], v162
	ds_read_b128 v[164:167], v162 offset:1024
	ds_read_b128 v[168:171], v162 offset:2048
	ds_read_b128 v[172:175], v162 offset:3072
	ds_read_b128 v[176:179], v163
	ds_read_b128 v[180:183], v163 offset:1024
	ds_read_b128 v[184:187], v163 offset:2048
	ds_read_b128 v[188:191], v163 offset:3072
	ds_read_b128 v[192:195], v161 offset:32768
	ds_read_b128 v[196:199], v161 offset:33792
	ds_read_b128 v[200:203], v161 offset:34816
	ds_read_b128 v[204:207], v161 offset:35840
	ds_read_b128 v[208:211], v161 offset:36864
	ds_read_b128 v[212:215], v161 offset:37888
	ds_read_b128 v[216:219], v161 offset:38912
	ds_read_b128 v[220:223], v161 offset:39936
	s_add_u32 s10, s94, 0x80000
	s_addc_u32 s11, s95, 0
	s_mov_b32 m0, s62
	s_nop 0
	global_load_lds_dwordx4 v151, s[10:11]
	s_nop 0
	s_mov_b32 m0, s63
	s_nop 0
	global_load_lds_dwordx4 v153, s[10:11]
	s_waitcnt vmcnt(8)
	s_waitcnt lgkmcnt(0)
	s_barrier
	s_setprio 1
	s_waitcnt lgkmcnt(7)
	v_mfma_i32_16x16x64_i8 v[126:129], v[138:141], v[192:195], v[126:129]
	v_mfma_i32_16x16x64_i8 v[118:121], v[168:171], v[192:195], v[118:121]
	s_waitcnt lgkmcnt(5)
	v_mfma_i32_16x16x64_i8 v[102:105], v[168:171], v[200:203], v[102:105]
	v_mfma_i32_16x16x64_i8 v[110:113], v[138:141], v[200:203], v[110:113]
	s_waitcnt lgkmcnt(3)
	v_mfma_i32_16x16x64_i8 v[94:97], v[138:141], v[208:211], v[94:97]
	v_mfma_i32_16x16x64_i8 v[86:89], v[168:171], v[208:211], v[86:89]
	s_waitcnt lgkmcnt(1)
	v_mfma_i32_16x16x64_i8 v[70:73], v[168:171], v[216:219], v[70:73]
	v_mfma_i32_16x16x64_i8 v[78:81], v[138:141], v[216:219], v[78:81]
	v_mfma_i32_16x16x64_i8 v[126:129], v[164:167], v[196:199], v[126:129]
	v_mfma_i32_16x16x64_i8 v[118:121], v[172:175], v[196:199], v[118:121]
	v_mfma_i32_16x16x64_i8 v[102:105], v[172:175], v[204:207], v[102:105]
	v_mfma_i32_16x16x64_i8 v[110:113], v[164:167], v[204:207], v[110:113]
	v_mfma_i32_16x16x64_i8 v[94:97], v[164:167], v[212:215], v[94:97]
	v_mfma_i32_16x16x64_i8 v[86:89], v[172:175], v[212:215], v[86:89]
	s_waitcnt lgkmcnt(0)
	v_mfma_i32_16x16x64_i8 v[70:73], v[172:175], v[220:223], v[70:73]
	v_mfma_i32_16x16x64_i8 v[78:81], v[164:167], v[220:223], v[78:81]
	s_setprio 0
	s_setprio 1
	v_mfma_i32_16x16x64_i8 v[122:125], v[176:179], v[192:195], v[122:125]
	v_mfma_i32_16x16x64_i8 v[114:117], v[184:187], v[192:195], v[114:117]
	v_mfma_i32_16x16x64_i8 v[98:101], v[184:187], v[200:203], v[98:101]
	v_mfma_i32_16x16x64_i8 v[106:109], v[176:179], v[200:203], v[106:109]
	v_mfma_i32_16x16x64_i8 v[90:93], v[176:179], v[208:211], v[90:93]
	v_mfma_i32_16x16x64_i8 v[82:85], v[184:187], v[208:211], v[82:85]
	v_mfma_i32_16x16x64_i8 v[66:69], v[184:187], v[216:219], v[66:69]
	v_mfma_i32_16x16x64_i8 v[74:77], v[176:179], v[216:219], v[74:77]
	v_mfma_i32_16x16x64_i8 v[122:125], v[180:183], v[196:199], v[122:125]
	v_mfma_i32_16x16x64_i8 v[114:117], v[188:191], v[196:199], v[114:117]
	v_mfma_i32_16x16x64_i8 v[98:101], v[188:191], v[204:207], v[98:101]
	v_mfma_i32_16x16x64_i8 v[106:109], v[180:183], v[204:207], v[106:109]
	v_mfma_i32_16x16x64_i8 v[90:93], v[180:183], v[212:215], v[90:93]
	v_mfma_i32_16x16x64_i8 v[82:85], v[188:191], v[212:215], v[82:85]
	v_mfma_i32_16x16x64_i8 v[66:69], v[188:191], v[220:223], v[66:69]
	v_mfma_i32_16x16x64_i8 v[74:77], v[180:183], v[220:223], v[74:77]
	s_setprio 0
	s_barrier
	ds_read_b128 v[192:195], v161 offset:49152
	ds_read_b128 v[196:199], v161 offset:50176
	ds_read_b128 v[200:203], v161 offset:51200
	ds_read_b128 v[204:207], v161 offset:52224
	ds_read_b128 v[208:211], v161 offset:53248
	ds_read_b128 v[212:215], v161 offset:54272
	ds_read_b128 v[216:219], v161 offset:55296
	ds_read_b128 v[220:223], v161 offset:56320
	s_add_u32 s10, s92, 0x80
	s_addc_u32 s11, s93, 0
	s_mov_b32 m0, s87
	s_nop 0
	global_load_lds_dwordx4 v152, s[10:11]
	s_nop 0
	s_mov_b32 m0, s96
	s_nop 0
	global_load_lds_dwordx4 v154, s[10:11]
	s_add_u32 s10, s92, 0x80080
	s_addc_u32 s11, s93, 0
	s_mov_b32 m0, s53
	s_nop 0
	global_load_lds_dwordx4 v152, s[10:11]
	s_nop 0
	s_mov_b32 m0, s56
	s_nop 0
	global_load_lds_dwordx4 v154, s[10:11]
	s_nop 0
	s_mov_b32 m0, s97
	s_nop 0
	global_load_lds_dwordx4 v151, s[90:91]
	s_nop 0
	s_mov_b32 m0, s52
	s_nop 0
	global_load_lds_dwordx4 v153, s[90:91]
	s_waitcnt vmcnt(8)
	s_waitcnt lgkmcnt(0)
	s_barrier
	s_setprio 1
	s_waitcnt lgkmcnt(7)
	v_mfma_i32_16x16x64_i8 v[62:65], v[138:141], v[192:195], v[62:65]
	v_mfma_i32_16x16x64_i8 v[54:57], v[168:171], v[192:195], v[54:57]
	s_waitcnt lgkmcnt(5)
	v_mfma_i32_16x16x64_i8 v[38:41], v[168:171], v[200:203], v[38:41]
	v_mfma_i32_16x16x64_i8 v[46:49], v[138:141], v[200:203], v[46:49]
	s_waitcnt lgkmcnt(3)
	v_mfma_i32_16x16x64_i8 v[30:33], v[138:141], v[208:211], v[30:33]
	v_mfma_i32_16x16x64_i8 v[22:25], v[168:171], v[208:211], v[22:25]
	s_waitcnt lgkmcnt(1)
	v_mfma_i32_16x16x64_i8 v[6:9], v[168:171], v[216:219], v[6:9]
	v_mfma_i32_16x16x64_i8 v[14:17], v[138:141], v[216:219], v[14:17]
	v_mfma_i32_16x16x64_i8 v[62:65], v[164:167], v[196:199], v[62:65]
	v_mfma_i32_16x16x64_i8 v[54:57], v[172:175], v[196:199], v[54:57]
	v_mfma_i32_16x16x64_i8 v[38:41], v[172:175], v[204:207], v[38:41]
	v_mfma_i32_16x16x64_i8 v[46:49], v[164:167], v[204:207], v[46:49]
	v_mfma_i32_16x16x64_i8 v[30:33], v[164:167], v[212:215], v[30:33]
	v_mfma_i32_16x16x64_i8 v[22:25], v[172:175], v[212:215], v[22:25]
	s_waitcnt lgkmcnt(0)
	v_mfma_i32_16x16x64_i8 v[6:9], v[172:175], v[220:223], v[6:9]
	v_mfma_i32_16x16x64_i8 v[14:17], v[164:167], v[220:223], v[14:17]
	s_setprio 0
	s_setprio 1
	v_mfma_i32_16x16x64_i8 v[58:61], v[176:179], v[192:195], v[58:61]
	v_mfma_i32_16x16x64_i8 v[50:53], v[184:187], v[192:195], v[50:53]
	v_mfma_i32_16x16x64_i8 v[34:37], v[184:187], v[200:203], v[34:37]
	v_mfma_i32_16x16x64_i8 v[42:45], v[176:179], v[200:203], v[42:45]
	v_mfma_i32_16x16x64_i8 v[26:29], v[176:179], v[208:211], v[26:29]
	v_mfma_i32_16x16x64_i8 v[18:21], v[184:187], v[208:211], v[18:21]
	v_mfma_i32_16x16x64_i8 v[2:5], v[184:187], v[216:219], v[2:5]
	v_mfma_i32_16x16x64_i8 v[10:13], v[176:179], v[216:219], v[10:13]
	v_mfma_i32_16x16x64_i8 v[58:61], v[180:183], v[196:199], v[58:61]
	v_mfma_i32_16x16x64_i8 v[50:53], v[188:191], v[196:199], v[50:53]
	v_mfma_i32_16x16x64_i8 v[34:37], v[188:191], v[204:207], v[34:37]
	v_mfma_i32_16x16x64_i8 v[42:45], v[180:183], v[204:207], v[42:45]
	v_mfma_i32_16x16x64_i8 v[26:29], v[180:183], v[212:215], v[26:29]
	v_mfma_i32_16x16x64_i8 v[18:21], v[188:191], v[212:215], v[18:21]
	v_mfma_i32_16x16x64_i8 v[2:5], v[188:191], v[220:223], v[2:5]
	v_mfma_i32_16x16x64_i8 v[10:13], v[180:183], v[220:223], v[10:13]
	s_setprio 0
	s_barrier
	s_add_i32 s6, s6, 2
	s_add_u32 vcc_lo, vcc_lo, 0x100
	s_addc_u32 vcc_hi, vcc_hi, 0
	s_add_u32 s54, s54, 0x100
	s_addc_u32 s55, s55, 0
	s_add_u32 s88, s88, 0x100
	s_addc_u32 s89, s89, 0
	s_cmp_gt_u32 s6, 29
	s_cbranch_scc0 .LBB0_539
	s_and_b64 vcc, exec, s[66:67]
	s_cbranch_vccz .LBB0_542
	s_barrier

; #define PG8_STAGE(bufoff, gbase, voff) do { if constexpr (VAR != 1 && VAR != 3) { _Pragma("unroll") for (int _i = 0; _i < 2; ++_i) \
;         asm volatile("s_mov_b32 m0, %2\n\ts_nop 0\n\tglobal_load_lds_dwordx4 %0, %1" :: "v"((voff)[_i]), "s"((const char*)(gbase)), "s"(ldsbase + (unsigned)((bufoff) + _i * 8192)) : "memory", "m0"); } } while (0)
; #define PG8_LDA(dst, b, h) do { if constexpr (VAR < 2) _Pragma("unroll") for (int m = 0; m < 4; ++m) _Pragma("unroll") for (int k = 0; k < 2; ++k) dst[m][k] = *(const LAS bf16x8*)(lds + PG8_SA(b, h) + aoff + m * 2048 + k * 1024); } while (0)
; #define PG8_LDB(dst, b, h) do { if constexpr (VAR < 2) _Pragma("unroll") for (int n = 0; n < 2; ++n) _Pragma("unroll") for (int k = 0; k < 2; ++k) dst[n][k] = *(const LAS bf16x8*)(lds + PG8_SB(b, h) + boff + n * 2048 + k * 1024); } while (0)
; #define PG8_WAIT_V(n) asm volatile("s_waitcnt vmcnt(" #n ")" ::: "memory")
; #define PG8_WAIT_L(n) asm volatile("s_waitcnt lgkmcnt(" #n ")" ::: "memory")
; #define PG8_BAR do { if constexpr (VAR != 3) __builtin_amdgcn_s_barrier(); } while (0)
; #define PG8_SCHED __builtin_amdgcn_sched_barrier(0)
;     ...
;             PG8_LDB(B0, 0, 0); PG8_LDB(B1, 0, 1); PG8_SCHED; PG8_LDA(At, 0, 0); PG8_STAGE(PG8_SA(1, 1), a1 + hstepA, voffA);
;             PG8_WAIT_V(8); PG8_WAIT_L(0); PG8_BAR; PG8_MMA(0, 0, At, B0); PG8_MMA(0, 1, At, B1); PG8_BAR; PG8_SCHED;
;             PG8_LDA(At, 0, 1); PG8_STAGE(PG8_SB(0, 0), b2, voffB); PG8_STAGE(PG8_SB(0, 1), b2 + hstepB, voffB); PG8_STAGE(PG8_SA(0, 0), a2, voffA);
;             PG8_WAIT_V(8); PG8_WAIT_L(0); PG8_BAR; PG8_MMA(1, 0, At, B0); PG8_MMA(1, 1, At, B1); PG8_BAR; PG8_SCHED;
.LBB0_561:
	ds_read_b128 v[136:139], v152
	ds_read_b128 v[140:143], v152 offset:1024
	ds_read_b128 v[158:161], v152 offset:2048
	ds_read_b128 v[162:165], v152 offset:3072
	ds_read_b128 v[166:169], v153
	ds_read_b128 v[170:173], v153 offset:1024
	ds_read_b128 v[174:177], v153 offset:2048
	ds_read_b128 v[178:181], v153 offset:3072
	s_cmp_eq_u32 s6, 60
	s_cselect_b32 s84, s14, s65
	s_cselect_b32 s85, s1, s92
	s_cselect_b32 s74, s61, s93
	s_cselect_b32 s75, s15, s94
	s_add_u32 s72, s84, 0x80
	s_addc_u32 s73, s85, 0
	ds_read_b128 v[182:185], v154
	ds_read_b128 v[186:189], v154 offset:1024
	ds_read_b128 v[190:193], v154 offset:2048
	ds_read_b128 v[194:197], v154 offset:3072
	ds_read_b128 v[198:201], v154 offset:4096
	ds_read_b128 v[202:205], v154 offset:5120
	ds_read_b128 v[206:209], v154 offset:6144
	ds_read_b128 v[210:213], v154 offset:7168
	s_mov_b32 m0, s86
	s_nop 0
	global_load_lds_dwordx4 v1, s[70:71]
	s_nop 0
	s_mov_b32 m0, s87
	s_nop 0
	global_load_lds_dwordx4 v147, s[70:71]
	s_waitcnt vmcnt(8)
	s_waitcnt lgkmcnt(0)
	s_barrier
	s_setprio 1
	s_waitcnt lgkmcnt(7)
	v_mfma_f32_16x16x32_bf16 v[126:129], v[136:139], v[182:185], v[126:129]
	v_mfma_f32_16x16x32_bf16 v[118:121], v[158:161], v[182:185], v[118:121]
	s_waitcnt lgkmcnt(5)
	v_mfma_f32_16x16x32_bf16 v[102:105], v[158:161], v[190:193], v[102:105]
	v_mfma_f32_16x16x32_bf16 v[110:113], v[136:139], v[190:193], v[110:113]
	s_waitcnt lgkmcnt(3)
	v_mfma_f32_16x16x32_bf16 v[94:97], v[136:139], v[198:201], v[94:97]
	v_mfma_f32_16x16x32_bf16 v[86:89], v[158:161], v[198:201], v[86:89]
	s_waitcnt lgkmcnt(1)
	v_mfma_f32_16x16x32_bf16 v[70:73], v[158:161], v[206:209], v[70:73]
	v_mfma_f32_16x16x32_bf16 v[78:81], v[136:139], v[206:209], v[78:81]
	v_mfma_f32_16x16x32_bf16 v[126:129], v[140:143], v[186:189], v[126:129]
	v_mfma_f32_16x16x32_bf16 v[118:121], v[162:165], v[186:189], v[118:121]
	v_mfma_f32_16x16x32_bf16 v[102:105], v[162:165], v[194:197], v[102:105]
	v_mfma_f32_16x16x32_bf16 v[110:113], v[140:143], v[194:197], v[110:113]
	v_mfma_f32_16x16x32_bf16 v[94:97], v[140:143], v[202:205], v[94:97]
	v_mfma_f32_16x16x32_bf16 v[86:89], v[162:165], v[202:205], v[86:89]
	s_waitcnt lgkmcnt(0)
	v_mfma_f32_16x16x32_bf16 v[70:73], v[162:165], v[210:213], v[70:73]
	v_mfma_f32_16x16x32_bf16 v[78:81], v[140:143], v[210:213], v[78:81]
	s_setprio 0
	s_setprio 1
	v_mfma_f32_16x16x32_bf16 v[122:125], v[166:169], v[182:185], v[122:125]
	v_mfma_f32_16x16x32_bf16 v[114:117], v[174:177], v[182:185], v[114:117]
	v_mfma_f32_16x16x32_bf16 v[98:101], v[174:177], v[190:193], v[98:101]
	v_mfma_f32_16x16x32_bf16 v[106:109], v[166:169], v[190:193], v[106:109]
	v_mfma_f32_16x16x32_bf16 v[90:93], v[166:169], v[198:201], v[90:93]
	v_mfma_f32_16x16x32_bf16 v[82:85], v[174:177], v[198:201], v[82:85]
	v_mfma_f32_16x16x32_bf16 v[66:69], v[174:177], v[206:209], v[66:69]
	v_mfma_f32_16x16x32_bf16 v[74:77], v[166:169], v[206:209], v[74:77]
	v_mfma_f32_16x16x32_bf16 v[122:125], v[170:173], v[186:189], v[122:125]
	v_mfma_f32_16x16x32_bf16 v[114:117], v[178:181], v[186:189], v[114:117]
	v_mfma_f32_16x16x32_bf16 v[98:101], v[178:181], v[194:197], v[98:101]
	v_mfma_f32_16x16x32_bf16 v[106:109], v[170:173], v[194:197], v[106:109]
	v_mfma_f32_16x16x32_bf16 v[90:93], v[170:173], v[202:205], v[90:93]
	v_mfma_f32_16x16x32_bf16 v[82:85], v[178:181], v[202:205], v[82:85]
	v_mfma_f32_16x16x32_bf16 v[66:69], v[178:181], v[210:213], v[66:69]
	v_mfma_f32_16x16x32_bf16 v[74:77], v[170:173], v[210:213], v[74:77]
	s_setprio 0
	s_barrier
	ds_read_b128 v[182:185], v154 offset:16384
	ds_read_b128 v[186:189], v154 offset:17408
	ds_read_b128 v[190:193], v154 offset:18432
	ds_read_b128 v[194:197], v154 offset:19456
	ds_read_b128 v[198:201], v154 offset:20480
	ds_read_b128 v[202:205], v154 offset:21504
	ds_read_b128 v[206:209], v154 offset:22528
	ds_read_b128 v[210:213], v154 offset:23552
	s_mov_b32 m0, s21
	s_nop 0
	global_load_lds_dwordx4 v146, s[74:75]
	s_add_u32 s10, s74, 0x100000
	s_mov_b32 m0, s23
	s_nop 0
	global_load_lds_dwordx4 v148, s[74:75]
	s_addc_u32 s11, s75, 0
	s_mov_b32 m0, s29
	s_nop 0
	global_load_lds_dwordx4 v146, s[10:11]
	s_nop 0
	s_mov_b32 m0, s30
	s_nop 0
	global_load_lds_dwordx4 v148, s[10:11]
	s_nop 0
	s_mov_b32 m0, s25
	s_nop 0
	global_load_lds_dwordx4 v1, s[84:85]
	s_nop 0
	s_mov_b32 m0, s31
	s_nop 0
	global_load_lds_dwordx4 v147, s[84:85]
	s_waitcnt vmcnt(8)
	s_waitcnt lgkmcnt(0)
	s_barrier
	s_setprio 1
	s_waitcnt lgkmcnt(7)
	v_mfma_f32_16x16x32_bf16 v[62:65], v[136:139], v[182:185], v[62:65]
	v_mfma_f32_16x16x32_bf16 v[54:57], v[158:161], v[182:185], v[54:57]
	s_waitcnt lgkmcnt(5)
	v_mfma_f32_16x16x32_bf16 v[38:41], v[158:161], v[190:193], v[38:41]
	v_mfma_f32_16x16x32_bf16 v[46:49], v[136:139], v[190:193], v[46:49]
	s_waitcnt lgkmcnt(3)
	v_mfma_f32_16x16x32_bf16 v[30:33], v[136:139], v[198:201], v[30:33]
	v_mfma_f32_16x16x32_bf16 v[22:25], v[158:161], v[198:201], v[22:25]
	s_waitcnt lgkmcnt(1)
	v_mfma_f32_16x16x32_bf16 v[6:9], v[158:161], v[206:209], v[6:9]
	v_mfma_f32_16x16x32_bf16 v[14:17], v[136:139], v[206:209], v[14:17]
	v_mfma_f32_16x16x32_bf16 v[62:65], v[140:143], v[186:189], v[62:65]
	v_mfma_f32_16x16x32_bf16 v[54:57], v[162:165], v[186:189], v[54:57]
	v_mfma_f32_16x16x32_bf16 v[38:41], v[162:165], v[194:197], v[38:41]
	v_mfma_f32_16x16x32_bf16 v[46:49], v[140:143], v[194:197], v[46:49]
	v_mfma_f32_16x16x32_bf16 v[30:33], v[140:143], v[202:205], v[30:33]
	v_mfma_f32_16x16x32_bf16 v[22:25], v[162:165], v[202:205], v[22:25]
	s_waitcnt lgkmcnt(0)
	v_mfma_f32_16x16x32_bf16 v[6:9], v[162:165], v[210:213], v[6:9]
	v_mfma_f32_16x16x32_bf16 v[14:17], v[140:143], v[210:213], v[14:17]
	s_setprio 0
	s_setprio 1
	v_mfma_f32_16x16x32_bf16 v[58:61], v[166:169], v[182:185], v[58:61]
	v_mfma_f32_16x16x32_bf16 v[50:53], v[174:177], v[182:185], v[50:53]
	v_mfma_f32_16x16x32_bf16 v[34:37], v[174:177], v[190:193], v[34:37]
	v_mfma_f32_16x16x32_bf16 v[42:45], v[166:169], v[190:193], v[42:45]
	v_mfma_f32_16x16x32_bf16 v[26:29], v[166:169], v[198:201], v[26:29]
	v_mfma_f32_16x16x32_bf16 v[18:21], v[174:177], v[198:201], v[18:21]
	v_mfma_f32_16x16x32_bf16 v[2:5], v[174:177], v[206:209], v[2:5]
	v_mfma_f32_16x16x32_bf16 v[10:13], v[166:169], v[206:209], v[10:13]
	v_mfma_f32_16x16x32_bf16 v[58:61], v[170:173], v[186:189], v[58:61]
	v_mfma_f32_16x16x32_bf16 v[50:53], v[178:181], v[186:189], v[50:53]
	v_mfma_f32_16x16x32_bf16 v[34:37], v[178:181], v[194:197], v[34:37]
	v_mfma_f32_16x16x32_bf16 v[42:45], v[170:173], v[194:197], v[42:45]
	v_mfma_f32_16x16x32_bf16 v[26:29], v[170:173], v[202:205], v[26:29]
	v_mfma_f32_16x16x32_bf16 v[18:21], v[178:181], v[202:205], v[18:21]
	v_mfma_f32_16x16x32_bf16 v[2:5], v[178:181], v[210:213], v[2:5]
	v_mfma_f32_16x16x32_bf16 v[10:13], v[170:173], v[210:213], v[10:13]
	s_setprio 0
	s_barrier
; #define PG8_STAGE(bufoff, gbase, voff) do { if constexpr (VAR != 1 && VAR != 3) { _Pragma("unroll") for (int _i = 0; _i < 2; ++_i) \
;         asm volatile("s_mov_b32 m0, %2\n\ts_nop 0\n\tglobal_load_lds_dwordx4 %0, %1" :: "v"((voff)[_i]), "s"((const char*)(gbase)), "s"(ldsbase + (unsigned)((bufoff) + _i * 8192)) : "memory", "m0"); } } while (0)
; #define PG8_LDA(dst, b, h) do { if constexpr (VAR < 2) _Pragma("unroll") for (int m = 0; m < 4; ++m) _Pragma("unroll") for (int k = 0; k < 2; ++k) dst[m][k] = *(const LAS bf16x8*)(lds + PG8_SA(b, h) + aoff + m * 2048 + k * 1024); } while (0)
; #define PG8_LDB(dst, b, h) do { if constexpr (VAR < 2) _Pragma("unroll") for (int n = 0; n < 2; ++n) _Pragma("unroll") for (int k = 0; k < 2; ++k) dst[n][k] = *(const LAS bf16x8*)(lds + PG8_SB(b, h) + boff + n * 2048 + k * 1024); } while (0)
; #define PG8_WAIT_V(n) asm volatile("s_waitcnt vmcnt(" #n ")" ::: "memory")
; #define PG8_WAIT_L(n) asm volatile("s_waitcnt lgkmcnt(" #n ")" ::: "memory")
; #define PG8_BAR do { if constexpr (VAR != 3) __builtin_amdgcn_s_barrier(); } while (0)
; #define PG8_SCHED __builtin_amdgcn_sched_barrier(0)
;     ...
;             PG8_LDB(B0, 1, 0); PG8_LDB(B1, 1, 1); PG8_SCHED; PG8_LDA(At, 1, 0); PG8_STAGE(PG8_SA(0, 1), a2 + hstepA, voffA);
;             PG8_WAIT_V(8); PG8_WAIT_L(0); PG8_BAR; PG8_MMA(0, 0, At, B0); PG8_MMA(0, 1, At, B1); PG8_BAR; PG8_SCHED;
;             PG8_LDA(At, 1, 1); PG8_STAGE(PG8_SB(1, 0), b3, voffB); PG8_STAGE(PG8_SB(1, 1), b3 + hstepB, voffB); PG8_STAGE(PG8_SA(1, 0), a3, voffA);
;             PG8_WAIT_V(8); PG8_WAIT_L(0); PG8_BAR; PG8_MMA(1, 0, At, B0); PG8_MMA(1, 1, At, B1); PG8_BAR; PG8_SCHED;
;         }
;         if (wr == 0) PG8_BAR;
	ds_read_b128 v[136:139], v155
	ds_read_b128 v[140:143], v155 offset:1024
	ds_read_b128 v[158:161], v155 offset:2048
	ds_read_b128 v[162:165], v155 offset:3072
	ds_read_b128 v[166:169], v156
	ds_read_b128 v[170:173], v156 offset:1024
	ds_read_b128 v[174:177], v156 offset:2048
	ds_read_b128 v[178:181], v156 offset:3072
	ds_read_b128 v[182:185], v154 offset:32768
	ds_read_b128 v[186:189], v154 offset:33792
	ds_read_b128 v[190:193], v154 offset:34816
	ds_read_b128 v[194:197], v154 offset:35840
	ds_read_b128 v[198:201], v154 offset:36864
	ds_read_b128 v[202:205], v154 offset:37888
	ds_read_b128 v[206:209], v154 offset:38912
	ds_read_b128 v[210:213], v154 offset:39936
	s_add_u32 s10, s84, 0x100000
	s_addc_u32 s11, s85, 0
	s_mov_b32 m0, s33
	s_nop 0
	global_load_lds_dwordx4 v1, s[10:11]
	s_nop 0
	s_mov_b32 m0, s35
	s_nop 0
	global_load_lds_dwordx4 v147, s[10:11]
	s_waitcnt vmcnt(8)
	s_waitcnt lgkmcnt(0)
	s_barrier
	s_setprio 1
	s_waitcnt lgkmcnt(7)
	v_mfma_f32_16x16x32_bf16 v[126:129], v[136:139], v[182:185], v[126:129]
	v_mfma_f32_16x16x32_bf16 v[118:121], v[158:161], v[182:185], v[118:121]
	s_waitcnt lgkmcnt(5)
	v_mfma_f32_16x16x32_bf16 v[102:105], v[158:161], v[190:193], v[102:105]
	v_mfma_f32_16x16x32_bf16 v[110:113], v[136:139], v[190:193], v[110:113]
	s_waitcnt lgkmcnt(3)
	v_mfma_f32_16x16x32_bf16 v[94:97], v[136:139], v[198:201], v[94:97]
	v_mfma_f32_16x16x32_bf16 v[86:89], v[158:161], v[198:201], v[86:89]
	s_waitcnt lgkmcnt(1)
	v_mfma_f32_16x16x32_bf16 v[70:73], v[158:161], v[206:209], v[70:73]
	v_mfma_f32_16x16x32_bf16 v[78:81], v[136:139], v[206:209], v[78:81]
	v_mfma_f32_16x16x32_bf16 v[126:129], v[140:143], v[186:189], v[126:129]
	v_mfma_f32_16x16x32_bf16 v[118:121], v[162:165], v[186:189], v[118:121]
	v_mfma_f32_16x16x32_bf16 v[102:105], v[162:165], v[194:197], v[102:105]
	v_mfma_f32_16x16x32_bf16 v[110:113], v[140:143], v[194:197], v[110:113]
	v_mfma_f32_16x16x32_bf16 v[94:97], v[140:143], v[202:205], v[94:97]
	v_mfma_f32_16x16x32_bf16 v[86:89], v[162:165], v[202:205], v[86:89]
	s_waitcnt lgkmcnt(0)
	v_mfma_f32_16x16x32_bf16 v[70:73], v[162:165], v[210:213], v[70:73]
	v_mfma_f32_16x16x32_bf16 v[78:81], v[140:143], v[210:213], v[78:81]
	s_setprio 0
	s_setprio 1
	v_mfma_f32_16x16x32_bf16 v[122:125], v[166:169], v[182:185], v[122:125]
	v_mfma_f32_16x16x32_bf16 v[114:117], v[174:177], v[182:185], v[114:117]
	v_mfma_f32_16x16x32_bf16 v[98:101], v[174:177], v[190:193], v[98:101]
	v_mfma_f32_16x16x32_bf16 v[106:109], v[166:169], v[190:193], v[106:109]
	v_mfma_f32_16x16x32_bf16 v[90:93], v[166:169], v[198:201], v[90:93]
	v_mfma_f32_16x16x32_bf16 v[82:85], v[174:177], v[198:201], v[82:85]
	v_mfma_f32_16x16x32_bf16 v[66:69], v[174:177], v[206:209], v[66:69]
	v_mfma_f32_16x16x32_bf16 v[74:77], v[166:169], v[206:209], v[74:77]
	v_mfma_f32_16x16x32_bf16 v[122:125], v[170:173], v[186:189], v[122:125]
	v_mfma_f32_16x16x32_bf16 v[114:117], v[178:181], v[186:189], v[114:117]
	v_mfma_f32_16x16x32_bf16 v[98:101], v[178:181], v[194:197], v[98:101]
	v_mfma_f32_16x16x32_bf16 v[106:109], v[170:173], v[194:197], v[106:109]
	v_mfma_f32_16x16x32_bf16 v[90:93], v[170:173], v[202:205], v[90:93]
	v_mfma_f32_16x16x32_bf16 v[82:85], v[178:181], v[202:205], v[82:85]
	v_mfma_f32_16x16x32_bf16 v[66:69], v[178:181], v[210:213], v[66:69]
	v_mfma_f32_16x16x32_bf16 v[74:77], v[170:173], v[210:213], v[74:77]
	s_setprio 0
	s_barrier
	ds_read_b128 v[182:185], v154 offset:49152
	ds_read_b128 v[186:189], v154 offset:50176
	ds_read_b128 v[190:193], v154 offset:51200
	ds_read_b128 v[194:197], v154 offset:52224
	ds_read_b128 v[198:201], v154 offset:53248
	ds_read_b128 v[202:205], v154 offset:54272
	ds_read_b128 v[206:209], v154 offset:55296
	ds_read_b128 v[210:213], v154 offset:56320
	s_add_u32 s10, s74, 0x80
	s_addc_u32 s11, s75, 0
	s_mov_b32 m0, s52
	s_nop 0
	global_load_lds_dwordx4 v146, s[10:11]
	s_nop 0
	s_mov_b32 m0, s53
	s_nop 0
	global_load_lds_dwordx4 v148, s[10:11]
	s_add_u32 s10, s74, 0x100080
	s_addc_u32 s11, s75, 0
	s_mov_b32 m0, s62
	s_nop 0
	global_load_lds_dwordx4 v146, s[10:11]
	s_nop 0
	s_mov_b32 m0, s63
	s_nop 0
	global_load_lds_dwordx4 v148, s[10:11]
	s_nop 0
	s_mov_b32 m0, s56
	s_nop 0
	global_load_lds_dwordx4 v1, s[72:73]
	s_nop 0
	s_mov_b32 m0, s57
	s_nop 0
	global_load_lds_dwordx4 v147, s[72:73]
	s_waitcnt vmcnt(8)
	s_waitcnt lgkmcnt(0)
	s_barrier
	s_setprio 1
	s_waitcnt lgkmcnt(7)
	v_mfma_f32_16x16x32_bf16 v[62:65], v[136:139], v[182:185], v[62:65]
	v_mfma_f32_16x16x32_bf16 v[54:57], v[158:161], v[182:185], v[54:57]
	s_waitcnt lgkmcnt(5)
	v_mfma_f32_16x16x32_bf16 v[38:41], v[158:161], v[190:193], v[38:41]
	v_mfma_f32_16x16x32_bf16 v[46:49], v[136:139], v[190:193], v[46:49]
	s_waitcnt lgkmcnt(3)
	v_mfma_f32_16x16x32_bf16 v[30:33], v[136:139], v[198:201], v[30:33]
	v_mfma_f32_16x16x32_bf16 v[22:25], v[158:161], v[198:201], v[22:25]
	s_waitcnt lgkmcnt(1)
	v_mfma_f32_16x16x32_bf16 v[6:9], v[158:161], v[206:209], v[6:9]
	v_mfma_f32_16x16x32_bf16 v[14:17], v[136:139], v[206:209], v[14:17]
	v_mfma_f32_16x16x32_bf16 v[62:65], v[140:143], v[186:189], v[62:65]
	v_mfma_f32_16x16x32_bf16 v[54:57], v[162:165], v[186:189], v[54:57]
	v_mfma_f32_16x16x32_bf16 v[38:41], v[162:165], v[194:197], v[38:41]
	v_mfma_f32_16x16x32_bf16 v[46:49], v[140:143], v[194:197], v[46:49]
	v_mfma_f32_16x16x32_bf16 v[30:33], v[140:143], v[202:205], v[30:33]
	v_mfma_f32_16x16x32_bf16 v[22:25], v[162:165], v[202:205], v[22:25]
	s_waitcnt lgkmcnt(0)
	v_mfma_f32_16x16x32_bf16 v[6:9], v[162:165], v[210:213], v[6:9]
	v_mfma_f32_16x16x32_bf16 v[14:17], v[140:143], v[210:213], v[14:17]
	s_setprio 0
	s_setprio 1
	v_mfma_f32_16x16x32_bf16 v[58:61], v[166:169], v[182:185], v[58:61]
	v_mfma_f32_16x16x32_bf16 v[50:53], v[174:177], v[182:185], v[50:53]
	v_mfma_f32_16x16x32_bf16 v[34:37], v[174:177], v[190:193], v[34:37]
	v_mfma_f32_16x16x32_bf16 v[42:45], v[166:169], v[190:193], v[42:45]
	v_mfma_f32_16x16x32_bf16 v[26:29], v[166:169], v[198:201], v[26:29]
	v_mfma_f32_16x16x32_bf16 v[18:21], v[174:177], v[198:201], v[18:21]
	v_mfma_f32_16x16x32_bf16 v[2:5], v[174:177], v[206:209], v[2:5]
	v_mfma_f32_16x16x32_bf16 v[10:13], v[166:169], v[206:209], v[10:13]
	v_mfma_f32_16x16x32_bf16 v[58:61], v[170:173], v[186:189], v[58:61]
	v_mfma_f32_16x16x32_bf16 v[50:53], v[178:181], v[186:189], v[50:53]
	v_mfma_f32_16x16x32_bf16 v[34:37], v[178:181], v[194:197], v[34:37]
	v_mfma_f32_16x16x32_bf16 v[42:45], v[170:173], v[194:197], v[42:45]
	v_mfma_f32_16x16x32_bf16 v[26:29], v[170:173], v[202:205], v[26:29]
	v_mfma_f32_16x16x32_bf16 v[18:21], v[178:181], v[202:205], v[18:21]
	v_mfma_f32_16x16x32_bf16 v[2:5], v[178:181], v[210:213], v[2:5]
	v_mfma_f32_16x16x32_bf16 v[10:13], v[170:173], v[210:213], v[10:13]
	s_setprio 0
	s_barrier
	s_add_i32 s6, s6, 2
	s_add_u32 s65, s65, 0x100
	s_addc_u32 s92, s92, 0
	s_add_u32 s93, s93, 0x100
	s_addc_u32 s94, s94, 0
	s_add_u32 s70, s70, 0x100
	s_addc_u32 s71, s71, 0
	s_cmp_gt_u32 s6, 61
	s_cbranch_scc0 .LBB0_561
	s_and_b64 vcc, exec, s[54:55]
	s_cbranch_vccz .LBB0_564
	s_barrier

; #define PG8_STAGE(bufoff, gbase, voff) do { if constexpr (VAR != 1 && VAR != 3) { _Pragma("unroll") for (int _i = 0; _i < 2; ++_i) \
;         asm volatile("s_mov_b32 m0, %2\n\ts_nop 0\n\tglobal_load_lds_dwordx4 %0, %1" :: "v"((voff)[_i]), "s"((const char*)(gbase)), "s"(ldsbase + (unsigned)((bufoff) + _i * 8192)) : "memory", "m0"); } } while (0)
; #define PG8_LDA(dst, b, h) do { if constexpr (VAR < 2) _Pragma("unroll") for (int m = 0; m < 4; ++m) _Pragma("unroll") for (int k = 0; k < 2; ++k) dst[m][k] = *(const LAS bf16x8*)(lds + PG8_SA(b, h) + aoff + m * 2048 + k * 1024); } while (0)
; #define PG8_LDB(dst, b, h) do { if constexpr (VAR < 2) _Pragma("unroll") for (int n = 0; n < 2; ++n) _Pragma("unroll") for (int k = 0; k < 2; ++k) dst[n][k] = *(const LAS bf16x8*)(lds + PG8_SB(b, h) + boff + n * 2048 + k * 1024); } while (0)
; #define PG8_WAIT_V(n) asm volatile("s_waitcnt vmcnt(" #n ")" ::: "memory")
; #define PG8_WAIT_L(n) asm volatile("s_waitcnt lgkmcnt(" #n ")" ::: "memory")
; #define PG8_BAR do { if constexpr (VAR != 3) __builtin_amdgcn_s_barrier(); } while (0)
; #define PG8_SCHED __builtin_amdgcn_sched_barrier(0)
;     ...
;             PG8_LDB(B0, 0, 0); PG8_LDB(B1, 0, 1); PG8_SCHED; PG8_LDA(At, 0, 0); PG8_STAGE(PG8_SA(1, 1), a1 + hstepA, voffA);
;             PG8_WAIT_V(8); PG8_WAIT_L(0); PG8_BAR; PG8_MMA(0, 0, At, B0); PG8_MMA(0, 1, At, B1); PG8_BAR; PG8_SCHED;
;             PG8_LDA(At, 0, 1); PG8_STAGE(PG8_SB(0, 0), b2, voffB); PG8_STAGE(PG8_SB(0, 1), b2 + hstepB, voffB); PG8_STAGE(PG8_SA(0, 0), a2, voffA);
;             PG8_WAIT_V(8); PG8_WAIT_L(0); PG8_BAR; PG8_MMA(1, 0, At, B0); PG8_MMA(1, 1, At, B1); PG8_BAR; PG8_SCHED;
.LBB0_673:
	ds_read_b128 v[150:153], v183
	ds_read_b128 v[154:157], v183 offset:1024
	ds_read_b128 v[158:161], v183 offset:2048
	ds_read_b128 v[162:165], v183 offset:3072
	ds_read_b128 v[166:169], v184
	ds_read_b128 v[188:191], v184 offset:1024
	ds_read_b128 v[192:195], v184 offset:2048
	ds_read_b128 v[196:199], v184 offset:3072
	s_cmp_eq_u32 s6, 12
	s_cselect_b32 s82, s0, s75
	s_cselect_b32 s83, s1, s92
	s_cselect_b32 s80, s76, s93
	s_cselect_b32 s81, s77, s94
	s_add_u32 s78, s82, 0x80
	s_addc_u32 s79, s83, 0
	ds_read_b128 v[200:203], v185
	ds_read_b128 v[204:207], v185 offset:1024
	ds_read_b128 v[208:211], v185 offset:2048
	ds_read_b128 v[212:215], v185 offset:3072
	ds_read_b128 v[216:219], v185 offset:4096
	ds_read_b128 v[220:223], v185 offset:5120
	ds_read_b128 v[224:227], v185 offset:6144
	ds_read_b128 v[228:231], v185 offset:7168
	s_mov_b32 m0, s85
	s_nop 0
	global_load_lds_dwordx4 v178, s[4:5]
	s_nop 0
	s_mov_b32 m0, s86
	s_nop 0
	global_load_lds_dwordx4 v180, s[4:5]
	s_waitcnt vmcnt(8)
	s_waitcnt lgkmcnt(0)
	s_barrier
	s_setprio 1
	s_waitcnt lgkmcnt(7)
	v_mfma_f32_16x16x32_bf16 v[126:129], v[150:153], v[200:203], v[126:129]
	v_mfma_f32_16x16x32_bf16 v[122:125], v[158:161], v[200:203], v[122:125]
	s_waitcnt lgkmcnt(5)
	v_mfma_f32_16x16x32_bf16 v[106:109], v[158:161], v[208:211], v[106:109]
	v_mfma_f32_16x16x32_bf16 v[114:117], v[150:153], v[208:211], v[114:117]
	s_waitcnt lgkmcnt(3)
	v_mfma_f32_16x16x32_bf16 v[98:101], v[150:153], v[216:219], v[98:101]
	v_mfma_f32_16x16x32_bf16 v[90:93], v[158:161], v[216:219], v[90:93]
	s_waitcnt lgkmcnt(1)
	v_mfma_f32_16x16x32_bf16 v[74:77], v[158:161], v[224:227], v[74:77]
	v_mfma_f32_16x16x32_bf16 v[82:85], v[150:153], v[224:227], v[82:85]
	v_mfma_f32_16x16x32_bf16 v[126:129], v[154:157], v[204:207], v[126:129]
	v_mfma_f32_16x16x32_bf16 v[122:125], v[162:165], v[204:207], v[122:125]
	v_mfma_f32_16x16x32_bf16 v[106:109], v[162:165], v[212:215], v[106:109]
	v_mfma_f32_16x16x32_bf16 v[114:117], v[154:157], v[212:215], v[114:117]
	v_mfma_f32_16x16x32_bf16 v[98:101], v[154:157], v[220:223], v[98:101]
	v_mfma_f32_16x16x32_bf16 v[90:93], v[162:165], v[220:223], v[90:93]
	s_waitcnt lgkmcnt(0)
	v_mfma_f32_16x16x32_bf16 v[74:77], v[162:165], v[228:231], v[74:77]
	v_mfma_f32_16x16x32_bf16 v[82:85], v[154:157], v[228:231], v[82:85]
	s_setprio 0
	s_setprio 1
	v_mfma_f32_16x16x32_bf16 v[118:121], v[166:169], v[200:203], v[118:121]
	v_mfma_f32_16x16x32_bf16 v[110:113], v[192:195], v[200:203], v[110:113]
	v_mfma_f32_16x16x32_bf16 v[94:97], v[192:195], v[208:211], v[94:97]
	v_mfma_f32_16x16x32_bf16 v[102:105], v[166:169], v[208:211], v[102:105]
	v_mfma_f32_16x16x32_bf16 v[86:89], v[166:169], v[216:219], v[86:89]
	v_mfma_f32_16x16x32_bf16 v[78:81], v[192:195], v[216:219], v[78:81]
	v_mfma_f32_16x16x32_bf16 v[66:69], v[192:195], v[224:227], v[66:69]
	v_mfma_f32_16x16x32_bf16 v[70:73], v[166:169], v[224:227], v[70:73]
	v_mfma_f32_16x16x32_bf16 v[118:121], v[188:191], v[204:207], v[118:121]
	v_mfma_f32_16x16x32_bf16 v[110:113], v[196:199], v[204:207], v[110:113]
	v_mfma_f32_16x16x32_bf16 v[94:97], v[196:199], v[212:215], v[94:97]
	v_mfma_f32_16x16x32_bf16 v[102:105], v[188:191], v[212:215], v[102:105]
	v_mfma_f32_16x16x32_bf16 v[86:89], v[188:191], v[220:223], v[86:89]
	v_mfma_f32_16x16x32_bf16 v[78:81], v[196:199], v[220:223], v[78:81]
	v_mfma_f32_16x16x32_bf16 v[66:69], v[196:199], v[228:231], v[66:69]
	v_mfma_f32_16x16x32_bf16 v[70:73], v[188:191], v[228:231], v[70:73]
	s_setprio 0
	s_barrier
	ds_read_b128 v[200:203], v185 offset:16384
	ds_read_b128 v[204:207], v185 offset:17408
	ds_read_b128 v[208:211], v185 offset:18432
	ds_read_b128 v[212:215], v185 offset:19456
	ds_read_b128 v[216:219], v185 offset:20480
	ds_read_b128 v[220:223], v185 offset:21504
	ds_read_b128 v[224:227], v185 offset:22528
	ds_read_b128 v[228:231], v185 offset:23552
	s_mov_b32 m0, s24
	s_nop 0
	global_load_lds_dwordx4 v179, s[80:81]
	s_add_u32 s96, s80, 0x100000
	s_mov_b32 m0, s25
	s_nop 0
	global_load_lds_dwordx4 v181, s[80:81]
	s_addc_u32 s97, s81, 0
	s_mov_b32 m0, s26
	s_nop 0
	global_load_lds_dwordx4 v179, s[96:97]
	s_nop 0
	s_mov_b32 m0, s27
	s_nop 0
	global_load_lds_dwordx4 v181, s[96:97]
	s_nop 0
	s_mov_b32 m0, s15
	s_nop 0
	global_load_lds_dwordx4 v178, s[82:83]
	s_nop 0
	s_mov_b32 m0, s28
	s_nop 0
	global_load_lds_dwordx4 v180, s[82:83]
	s_waitcnt vmcnt(8)
	s_waitcnt lgkmcnt(0)
	s_barrier
	s_setprio 1
	s_waitcnt lgkmcnt(7)
	v_mfma_f32_16x16x32_bf16 v[62:65], v[150:153], v[200:203], v[62:65]
	v_mfma_f32_16x16x32_bf16 v[58:61], v[158:161], v[200:203], v[58:61]
	s_waitcnt lgkmcnt(5)
	v_mfma_f32_16x16x32_bf16 v[42:45], v[158:161], v[208:211], v[42:45]
	v_mfma_f32_16x16x32_bf16 v[50:53], v[150:153], v[208:211], v[50:53]
	s_waitcnt lgkmcnt(3)
	v_mfma_f32_16x16x32_bf16 v[34:37], v[150:153], v[216:219], v[34:37]
	v_mfma_f32_16x16x32_bf16 v[26:29], v[158:161], v[216:219], v[26:29]
	s_waitcnt lgkmcnt(1)
	v_mfma_f32_16x16x32_bf16 v[10:13], v[158:161], v[224:227], v[10:13]
	v_mfma_f32_16x16x32_bf16 v[18:21], v[150:153], v[224:227], v[18:21]
	v_mfma_f32_16x16x32_bf16 v[62:65], v[154:157], v[204:207], v[62:65]
	v_mfma_f32_16x16x32_bf16 v[58:61], v[162:165], v[204:207], v[58:61]
	v_mfma_f32_16x16x32_bf16 v[42:45], v[162:165], v[212:215], v[42:45]
	v_mfma_f32_16x16x32_bf16 v[50:53], v[154:157], v[212:215], v[50:53]
	v_mfma_f32_16x16x32_bf16 v[34:37], v[154:157], v[220:223], v[34:37]
	v_mfma_f32_16x16x32_bf16 v[26:29], v[162:165], v[220:223], v[26:29]
	s_waitcnt lgkmcnt(0)
	v_mfma_f32_16x16x32_bf16 v[10:13], v[162:165], v[228:231], v[10:13]
	v_mfma_f32_16x16x32_bf16 v[18:21], v[154:157], v[228:231], v[18:21]
	s_setprio 0
	s_setprio 1
	v_mfma_f32_16x16x32_bf16 v[54:57], v[166:169], v[200:203], v[54:57]
	v_mfma_f32_16x16x32_bf16 v[46:49], v[192:195], v[200:203], v[46:49]
	v_mfma_f32_16x16x32_bf16 v[30:33], v[192:195], v[208:211], v[30:33]
	v_mfma_f32_16x16x32_bf16 v[38:41], v[166:169], v[208:211], v[38:41]
	v_mfma_f32_16x16x32_bf16 v[22:25], v[166:169], v[216:219], v[22:25]
	v_mfma_f32_16x16x32_bf16 v[14:17], v[192:195], v[216:219], v[14:17]
	v_mfma_f32_16x16x32_bf16 v[2:5], v[192:195], v[224:227], v[2:5]
	v_mfma_f32_16x16x32_bf16 v[6:9], v[166:169], v[224:227], v[6:9]
	v_mfma_f32_16x16x32_bf16 v[54:57], v[188:191], v[204:207], v[54:57]
	v_mfma_f32_16x16x32_bf16 v[46:49], v[196:199], v[204:207], v[46:49]
	v_mfma_f32_16x16x32_bf16 v[30:33], v[196:199], v[212:215], v[30:33]
	v_mfma_f32_16x16x32_bf16 v[38:41], v[188:191], v[212:215], v[38:41]
	v_mfma_f32_16x16x32_bf16 v[22:25], v[188:191], v[220:223], v[22:25]
	v_mfma_f32_16x16x32_bf16 v[14:17], v[196:199], v[220:223], v[14:17]
	v_mfma_f32_16x16x32_bf16 v[2:5], v[196:199], v[228:231], v[2:5]
	v_mfma_f32_16x16x32_bf16 v[6:9], v[188:191], v[228:231], v[6:9]
	s_setprio 0
	s_barrier
; #define PG8_STAGE(bufoff, gbase, voff) do { if constexpr (VAR != 1 && VAR != 3) { _Pragma("unroll") for (int _i = 0; _i < 2; ++_i) \
;         asm volatile("s_mov_b32 m0, %2\n\ts_nop 0\n\tglobal_load_lds_dwordx4 %0, %1" :: "v"((voff)[_i]), "s"((const char*)(gbase)), "s"(ldsbase + (unsigned)((bufoff) + _i * 8192)) : "memory", "m0"); } } while (0)
; #define PG8_LDA(dst, b, h) do { if constexpr (VAR < 2) _Pragma("unroll") for (int m = 0; m < 4; ++m) _Pragma("unroll") for (int k = 0; k < 2; ++k) dst[m][k] = *(const LAS bf16x8*)(lds + PG8_SA(b, h) + aoff + m * 2048 + k * 1024); } while (0)
; #define PG8_LDB(dst, b, h) do { if constexpr (VAR < 2) _Pragma("unroll") for (int n = 0; n < 2; ++n) _Pragma("unroll") for (int k = 0; k < 2; ++k) dst[n][k] = *(const LAS bf16x8*)(lds + PG8_SB(b, h) + boff + n * 2048 + k * 1024); } while (0)
; #define PG8_WAIT_V(n) asm volatile("s_waitcnt vmcnt(" #n ")" ::: "memory")
; #define PG8_WAIT_L(n) asm volatile("s_waitcnt lgkmcnt(" #n ")" ::: "memory")
; #define PG8_BAR do { if constexpr (VAR != 3) __builtin_amdgcn_s_barrier(); } while (0)
; #define PG8_SCHED __builtin_amdgcn_sched_barrier(0)
;     ...
;             PG8_LDB(B0, 1, 0); PG8_LDB(B1, 1, 1); PG8_SCHED; PG8_LDA(At, 1, 0); PG8_STAGE(PG8_SA(0, 1), a2 + hstepA, voffA);
;             PG8_WAIT_V(8); PG8_WAIT_L(0); PG8_BAR; PG8_MMA(0, 0, At, B0); PG8_MMA(0, 1, At, B1); PG8_BAR; PG8_SCHED;
;             PG8_LDA(At, 1, 1); PG8_STAGE(PG8_SB(1, 0), b3, voffB); PG8_STAGE(PG8_SB(1, 1), b3 + hstepB, voffB); PG8_STAGE(PG8_SA(1, 0), a3, voffA);
;             PG8_WAIT_V(8); PG8_WAIT_L(0); PG8_BAR; PG8_MMA(1, 0, At, B0); PG8_MMA(1, 1, At, B1); PG8_BAR; PG8_SCHED;
;         }
;         if (wr == 0) PG8_BAR;
	ds_read_b128 v[150:153], v186
	ds_read_b128 v[154:157], v186 offset:1024
	ds_read_b128 v[158:161], v186 offset:2048
	ds_read_b128 v[162:165], v186 offset:3072
	ds_read_b128 v[166:169], v187
	ds_read_b128 v[188:191], v187 offset:1024
	ds_read_b128 v[192:195], v187 offset:2048
	ds_read_b128 v[196:199], v187 offset:3072
	ds_read_b128 v[200:203], v185 offset:32768
	ds_read_b128 v[204:207], v185 offset:33792
	ds_read_b128 v[208:211], v185 offset:34816
	ds_read_b128 v[212:215], v185 offset:35840
	ds_read_b128 v[216:219], v185 offset:36864
	ds_read_b128 v[220:223], v185 offset:37888
	ds_read_b128 v[224:227], v185 offset:38912
	ds_read_b128 v[228:231], v185 offset:39936
	s_add_u32 s82, s82, 0x200000
	s_addc_u32 s83, s83, 0
	s_mov_b32 m0, s29
	s_nop 0
	global_load_lds_dwordx4 v178, s[82:83]
	s_nop 0
	s_mov_b32 m0, s30
	s_nop 0
	global_load_lds_dwordx4 v180, s[82:83]
	s_waitcnt vmcnt(8)
	s_waitcnt lgkmcnt(0)
	s_barrier
	s_setprio 1
	s_waitcnt lgkmcnt(7)
	v_mfma_f32_16x16x32_bf16 v[126:129], v[150:153], v[200:203], v[126:129]
	v_mfma_f32_16x16x32_bf16 v[122:125], v[158:161], v[200:203], v[122:125]
	s_waitcnt lgkmcnt(5)
	v_mfma_f32_16x16x32_bf16 v[106:109], v[158:161], v[208:211], v[106:109]
	v_mfma_f32_16x16x32_bf16 v[114:117], v[150:153], v[208:211], v[114:117]
	s_waitcnt lgkmcnt(3)
	v_mfma_f32_16x16x32_bf16 v[98:101], v[150:153], v[216:219], v[98:101]
	v_mfma_f32_16x16x32_bf16 v[90:93], v[158:161], v[216:219], v[90:93]
	s_waitcnt lgkmcnt(1)
	v_mfma_f32_16x16x32_bf16 v[74:77], v[158:161], v[224:227], v[74:77]
	v_mfma_f32_16x16x32_bf16 v[82:85], v[150:153], v[224:227], v[82:85]
	v_mfma_f32_16x16x32_bf16 v[126:129], v[154:157], v[204:207], v[126:129]
	v_mfma_f32_16x16x32_bf16 v[122:125], v[162:165], v[204:207], v[122:125]
	v_mfma_f32_16x16x32_bf16 v[106:109], v[162:165], v[212:215], v[106:109]
	v_mfma_f32_16x16x32_bf16 v[114:117], v[154:157], v[212:215], v[114:117]
	v_mfma_f32_16x16x32_bf16 v[98:101], v[154:157], v[220:223], v[98:101]
	v_mfma_f32_16x16x32_bf16 v[90:93], v[162:165], v[220:223], v[90:93]
	s_waitcnt lgkmcnt(0)
	v_mfma_f32_16x16x32_bf16 v[74:77], v[162:165], v[228:231], v[74:77]
	v_mfma_f32_16x16x32_bf16 v[82:85], v[154:157], v[228:231], v[82:85]
	s_setprio 0
	s_setprio 1
	v_mfma_f32_16x16x32_bf16 v[118:121], v[166:169], v[200:203], v[118:121]
	v_mfma_f32_16x16x32_bf16 v[110:113], v[192:195], v[200:203], v[110:113]
	v_mfma_f32_16x16x32_bf16 v[94:97], v[192:195], v[208:211], v[94:97]
	v_mfma_f32_16x16x32_bf16 v[102:105], v[166:169], v[208:211], v[102:105]
	v_mfma_f32_16x16x32_bf16 v[86:89], v[166:169], v[216:219], v[86:89]
	v_mfma_f32_16x16x32_bf16 v[78:81], v[192:195], v[216:219], v[78:81]
	v_mfma_f32_16x16x32_bf16 v[66:69], v[192:195], v[224:227], v[66:69]
	v_mfma_f32_16x16x32_bf16 v[70:73], v[166:169], v[224:227], v[70:73]
	v_mfma_f32_16x16x32_bf16 v[118:121], v[188:191], v[204:207], v[118:121]
	v_mfma_f32_16x16x32_bf16 v[110:113], v[196:199], v[204:207], v[110:113]
	v_mfma_f32_16x16x32_bf16 v[94:97], v[196:199], v[212:215], v[94:97]
	v_mfma_f32_16x16x32_bf16 v[102:105], v[188:191], v[212:215], v[102:105]
	v_mfma_f32_16x16x32_bf16 v[86:89], v[188:191], v[220:223], v[86:89]
	v_mfma_f32_16x16x32_bf16 v[78:81], v[196:199], v[220:223], v[78:81]
	v_mfma_f32_16x16x32_bf16 v[66:69], v[196:199], v[228:231], v[66:69]
	v_mfma_f32_16x16x32_bf16 v[70:73], v[188:191], v[228:231], v[70:73]
	s_setprio 0
	s_barrier
	ds_read_b128 v[200:203], v185 offset:49152
	ds_read_b128 v[204:207], v185 offset:50176
	ds_read_b128 v[208:211], v185 offset:51200
	ds_read_b128 v[212:215], v185 offset:52224
	ds_read_b128 v[216:219], v185 offset:53248
	ds_read_b128 v[220:223], v185 offset:54272
	ds_read_b128 v[224:227], v185 offset:55296
	ds_read_b128 v[228:231], v185 offset:56320
	s_add_u32 s82, s80, 0x80
	s_addc_u32 s83, s81, 0
	s_mov_b32 m0, s31
	s_nop 0
	global_load_lds_dwordx4 v179, s[82:83]
	s_add_u32 s80, s80, 0x100080
	s_mov_b32 m0, s33
	s_nop 0
	global_load_lds_dwordx4 v181, s[82:83]
	s_addc_u32 s81, s81, 0
	s_mov_b32 m0, s73
	s_nop 0
	global_load_lds_dwordx4 v179, s[80:81]
	s_nop 0
	s_mov_b32 m0, s84
	s_nop 0
	global_load_lds_dwordx4 v181, s[80:81]
	s_nop 0
	s_mov_b32 m0, s56
	s_nop 0
	global_load_lds_dwordx4 v178, s[78:79]
	s_nop 0
	s_mov_b32 m0, s57
	s_nop 0
	global_load_lds_dwordx4 v180, s[78:79]
	s_waitcnt vmcnt(8)
	s_waitcnt lgkmcnt(0)
	s_barrier
	s_setprio 1
	s_waitcnt lgkmcnt(7)
	v_mfma_f32_16x16x32_bf16 v[62:65], v[150:153], v[200:203], v[62:65]
	v_mfma_f32_16x16x32_bf16 v[58:61], v[158:161], v[200:203], v[58:61]
	s_waitcnt lgkmcnt(5)
	v_mfma_f32_16x16x32_bf16 v[42:45], v[158:161], v[208:211], v[42:45]
	v_mfma_f32_16x16x32_bf16 v[50:53], v[150:153], v[208:211], v[50:53]
	s_waitcnt lgkmcnt(3)
	v_mfma_f32_16x16x32_bf16 v[34:37], v[150:153], v[216:219], v[34:37]
	v_mfma_f32_16x16x32_bf16 v[26:29], v[158:161], v[216:219], v[26:29]
	s_waitcnt lgkmcnt(1)
	v_mfma_f32_16x16x32_bf16 v[10:13], v[158:161], v[224:227], v[10:13]
	v_mfma_f32_16x16x32_bf16 v[18:21], v[150:153], v[224:227], v[18:21]
	v_mfma_f32_16x16x32_bf16 v[62:65], v[154:157], v[204:207], v[62:65]
	v_mfma_f32_16x16x32_bf16 v[58:61], v[162:165], v[204:207], v[58:61]
	v_mfma_f32_16x16x32_bf16 v[42:45], v[162:165], v[212:215], v[42:45]
	v_mfma_f32_16x16x32_bf16 v[50:53], v[154:157], v[212:215], v[50:53]
	v_mfma_f32_16x16x32_bf16 v[34:37], v[154:157], v[220:223], v[34:37]
	v_mfma_f32_16x16x32_bf16 v[26:29], v[162:165], v[220:223], v[26:29]
	s_waitcnt lgkmcnt(0)
	v_mfma_f32_16x16x32_bf16 v[10:13], v[162:165], v[228:231], v[10:13]
	v_mfma_f32_16x16x32_bf16 v[18:21], v[154:157], v[228:231], v[18:21]
	s_setprio 0
	s_setprio 1
	v_mfma_f32_16x16x32_bf16 v[54:57], v[166:169], v[200:203], v[54:57]
	v_mfma_f32_16x16x32_bf16 v[46:49], v[192:195], v[200:203], v[46:49]
	v_mfma_f32_16x16x32_bf16 v[30:33], v[192:195], v[208:211], v[30:33]
	v_mfma_f32_16x16x32_bf16 v[38:41], v[166:169], v[208:211], v[38:41]
	v_mfma_f32_16x16x32_bf16 v[22:25], v[166:169], v[216:219], v[22:25]
	v_mfma_f32_16x16x32_bf16 v[14:17], v[192:195], v[216:219], v[14:17]
	v_mfma_f32_16x16x32_bf16 v[2:5], v[192:195], v[224:227], v[2:5]
	v_mfma_f32_16x16x32_bf16 v[6:9], v[166:169], v[224:227], v[6:9]
	v_mfma_f32_16x16x32_bf16 v[54:57], v[188:191], v[204:207], v[54:57]
	v_mfma_f32_16x16x32_bf16 v[46:49], v[196:199], v[204:207], v[46:49]
	v_mfma_f32_16x16x32_bf16 v[30:33], v[196:199], v[212:215], v[30:33]
	v_mfma_f32_16x16x32_bf16 v[38:41], v[188:191], v[212:215], v[38:41]
	v_mfma_f32_16x16x32_bf16 v[22:25], v[188:191], v[220:223], v[22:25]
	v_mfma_f32_16x16x32_bf16 v[14:17], v[196:199], v[220:223], v[14:17]
	v_mfma_f32_16x16x32_bf16 v[2:5], v[196:199], v[228:231], v[2:5]
	v_mfma_f32_16x16x32_bf16 v[6:9], v[188:191], v[228:231], v[6:9]
	s_setprio 0
	s_barrier
	s_add_i32 s6, s6, 2
	s_add_u32 s75, s75, 0x100
	s_addc_u32 s92, s92, 0
	s_add_u32 s93, s93, 0x100
	s_addc_u32 s94, s94, 0
	s_add_u32 s4, s4, 0x100
	s_addc_u32 s5, s5, 0
	s_cmp_gt_u32 s6, 13
	s_cbranch_scc0 .LBB0_673
	s_and_b64 vcc, exec, s[70:71]
	s_cbranch_vccz .LBB0_676
	s_barrier

; #define PG8_STAGE(bufoff, gbase, voff) do { if constexpr (VAR != 1 && VAR != 3) { _Pragma("unroll") for (int _i = 0; _i < 2; ++_i) \
;         asm volatile("s_mov_b32 m0, %2\n\ts_nop 0\n\tglobal_load_lds_dwordx4 %0, %1" :: "v"((voff)[_i]), "s"((const char*)(gbase)), "s"(ldsbase + (unsigned)((bufoff) + _i * 8192)) : "memory", "m0"); } } while (0)
; #define PG8_LDA(dst, b, h) do { if constexpr (VAR < 2) _Pragma("unroll") for (int m = 0; m < 4; ++m) _Pragma("unroll") for (int k = 0; k < 2; ++k) dst[m][k] = *(const LAS bf16x8*)(lds + PG8_SA(b, h) + aoff + m * 2048 + k * 1024); } while (0)
; #define PG8_LDB(dst, b, h) do { if constexpr (VAR < 2) _Pragma("unroll") for (int n = 0; n < 2; ++n) _Pragma("unroll") for (int k = 0; k < 2; ++k) dst[n][k] = *(const LAS bf16x8*)(lds + PG8_SB(b, h) + boff + n * 2048 + k * 1024); } while (0)
; #define PG8_WAIT_V(n) asm volatile("s_waitcnt vmcnt(" #n ")" ::: "memory")
; #define PG8_WAIT_L(n) asm volatile("s_waitcnt lgkmcnt(" #n ")" ::: "memory")
; #define PG8_BAR do { if constexpr (VAR != 3) __builtin_amdgcn_s_barrier(); } while (0)
; #define PG8_SCHED __builtin_amdgcn_sched_barrier(0)
;     ...
;             PG8_LDB(B0, 0, 0); PG8_LDB(B1, 0, 1); PG8_SCHED; PG8_LDA(At, 0, 0); PG8_STAGE(PG8_SA(1, 1), a1 + hstepA, voffA);
;             PG8_WAIT_V(8); PG8_WAIT_L(0); PG8_BAR; PG8_MMA(0, 0, At, B0); PG8_MMA(0, 1, At, B1); PG8_BAR; PG8_SCHED;
;             PG8_LDA(At, 0, 1); PG8_STAGE(PG8_SB(0, 0), b2, voffB); PG8_STAGE(PG8_SB(0, 1), b2 + hstepB, voffB); PG8_STAGE(PG8_SA(0, 0), a2, voffA);
;             PG8_WAIT_V(8); PG8_WAIT_L(0); PG8_BAR; PG8_MMA(1, 0, At, B0); PG8_MMA(1, 1, At, B1); PG8_BAR; PG8_SCHED;
.LBB0_701:
	ds_read_b128 v[148:151], v1
	ds_read_b128 v[152:155], v1 offset:1024
	ds_read_b128 v[156:159], v1 offset:2048
	ds_read_b128 v[160:163], v1 offset:3072
	ds_read_b128 v[164:167], v143
	ds_read_b128 v[168:171], v143 offset:1024
	ds_read_b128 v[172:175], v143 offset:2048
	ds_read_b128 v[176:179], v143 offset:3072
	s_cmp_eq_u32 s6, 12
	s_cselect_b32 s70, s0, s57
	s_cselect_b32 s71, s1, s81
	s_cselect_b32 s68, s62, s82
	s_cselect_b32 s69, s63, s83
	s_add_u32 s66, s70, 0x80
	s_addc_u32 s67, s71, 0
	ds_read_b128 v[180:183], v144
	ds_read_b128 v[184:187], v144 offset:1024
	ds_read_b128 v[188:191], v144 offset:2048
	ds_read_b128 v[192:195], v144 offset:3072
	ds_read_b128 v[196:199], v144 offset:4096
	ds_read_b128 v[200:203], v144 offset:5120
	ds_read_b128 v[204:207], v144 offset:6144
	ds_read_b128 v[208:211], v144 offset:7168
	s_mov_b32 m0, s76
	s_nop 0
	global_load_lds_dwordx4 v138, s[64:65]
	s_nop 0
	s_mov_b32 m0, s77
	s_nop 0
	global_load_lds_dwordx4 v140, s[64:65]
	s_waitcnt vmcnt(8)
	s_waitcnt lgkmcnt(0)
	s_barrier
	s_setprio 1
	s_waitcnt lgkmcnt(7)
	v_mfma_f32_16x16x32_bf16 v[126:129], v[148:151], v[180:183], v[126:129]
	v_mfma_f32_16x16x32_bf16 v[122:125], v[156:159], v[180:183], v[122:125]
	s_waitcnt lgkmcnt(5)
	v_mfma_f32_16x16x32_bf16 v[110:113], v[156:159], v[188:191], v[110:113]
	v_mfma_f32_16x16x32_bf16 v[118:121], v[148:151], v[188:191], v[118:121]
	s_waitcnt lgkmcnt(3)
	v_mfma_f32_16x16x32_bf16 v[102:105], v[148:151], v[196:199], v[102:105]
	v_mfma_f32_16x16x32_bf16 v[94:97], v[156:159], v[196:199], v[94:97]
	s_waitcnt lgkmcnt(1)
	v_mfma_f32_16x16x32_bf16 v[78:81], v[156:159], v[204:207], v[78:81]
	v_mfma_f32_16x16x32_bf16 v[86:89], v[148:151], v[204:207], v[86:89]
	v_mfma_f32_16x16x32_bf16 v[126:129], v[152:155], v[184:187], v[126:129]
	v_mfma_f32_16x16x32_bf16 v[122:125], v[160:163], v[184:187], v[122:125]
	v_mfma_f32_16x16x32_bf16 v[110:113], v[160:163], v[192:195], v[110:113]
	v_mfma_f32_16x16x32_bf16 v[118:121], v[152:155], v[192:195], v[118:121]
	v_mfma_f32_16x16x32_bf16 v[102:105], v[152:155], v[200:203], v[102:105]
	v_mfma_f32_16x16x32_bf16 v[94:97], v[160:163], v[200:203], v[94:97]
	s_waitcnt lgkmcnt(0)
	v_mfma_f32_16x16x32_bf16 v[78:81], v[160:163], v[208:211], v[78:81]
	v_mfma_f32_16x16x32_bf16 v[86:89], v[152:155], v[208:211], v[86:89]
	s_setprio 0
	s_setprio 1
	v_mfma_f32_16x16x32_bf16 v[114:117], v[164:167], v[180:183], v[114:117]
	v_mfma_f32_16x16x32_bf16 v[106:109], v[172:175], v[180:183], v[106:109]
	v_mfma_f32_16x16x32_bf16 v[90:93], v[172:175], v[188:191], v[90:93]
	v_mfma_f32_16x16x32_bf16 v[98:101], v[164:167], v[188:191], v[98:101]
	v_mfma_f32_16x16x32_bf16 v[82:85], v[164:167], v[196:199], v[82:85]
	v_mfma_f32_16x16x32_bf16 v[74:77], v[172:175], v[196:199], v[74:77]
	v_mfma_f32_16x16x32_bf16 v[66:69], v[172:175], v[204:207], v[66:69]
	v_mfma_f32_16x16x32_bf16 v[70:73], v[164:167], v[204:207], v[70:73]
	v_mfma_f32_16x16x32_bf16 v[114:117], v[168:171], v[184:187], v[114:117]
	v_mfma_f32_16x16x32_bf16 v[106:109], v[176:179], v[184:187], v[106:109]
	v_mfma_f32_16x16x32_bf16 v[90:93], v[176:179], v[192:195], v[90:93]
	v_mfma_f32_16x16x32_bf16 v[98:101], v[168:171], v[192:195], v[98:101]
	v_mfma_f32_16x16x32_bf16 v[82:85], v[168:171], v[200:203], v[82:85]
	v_mfma_f32_16x16x32_bf16 v[74:77], v[176:179], v[200:203], v[74:77]
	v_mfma_f32_16x16x32_bf16 v[66:69], v[176:179], v[208:211], v[66:69]
	v_mfma_f32_16x16x32_bf16 v[70:73], v[168:171], v[208:211], v[70:73]
	s_setprio 0
	s_barrier
	ds_read_b128 v[180:183], v144 offset:16384
	ds_read_b128 v[184:187], v144 offset:17408
	ds_read_b128 v[188:191], v144 offset:18432
	ds_read_b128 v[192:195], v144 offset:19456
	ds_read_b128 v[196:199], v144 offset:20480
	ds_read_b128 v[200:203], v144 offset:21504
	ds_read_b128 v[204:207], v144 offset:22528
	ds_read_b128 v[208:211], v144 offset:23552
	s_mov_b32 m0, s24
	s_nop 0
	global_load_lds_dwordx4 v139, s[68:69]
	s_add_u32 s84, s68, 0x200000
	s_mov_b32 m0, s25
	s_nop 0
	global_load_lds_dwordx4 v141, s[68:69]
	s_addc_u32 s85, s69, 0
	s_mov_b32 m0, s26
	s_nop 0
	global_load_lds_dwordx4 v139, s[84:85]
	s_nop 0
	s_mov_b32 m0, s27
	s_nop 0
	global_load_lds_dwordx4 v141, s[84:85]
	s_nop 0
	s_mov_b32 m0, s15
	s_nop 0
	global_load_lds_dwordx4 v138, s[70:71]
	s_nop 0
	s_mov_b32 m0, s28
	s_nop 0
	global_load_lds_dwordx4 v140, s[70:71]
	s_waitcnt vmcnt(8)
	s_waitcnt lgkmcnt(0)
	s_barrier
	s_setprio 1
	s_waitcnt lgkmcnt(7)
	v_mfma_f32_16x16x32_bf16 v[62:65], v[148:151], v[180:183], v[62:65]
	v_mfma_f32_16x16x32_bf16 v[58:61], v[156:159], v[180:183], v[58:61]
	s_waitcnt lgkmcnt(5)
	v_mfma_f32_16x16x32_bf16 v[46:49], v[156:159], v[188:191], v[46:49]
	v_mfma_f32_16x16x32_bf16 v[54:57], v[148:151], v[188:191], v[54:57]
	s_waitcnt lgkmcnt(3)
	v_mfma_f32_16x16x32_bf16 v[38:41], v[148:151], v[196:199], v[38:41]
	v_mfma_f32_16x16x32_bf16 v[30:33], v[156:159], v[196:199], v[30:33]
	s_waitcnt lgkmcnt(1)
	v_mfma_f32_16x16x32_bf16 v[14:17], v[156:159], v[204:207], v[14:17]
	v_mfma_f32_16x16x32_bf16 v[22:25], v[148:151], v[204:207], v[22:25]
	v_mfma_f32_16x16x32_bf16 v[62:65], v[152:155], v[184:187], v[62:65]
	v_mfma_f32_16x16x32_bf16 v[58:61], v[160:163], v[184:187], v[58:61]
	v_mfma_f32_16x16x32_bf16 v[46:49], v[160:163], v[192:195], v[46:49]
	v_mfma_f32_16x16x32_bf16 v[54:57], v[152:155], v[192:195], v[54:57]
	v_mfma_f32_16x16x32_bf16 v[38:41], v[152:155], v[200:203], v[38:41]
	v_mfma_f32_16x16x32_bf16 v[30:33], v[160:163], v[200:203], v[30:33]
	s_waitcnt lgkmcnt(0)
	v_mfma_f32_16x16x32_bf16 v[14:17], v[160:163], v[208:211], v[14:17]
	v_mfma_f32_16x16x32_bf16 v[22:25], v[152:155], v[208:211], v[22:25]
	s_setprio 0
	s_setprio 1
	v_mfma_f32_16x16x32_bf16 v[50:53], v[164:167], v[180:183], v[50:53]
	v_mfma_f32_16x16x32_bf16 v[42:45], v[172:175], v[180:183], v[42:45]
	v_mfma_f32_16x16x32_bf16 v[26:29], v[172:175], v[188:191], v[26:29]
	v_mfma_f32_16x16x32_bf16 v[34:37], v[164:167], v[188:191], v[34:37]
	v_mfma_f32_16x16x32_bf16 v[18:21], v[164:167], v[196:199], v[18:21]
	v_mfma_f32_16x16x32_bf16 v[10:13], v[172:175], v[196:199], v[10:13]
	v_mfma_f32_16x16x32_bf16 v[2:5], v[172:175], v[204:207], v[2:5]
	v_mfma_f32_16x16x32_bf16 v[6:9], v[164:167], v[204:207], v[6:9]
	v_mfma_f32_16x16x32_bf16 v[50:53], v[168:171], v[184:187], v[50:53]
	v_mfma_f32_16x16x32_bf16 v[42:45], v[176:179], v[184:187], v[42:45]
	v_mfma_f32_16x16x32_bf16 v[26:29], v[176:179], v[192:195], v[26:29]
	v_mfma_f32_16x16x32_bf16 v[34:37], v[168:171], v[192:195], v[34:37]
	v_mfma_f32_16x16x32_bf16 v[18:21], v[168:171], v[200:203], v[18:21]
	v_mfma_f32_16x16x32_bf16 v[10:13], v[176:179], v[200:203], v[10:13]
	v_mfma_f32_16x16x32_bf16 v[2:5], v[176:179], v[208:211], v[2:5]
	v_mfma_f32_16x16x32_bf16 v[6:9], v[168:171], v[208:211], v[6:9]
	s_setprio 0
	s_barrier
; #define PG8_STAGE(bufoff, gbase, voff) do { if constexpr (VAR != 1 && VAR != 3) { _Pragma("unroll") for (int _i = 0; _i < 2; ++_i) \
;         asm volatile("s_mov_b32 m0, %2\n\ts_nop 0\n\tglobal_load_lds_dwordx4 %0, %1" :: "v"((voff)[_i]), "s"((const char*)(gbase)), "s"(ldsbase + (unsigned)((bufoff) + _i * 8192)) : "memory", "m0"); } } while (0)
; #define PG8_LDA(dst, b, h) do { if constexpr (VAR < 2) _Pragma("unroll") for (int m = 0; m < 4; ++m) _Pragma("unroll") for (int k = 0; k < 2; ++k) dst[m][k] = *(const LAS bf16x8*)(lds + PG8_SA(b, h) + aoff + m * 2048 + k * 1024); } while (0)
; #define PG8_LDB(dst, b, h) do { if constexpr (VAR < 2) _Pragma("unroll") for (int n = 0; n < 2; ++n) _Pragma("unroll") for (int k = 0; k < 2; ++k) dst[n][k] = *(const LAS bf16x8*)(lds + PG8_SB(b, h) + boff + n * 2048 + k * 1024); } while (0)
; #define PG8_WAIT_V(n) asm volatile("s_waitcnt vmcnt(" #n ")" ::: "memory")
; #define PG8_WAIT_L(n) asm volatile("s_waitcnt lgkmcnt(" #n ")" ::: "memory")
; #define PG8_BAR do { if constexpr (VAR != 3) __builtin_amdgcn_s_barrier(); } while (0)
; #define PG8_SCHED __builtin_amdgcn_sched_barrier(0)
;     ...
;             PG8_LDB(B0, 1, 0); PG8_LDB(B1, 1, 1); PG8_SCHED; PG8_LDA(At, 1, 0); PG8_STAGE(PG8_SA(0, 1), a2 + hstepA, voffA);
;             PG8_WAIT_V(8); PG8_WAIT_L(0); PG8_BAR; PG8_MMA(0, 0, At, B0); PG8_MMA(0, 1, At, B1); PG8_BAR; PG8_SCHED;
;             PG8_LDA(At, 1, 1); PG8_STAGE(PG8_SB(1, 0), b3, voffB); PG8_STAGE(PG8_SB(1, 1), b3 + hstepB, voffB); PG8_STAGE(PG8_SA(1, 0), a3, voffA);
;             PG8_WAIT_V(8); PG8_WAIT_L(0); PG8_BAR; PG8_MMA(1, 0, At, B0); PG8_MMA(1, 1, At, B1); PG8_BAR; PG8_SCHED;
;         }
;         if (wr == 0) PG8_BAR;
	ds_read_b128 v[148:151], v145
	ds_read_b128 v[152:155], v145 offset:1024
	ds_read_b128 v[156:159], v145 offset:2048
	ds_read_b128 v[160:163], v145 offset:3072
	ds_read_b128 v[164:167], v146
	ds_read_b128 v[168:171], v146 offset:1024
	ds_read_b128 v[172:175], v146 offset:2048
	ds_read_b128 v[176:179], v146 offset:3072
	ds_read_b128 v[180:183], v144 offset:32768
	ds_read_b128 v[184:187], v144 offset:33792
	ds_read_b128 v[188:191], v144 offset:34816
	ds_read_b128 v[192:195], v144 offset:35840
	ds_read_b128 v[196:199], v144 offset:36864
	ds_read_b128 v[200:203], v144 offset:37888
	ds_read_b128 v[204:207], v144 offset:38912
	ds_read_b128 v[208:211], v144 offset:39936
	s_add_u32 s70, s70, 0x100000
	s_addc_u32 s71, s71, 0
	s_mov_b32 m0, s29
	s_nop 0
	global_load_lds_dwordx4 v138, s[70:71]
	s_nop 0
	s_mov_b32 m0, s30
	s_nop 0
	global_load_lds_dwordx4 v140, s[70:71]
	s_waitcnt vmcnt(8)
	s_waitcnt lgkmcnt(0)
	s_barrier
	s_setprio 1
	s_waitcnt lgkmcnt(7)
	v_mfma_f32_16x16x32_bf16 v[126:129], v[148:151], v[180:183], v[126:129]
	v_mfma_f32_16x16x32_bf16 v[122:125], v[156:159], v[180:183], v[122:125]
	s_waitcnt lgkmcnt(5)
	v_mfma_f32_16x16x32_bf16 v[110:113], v[156:159], v[188:191], v[110:113]
	v_mfma_f32_16x16x32_bf16 v[118:121], v[148:151], v[188:191], v[118:121]
	s_waitcnt lgkmcnt(3)
	v_mfma_f32_16x16x32_bf16 v[102:105], v[148:151], v[196:199], v[102:105]
	v_mfma_f32_16x16x32_bf16 v[94:97], v[156:159], v[196:199], v[94:97]
	s_waitcnt lgkmcnt(1)
	v_mfma_f32_16x16x32_bf16 v[78:81], v[156:159], v[204:207], v[78:81]
	v_mfma_f32_16x16x32_bf16 v[86:89], v[148:151], v[204:207], v[86:89]
	v_mfma_f32_16x16x32_bf16 v[126:129], v[152:155], v[184:187], v[126:129]
	v_mfma_f32_16x16x32_bf16 v[122:125], v[160:163], v[184:187], v[122:125]
	v_mfma_f32_16x16x32_bf16 v[110:113], v[160:163], v[192:195], v[110:113]
	v_mfma_f32_16x16x32_bf16 v[118:121], v[152:155], v[192:195], v[118:121]
	v_mfma_f32_16x16x32_bf16 v[102:105], v[152:155], v[200:203], v[102:105]
	v_mfma_f32_16x16x32_bf16 v[94:97], v[160:163], v[200:203], v[94:97]
	s_waitcnt lgkmcnt(0)
	v_mfma_f32_16x16x32_bf16 v[78:81], v[160:163], v[208:211], v[78:81]
	v_mfma_f32_16x16x32_bf16 v[86:89], v[152:155], v[208:211], v[86:89]
	s_setprio 0
	s_setprio 1
	v_mfma_f32_16x16x32_bf16 v[114:117], v[164:167], v[180:183], v[114:117]
	v_mfma_f32_16x16x32_bf16 v[106:109], v[172:175], v[180:183], v[106:109]
	v_mfma_f32_16x16x32_bf16 v[90:93], v[172:175], v[188:191], v[90:93]
	v_mfma_f32_16x16x32_bf16 v[98:101], v[164:167], v[188:191], v[98:101]
	v_mfma_f32_16x16x32_bf16 v[82:85], v[164:167], v[196:199], v[82:85]
	v_mfma_f32_16x16x32_bf16 v[74:77], v[172:175], v[196:199], v[74:77]
	v_mfma_f32_16x16x32_bf16 v[66:69], v[172:175], v[204:207], v[66:69]
	v_mfma_f32_16x16x32_bf16 v[70:73], v[164:167], v[204:207], v[70:73]
	v_mfma_f32_16x16x32_bf16 v[114:117], v[168:171], v[184:187], v[114:117]
	v_mfma_f32_16x16x32_bf16 v[106:109], v[176:179], v[184:187], v[106:109]
	v_mfma_f32_16x16x32_bf16 v[90:93], v[176:179], v[192:195], v[90:93]
	v_mfma_f32_16x16x32_bf16 v[98:101], v[168:171], v[192:195], v[98:101]
	v_mfma_f32_16x16x32_bf16 v[82:85], v[168:171], v[200:203], v[82:85]
	v_mfma_f32_16x16x32_bf16 v[74:77], v[176:179], v[200:203], v[74:77]
	v_mfma_f32_16x16x32_bf16 v[66:69], v[176:179], v[208:211], v[66:69]
	v_mfma_f32_16x16x32_bf16 v[70:73], v[168:171], v[208:211], v[70:73]
	s_setprio 0
	s_barrier
	ds_read_b128 v[180:183], v144 offset:49152
	ds_read_b128 v[184:187], v144 offset:50176
	ds_read_b128 v[188:191], v144 offset:51200
	ds_read_b128 v[192:195], v144 offset:52224
	ds_read_b128 v[196:199], v144 offset:53248
	ds_read_b128 v[200:203], v144 offset:54272
	ds_read_b128 v[204:207], v144 offset:55296
	ds_read_b128 v[208:211], v144 offset:56320
	s_add_u32 s70, s68, 0x80
	s_addc_u32 s71, s69, 0
	s_mov_b32 m0, s31
	s_nop 0
	global_load_lds_dwordx4 v139, s[70:71]
	s_add_u32 s68, s68, 0x200080
	s_mov_b32 m0, s33
	s_nop 0
	global_load_lds_dwordx4 v141, s[70:71]
	s_addc_u32 s69, s69, 0
	s_mov_b32 m0, s74
	s_nop 0
	global_load_lds_dwordx4 v139, s[68:69]
	s_nop 0
	s_mov_b32 m0, s75
	s_nop 0
	global_load_lds_dwordx4 v141, s[68:69]
	s_nop 0
	s_mov_b32 m0, s72
	s_nop 0
	global_load_lds_dwordx4 v138, s[66:67]
	s_nop 0
	s_mov_b32 m0, s73
	s_nop 0
	global_load_lds_dwordx4 v140, s[66:67]
	s_waitcnt vmcnt(8)
	s_waitcnt lgkmcnt(0)
	s_barrier
	s_setprio 1
	s_waitcnt lgkmcnt(7)
	v_mfma_f32_16x16x32_bf16 v[62:65], v[148:151], v[180:183], v[62:65]
	v_mfma_f32_16x16x32_bf16 v[58:61], v[156:159], v[180:183], v[58:61]
	s_waitcnt lgkmcnt(5)
	v_mfma_f32_16x16x32_bf16 v[46:49], v[156:159], v[188:191], v[46:49]
	v_mfma_f32_16x16x32_bf16 v[54:57], v[148:151], v[188:191], v[54:57]
	s_waitcnt lgkmcnt(3)
	v_mfma_f32_16x16x32_bf16 v[38:41], v[148:151], v[196:199], v[38:41]
	v_mfma_f32_16x16x32_bf16 v[30:33], v[156:159], v[196:199], v[30:33]
	s_waitcnt lgkmcnt(1)
	v_mfma_f32_16x16x32_bf16 v[14:17], v[156:159], v[204:207], v[14:17]
	v_mfma_f32_16x16x32_bf16 v[22:25], v[148:151], v[204:207], v[22:25]
	v_mfma_f32_16x16x32_bf16 v[62:65], v[152:155], v[184:187], v[62:65]
	v_mfma_f32_16x16x32_bf16 v[58:61], v[160:163], v[184:187], v[58:61]
	v_mfma_f32_16x16x32_bf16 v[46:49], v[160:163], v[192:195], v[46:49]
	v_mfma_f32_16x16x32_bf16 v[54:57], v[152:155], v[192:195], v[54:57]
	v_mfma_f32_16x16x32_bf16 v[38:41], v[152:155], v[200:203], v[38:41]
	v_mfma_f32_16x16x32_bf16 v[30:33], v[160:163], v[200:203], v[30:33]
	s_waitcnt lgkmcnt(0)
	v_mfma_f32_16x16x32_bf16 v[14:17], v[160:163], v[208:211], v[14:17]
	v_mfma_f32_16x16x32_bf16 v[22:25], v[152:155], v[208:211], v[22:25]
	s_setprio 0
	s_setprio 1
	v_mfma_f32_16x16x32_bf16 v[50:53], v[164:167], v[180:183], v[50:53]
	v_mfma_f32_16x16x32_bf16 v[42:45], v[172:175], v[180:183], v[42:45]
	v_mfma_f32_16x16x32_bf16 v[26:29], v[172:175], v[188:191], v[26:29]
	v_mfma_f32_16x16x32_bf16 v[34:37], v[164:167], v[188:191], v[34:37]
	v_mfma_f32_16x16x32_bf16 v[18:21], v[164:167], v[196:199], v[18:21]
	v_mfma_f32_16x16x32_bf16 v[10:13], v[172:175], v[196:199], v[10:13]
	v_mfma_f32_16x16x32_bf16 v[2:5], v[172:175], v[204:207], v[2:5]
	v_mfma_f32_16x16x32_bf16 v[6:9], v[164:167], v[204:207], v[6:9]
	v_mfma_f32_16x16x32_bf16 v[50:53], v[168:171], v[184:187], v[50:53]
	v_mfma_f32_16x16x32_bf16 v[42:45], v[176:179], v[184:187], v[42:45]
	v_mfma_f32_16x16x32_bf16 v[26:29], v[176:179], v[192:195], v[26:29]
	v_mfma_f32_16x16x32_bf16 v[34:37], v[168:171], v[192:195], v[34:37]
	v_mfma_f32_16x16x32_bf16 v[18:21], v[168:171], v[200:203], v[18:21]
	v_mfma_f32_16x16x32_bf16 v[10:13], v[176:179], v[200:203], v[10:13]
	v_mfma_f32_16x16x32_bf16 v[2:5], v[176:179], v[208:211], v[2:5]
	v_mfma_f32_16x16x32_bf16 v[6:9], v[168:171], v[208:211], v[6:9]
	s_setprio 0
	s_barrier
	s_add_i32 s6, s6, 2
	s_add_u32 s57, s57, 0x100
	s_addc_u32 s81, s81, 0
	s_add_u32 s82, s82, 0x100
	s_addc_u32 s83, s83, 0
	s_add_u32 s64, s64, 0x100
	s_addc_u32 s65, s65, 0
	s_cmp_gt_u32 s6, 13
	s_cbranch_scc0 .LBB0_701
	s_and_b64 vcc, exec, s[8:9]
	s_cbranch_vccz .LBB0_704
	s_barrier

; #define PG8_STAGE(bufoff, gbase, voff) do { if constexpr (VAR != 1 && VAR != 3) { _Pragma("unroll") for (int _i = 0; _i < 2; ++_i) \
;         asm volatile("s_mov_b32 m0, %2\n\ts_nop 0\n\tglobal_load_lds_dwordx4 %0, %1" :: "v"((voff)[_i]), "s"((const char*)(gbase)), "s"(ldsbase + (unsigned)((bufoff) + _i * 8192)) : "memory", "m0"); } } while (0)
; #define PG8_LDA(dst, b, h) do { if constexpr (VAR < 2) _Pragma("unroll") for (int m = 0; m < 4; ++m) _Pragma("unroll") for (int k = 0; k < 2; ++k) dst[m][k] = *(const LAS bf16x8*)(lds + PG8_SA(b, h) + aoff + m * 2048 + k * 1024); } while (0)
; #define PG8_LDB(dst, b, h) do { if constexpr (VAR < 2) _Pragma("unroll") for (int n = 0; n < 2; ++n) _Pragma("unroll") for (int k = 0; k < 2; ++k) dst[n][k] = *(const LAS bf16x8*)(lds + PG8_SB(b, h) + boff + n * 2048 + k * 1024); } while (0)
; #define PG8_WAIT_V(n) asm volatile("s_waitcnt vmcnt(" #n ")" ::: "memory")
; #define PG8_WAIT_L(n) asm volatile("s_waitcnt lgkmcnt(" #n ")" ::: "memory")
; #define PG8_BAR do { if constexpr (VAR != 3) __builtin_amdgcn_s_barrier(); } while (0)
; #define PG8_SCHED __builtin_amdgcn_sched_barrier(0)
;     ...
;             PG8_LDB(B0, 0, 0); PG8_LDB(B1, 0, 1); PG8_SCHED; PG8_LDA(At, 0, 0); PG8_STAGE(PG8_SA(1, 1), a1 + hstepA, voffA);
;             PG8_WAIT_V(8); PG8_WAIT_L(0); PG8_BAR; PG8_MMA(0, 0, At, B0); PG8_MMA(0, 1, At, B1); PG8_BAR; PG8_SCHED;
;             PG8_LDA(At, 0, 1); PG8_STAGE(PG8_SB(0, 0), b2, voffB); PG8_STAGE(PG8_SB(0, 1), b2 + hstepB, voffB); PG8_STAGE(PG8_SA(0, 0), a2, voffA);
;             PG8_WAIT_V(8); PG8_WAIT_L(0); PG8_BAR; PG8_MMA(1, 0, At, B0); PG8_MMA(1, 1, At, B1); PG8_BAR; PG8_SCHED;
.LBB0_789:
	ds_read_b128 v[98:101], v191
	ds_read_b128 v[110:113], v191 offset:1024
	ds_read_b128 v[122:125], v191 offset:2048
	ds_read_b128 v[134:137], v191 offset:3072
	ds_read_b128 v[138:141], v192
	ds_read_b128 v[150:153], v192 offset:1024
	ds_read_b128 v[154:157], v192 offset:2048
	ds_read_b128 v[162:165], v192 offset:3072
	s_cmp_eq_u32 vcc_hi, 60
	s_cselect_b32 s86, s15, s27
	s_cselect_b32 s87, s14, s71
	s_cselect_b32 s84, s26, s73
	s_cselect_b32 s85, s25, vcc_lo
	s_add_u32 s82, s86, 0x80
	s_addc_u32 s83, s87, 0
	ds_read_b128 v[166:169], v193
	ds_read_b128 v[170:173], v193 offset:1024
	ds_read_b128 v[174:177], v193 offset:2048
	ds_read_b128 v[178:181], v193 offset:3072
	ds_read_b128 v[198:201], v193 offset:4096
	ds_read_b128 v[202:205], v193 offset:5120
	ds_read_b128 v[206:209], v193 offset:6144
	ds_read_b128 v[210:213], v193 offset:7168
	s_mov_b32 m0, s31
	s_nop 0
	global_load_lds_dwordx4 v184, s[80:81]
	s_nop 0
	s_mov_b32 m0, s19
	s_nop 0
	global_load_lds_dwordx4 v186, s[80:81]
	s_waitcnt vmcnt(8)
	s_waitcnt lgkmcnt(0)
	s_barrier
	s_setprio 1
	s_waitcnt lgkmcnt(7)
	v_mfma_f32_16x16x32_bf16 v[146:149], v[98:101], v[166:169], v[146:149]
	v_mfma_f32_16x16x32_bf16 v[142:145], v[122:125], v[166:169], v[142:145]
	s_waitcnt lgkmcnt(5)
	v_mfma_f32_16x16x32_bf16 v[114:117], v[122:125], v[174:177], v[114:117]
	v_mfma_f32_16x16x32_bf16 v[118:121], v[98:101], v[174:177], v[118:121]
	s_waitcnt lgkmcnt(3)
	v_mfma_f32_16x16x32_bf16 v[94:97], v[98:101], v[198:201], v[94:97]
	v_mfma_f32_16x16x32_bf16 v[90:93], v[122:125], v[198:201], v[90:93]
	s_waitcnt lgkmcnt(1)
	v_mfma_f32_16x16x32_bf16 v[74:77], v[122:125], v[206:209], v[74:77]
	v_mfma_f32_16x16x32_bf16 v[78:81], v[98:101], v[206:209], v[78:81]
	v_mfma_f32_16x16x32_bf16 v[146:149], v[110:113], v[170:173], v[146:149]
	v_mfma_f32_16x16x32_bf16 v[142:145], v[134:137], v[170:173], v[142:145]
	v_mfma_f32_16x16x32_bf16 v[114:117], v[134:137], v[178:181], v[114:117]
	v_mfma_f32_16x16x32_bf16 v[118:121], v[110:113], v[178:181], v[118:121]
	v_mfma_f32_16x16x32_bf16 v[94:97], v[110:113], v[202:205], v[94:97]
	v_mfma_f32_16x16x32_bf16 v[90:93], v[134:137], v[202:205], v[90:93]
	s_waitcnt lgkmcnt(0)
	v_mfma_f32_16x16x32_bf16 v[74:77], v[134:137], v[210:213], v[74:77]
	v_mfma_f32_16x16x32_bf16 v[78:81], v[110:113], v[210:213], v[78:81]
	s_setprio 0
	s_setprio 1
	v_mfma_f32_16x16x32_bf16 v[130:133], v[138:141], v[166:169], v[130:133]
	v_mfma_f32_16x16x32_bf16 v[126:129], v[154:157], v[166:169], v[126:129]
	v_mfma_f32_16x16x32_bf16 v[102:105], v[154:157], v[174:177], v[102:105]
	v_mfma_f32_16x16x32_bf16 v[106:109], v[138:141], v[174:177], v[106:109]
	v_mfma_f32_16x16x32_bf16 v[86:89], v[138:141], v[198:201], v[86:89]
	v_mfma_f32_16x16x32_bf16 v[82:85], v[154:157], v[198:201], v[82:85]
	v_mfma_f32_16x16x32_bf16 v[66:69], v[154:157], v[206:209], v[66:69]
	v_mfma_f32_16x16x32_bf16 v[70:73], v[138:141], v[206:209], v[70:73]
	v_mfma_f32_16x16x32_bf16 v[130:133], v[150:153], v[170:173], v[130:133]
	v_mfma_f32_16x16x32_bf16 v[126:129], v[162:165], v[170:173], v[126:129]
	v_mfma_f32_16x16x32_bf16 v[102:105], v[162:165], v[178:181], v[102:105]
	v_mfma_f32_16x16x32_bf16 v[106:109], v[150:153], v[178:181], v[106:109]
	v_mfma_f32_16x16x32_bf16 v[86:89], v[150:153], v[202:205], v[86:89]
	v_mfma_f32_16x16x32_bf16 v[82:85], v[162:165], v[202:205], v[82:85]
	v_mfma_f32_16x16x32_bf16 v[66:69], v[162:165], v[210:213], v[66:69]
	v_mfma_f32_16x16x32_bf16 v[70:73], v[150:153], v[210:213], v[70:73]
	s_setprio 0
	s_barrier
	ds_read_b128 v[166:169], v193 offset:16384
	ds_read_b128 v[170:173], v193 offset:17408
	ds_read_b128 v[174:177], v193 offset:18432
	ds_read_b128 v[178:181], v193 offset:19456
	ds_read_b128 v[198:201], v193 offset:20480
	ds_read_b128 v[202:205], v193 offset:21504
	ds_read_b128 v[206:209], v193 offset:22528
	ds_read_b128 v[210:213], v193 offset:23552
	s_mov_b32 m0, s91
	s_nop 0
	global_load_lds_dwordx4 v185, s[84:85]
	s_add_u32 s88, s84, 0x100000
	s_mov_b32 m0, s92
	s_nop 0
	global_load_lds_dwordx4 v187, s[84:85]
	s_addc_u32 s89, s85, 0
	s_mov_b32 m0, s93
	s_nop 0
	global_load_lds_dwordx4 v185, s[88:89]
	s_nop 0
	s_mov_b32 m0, s94
	s_nop 0
	global_load_lds_dwordx4 v187, s[88:89]
	s_nop 0
	s_mov_b32 m0, s35
	s_nop 0
	global_load_lds_dwordx4 v184, s[86:87]
	s_nop 0
	s_mov_b32 m0, s79
	s_nop 0
	global_load_lds_dwordx4 v186, s[86:87]
	s_waitcnt vmcnt(8)
	s_waitcnt lgkmcnt(0)
	s_barrier
	s_setprio 1
	s_waitcnt lgkmcnt(7)
	v_mfma_f32_16x16x32_bf16 v[62:65], v[98:101], v[166:169], v[62:65]
	v_mfma_f32_16x16x32_bf16 v[58:61], v[122:125], v[166:169], v[58:61]
	s_waitcnt lgkmcnt(5)
	v_mfma_f32_16x16x32_bf16 v[42:45], v[122:125], v[174:177], v[42:45]
	v_mfma_f32_16x16x32_bf16 v[46:49], v[98:101], v[174:177], v[46:49]
	s_waitcnt lgkmcnt(3)
	v_mfma_f32_16x16x32_bf16 v[30:33], v[98:101], v[198:201], v[30:33]
	v_mfma_f32_16x16x32_bf16 v[26:29], v[122:125], v[198:201], v[26:29]
	s_waitcnt lgkmcnt(1)
	v_mfma_f32_16x16x32_bf16 v[10:13], v[122:125], v[206:209], v[10:13]
	v_mfma_f32_16x16x32_bf16 v[14:17], v[98:101], v[206:209], v[14:17]
	v_mfma_f32_16x16x32_bf16 v[62:65], v[110:113], v[170:173], v[62:65]
	v_mfma_f32_16x16x32_bf16 v[58:61], v[134:137], v[170:173], v[58:61]
	v_mfma_f32_16x16x32_bf16 v[42:45], v[134:137], v[178:181], v[42:45]
	v_mfma_f32_16x16x32_bf16 v[46:49], v[110:113], v[178:181], v[46:49]
	v_mfma_f32_16x16x32_bf16 v[30:33], v[110:113], v[202:205], v[30:33]
	v_mfma_f32_16x16x32_bf16 v[26:29], v[134:137], v[202:205], v[26:29]
	s_waitcnt lgkmcnt(0)
	v_mfma_f32_16x16x32_bf16 v[10:13], v[134:137], v[210:213], v[10:13]
	v_mfma_f32_16x16x32_bf16 v[14:17], v[110:113], v[210:213], v[14:17]
	s_setprio 0
	s_setprio 1
	v_mfma_f32_16x16x32_bf16 v[54:57], v[138:141], v[166:169], v[54:57]
	v_mfma_f32_16x16x32_bf16 v[50:53], v[154:157], v[166:169], v[50:53]
	v_mfma_f32_16x16x32_bf16 v[34:37], v[154:157], v[174:177], v[34:37]
	v_mfma_f32_16x16x32_bf16 v[38:41], v[138:141], v[174:177], v[38:41]
	v_mfma_f32_16x16x32_bf16 v[22:25], v[138:141], v[198:201], v[22:25]
	v_mfma_f32_16x16x32_bf16 v[18:21], v[154:157], v[198:201], v[18:21]
	v_mfma_f32_16x16x32_bf16 v[2:5], v[154:157], v[206:209], v[2:5]
	v_mfma_f32_16x16x32_bf16 v[6:9], v[138:141], v[206:209], v[6:9]
	v_mfma_f32_16x16x32_bf16 v[54:57], v[150:153], v[170:173], v[54:57]
	v_mfma_f32_16x16x32_bf16 v[50:53], v[162:165], v[170:173], v[50:53]
	v_mfma_f32_16x16x32_bf16 v[34:37], v[162:165], v[178:181], v[34:37]
	v_mfma_f32_16x16x32_bf16 v[38:41], v[150:153], v[178:181], v[38:41]
	v_mfma_f32_16x16x32_bf16 v[22:25], v[150:153], v[202:205], v[22:25]
	v_mfma_f32_16x16x32_bf16 v[18:21], v[162:165], v[202:205], v[18:21]
	v_mfma_f32_16x16x32_bf16 v[2:5], v[162:165], v[210:213], v[2:5]
	v_mfma_f32_16x16x32_bf16 v[6:9], v[150:153], v[210:213], v[6:9]
	s_setprio 0
	s_barrier
; #define PG8_STAGE(bufoff, gbase, voff) do { if constexpr (VAR != 1 && VAR != 3) { _Pragma("unroll") for (int _i = 0; _i < 2; ++_i) \
;         asm volatile("s_mov_b32 m0, %2\n\ts_nop 0\n\tglobal_load_lds_dwordx4 %0, %1" :: "v"((voff)[_i]), "s"((const char*)(gbase)), "s"(ldsbase + (unsigned)((bufoff) + _i * 8192)) : "memory", "m0"); } } while (0)
; #define PG8_LDA(dst, b, h) do { if constexpr (VAR < 2) _Pragma("unroll") for (int m = 0; m < 4; ++m) _Pragma("unroll") for (int k = 0; k < 2; ++k) dst[m][k] = *(const LAS bf16x8*)(lds + PG8_SA(b, h) + aoff + m * 2048 + k * 1024); } while (0)
; #define PG8_LDB(dst, b, h) do { if constexpr (VAR < 2) _Pragma("unroll") for (int n = 0; n < 2; ++n) _Pragma("unroll") for (int k = 0; k < 2; ++k) dst[n][k] = *(const LAS bf16x8*)(lds + PG8_SB(b, h) + boff + n * 2048 + k * 1024); } while (0)
; #define PG8_WAIT_V(n) asm volatile("s_waitcnt vmcnt(" #n ")" ::: "memory")
; #define PG8_WAIT_L(n) asm volatile("s_waitcnt lgkmcnt(" #n ")" ::: "memory")
; #define PG8_BAR do { if constexpr (VAR != 3) __builtin_amdgcn_s_barrier(); } while (0)
; #define PG8_SCHED __builtin_amdgcn_sched_barrier(0)
;     ...
;             PG8_LDB(B0, 1, 0); PG8_LDB(B1, 1, 1); PG8_SCHED; PG8_LDA(At, 1, 0); PG8_STAGE(PG8_SA(0, 1), a2 + hstepA, voffA);
;             PG8_WAIT_V(8); PG8_WAIT_L(0); PG8_BAR; PG8_MMA(0, 0, At, B0); PG8_MMA(0, 1, At, B1); PG8_BAR; PG8_SCHED;
;             PG8_LDA(At, 1, 1); PG8_STAGE(PG8_SB(1, 0), b3, voffB); PG8_STAGE(PG8_SB(1, 1), b3 + hstepB, voffB); PG8_STAGE(PG8_SA(1, 0), a3, voffA);
;             PG8_WAIT_V(8); PG8_WAIT_L(0); PG8_BAR; PG8_MMA(1, 0, At, B0); PG8_MMA(1, 1, At, B1); PG8_BAR; PG8_SCHED;
;         }
;         if (wr == 0) PG8_BAR;
	ds_read_b128 v[98:101], v194
	ds_read_b128 v[110:113], v194 offset:1024
	ds_read_b128 v[122:125], v194 offset:2048
	ds_read_b128 v[134:137], v194 offset:3072
	ds_read_b128 v[138:141], v195
	ds_read_b128 v[150:153], v195 offset:1024
	ds_read_b128 v[154:157], v195 offset:2048
	ds_read_b128 v[162:165], v195 offset:3072
	ds_read_b128 v[166:169], v193 offset:32768
	ds_read_b128 v[170:173], v193 offset:33792
	ds_read_b128 v[174:177], v193 offset:34816
	ds_read_b128 v[178:181], v193 offset:35840
	ds_read_b128 v[198:201], v193 offset:36864
	ds_read_b128 v[202:205], v193 offset:37888
	ds_read_b128 v[206:209], v193 offset:38912
	ds_read_b128 v[210:213], v193 offset:39936
	s_add_u32 s86, s86, 0x100000
	s_addc_u32 s87, s87, 0
	s_mov_b32 m0, s95
	s_nop 0
	global_load_lds_dwordx4 v184, s[86:87]
	s_nop 0
	s_mov_b32 m0, s96
	s_nop 0
	global_load_lds_dwordx4 v186, s[86:87]
	s_waitcnt vmcnt(8)
	s_waitcnt lgkmcnt(0)
	s_barrier
	s_setprio 1
	s_waitcnt lgkmcnt(7)
	v_mfma_f32_16x16x32_bf16 v[146:149], v[98:101], v[166:169], v[146:149]
	v_mfma_f32_16x16x32_bf16 v[142:145], v[122:125], v[166:169], v[142:145]
	s_waitcnt lgkmcnt(5)
	v_mfma_f32_16x16x32_bf16 v[114:117], v[122:125], v[174:177], v[114:117]
	v_mfma_f32_16x16x32_bf16 v[118:121], v[98:101], v[174:177], v[118:121]
	s_waitcnt lgkmcnt(3)
	v_mfma_f32_16x16x32_bf16 v[94:97], v[98:101], v[198:201], v[94:97]
	v_mfma_f32_16x16x32_bf16 v[90:93], v[122:125], v[198:201], v[90:93]
	s_waitcnt lgkmcnt(1)
	v_mfma_f32_16x16x32_bf16 v[74:77], v[122:125], v[206:209], v[74:77]
	v_mfma_f32_16x16x32_bf16 v[78:81], v[98:101], v[206:209], v[78:81]
	v_mfma_f32_16x16x32_bf16 v[146:149], v[110:113], v[170:173], v[146:149]
	v_mfma_f32_16x16x32_bf16 v[142:145], v[134:137], v[170:173], v[142:145]
	v_mfma_f32_16x16x32_bf16 v[114:117], v[134:137], v[178:181], v[114:117]
	v_mfma_f32_16x16x32_bf16 v[118:121], v[110:113], v[178:181], v[118:121]
	v_mfma_f32_16x16x32_bf16 v[94:97], v[110:113], v[202:205], v[94:97]
	v_mfma_f32_16x16x32_bf16 v[90:93], v[134:137], v[202:205], v[90:93]
	s_waitcnt lgkmcnt(0)
	v_mfma_f32_16x16x32_bf16 v[74:77], v[134:137], v[210:213], v[74:77]
	v_mfma_f32_16x16x32_bf16 v[78:81], v[110:113], v[210:213], v[78:81]
	s_setprio 0
	s_setprio 1
	v_mfma_f32_16x16x32_bf16 v[130:133], v[138:141], v[166:169], v[130:133]
	v_mfma_f32_16x16x32_bf16 v[126:129], v[154:157], v[166:169], v[126:129]
	v_mfma_f32_16x16x32_bf16 v[102:105], v[154:157], v[174:177], v[102:105]
	v_mfma_f32_16x16x32_bf16 v[106:109], v[138:141], v[174:177], v[106:109]
	v_mfma_f32_16x16x32_bf16 v[86:89], v[138:141], v[198:201], v[86:89]
	v_mfma_f32_16x16x32_bf16 v[82:85], v[154:157], v[198:201], v[82:85]
	v_mfma_f32_16x16x32_bf16 v[66:69], v[154:157], v[206:209], v[66:69]
	v_mfma_f32_16x16x32_bf16 v[70:73], v[138:141], v[206:209], v[70:73]
	v_mfma_f32_16x16x32_bf16 v[130:133], v[150:153], v[170:173], v[130:133]
	v_mfma_f32_16x16x32_bf16 v[126:129], v[162:165], v[170:173], v[126:129]
	v_mfma_f32_16x16x32_bf16 v[102:105], v[162:165], v[178:181], v[102:105]
	v_mfma_f32_16x16x32_bf16 v[106:109], v[150:153], v[178:181], v[106:109]
	v_mfma_f32_16x16x32_bf16 v[86:89], v[150:153], v[202:205], v[86:89]
	v_mfma_f32_16x16x32_bf16 v[82:85], v[162:165], v[202:205], v[82:85]
	v_mfma_f32_16x16x32_bf16 v[66:69], v[162:165], v[210:213], v[66:69]
	v_mfma_f32_16x16x32_bf16 v[70:73], v[150:153], v[210:213], v[70:73]
	s_setprio 0
	s_barrier
	ds_read_b128 v[166:169], v193 offset:49152
	ds_read_b128 v[170:173], v193 offset:50176
	ds_read_b128 v[174:177], v193 offset:51200
	ds_read_b128 v[178:181], v193 offset:52224
	ds_read_b128 v[198:201], v193 offset:53248
	ds_read_b128 v[202:205], v193 offset:54272
	ds_read_b128 v[206:209], v193 offset:55296
	ds_read_b128 v[210:213], v193 offset:56320
	s_add_u32 s86, s84, 0x80
	s_addc_u32 s87, s85, 0
	s_mov_b32 m0, s64
	s_nop 0
	global_load_lds_dwordx4 v185, s[86:87]
	s_add_u32 s84, s84, 0x100080
	s_mov_b32 m0, s65
	s_nop 0
	global_load_lds_dwordx4 v187, s[86:87]
	s_addc_u32 s85, s85, 0
	s_mov_b32 m0, s33
	s_nop 0
	global_load_lds_dwordx4 v185, s[84:85]
	s_nop 0
	s_mov_b32 m0, s30
	s_nop 0
	global_load_lds_dwordx4 v187, s[84:85]
	s_nop 0
	s_mov_b32 m0, s17
	s_nop 0
	global_load_lds_dwordx4 v184, s[82:83]
	s_nop 0
	s_mov_b32 m0, s28
	s_nop 0
	global_load_lds_dwordx4 v186, s[82:83]
	s_waitcnt vmcnt(8)
	s_waitcnt lgkmcnt(0)
	s_barrier
	s_setprio 1
	s_waitcnt lgkmcnt(7)
	v_mfma_f32_16x16x32_bf16 v[62:65], v[98:101], v[166:169], v[62:65]
	v_mfma_f32_16x16x32_bf16 v[58:61], v[122:125], v[166:169], v[58:61]
	s_waitcnt lgkmcnt(5)
	v_mfma_f32_16x16x32_bf16 v[42:45], v[122:125], v[174:177], v[42:45]
	v_mfma_f32_16x16x32_bf16 v[46:49], v[98:101], v[174:177], v[46:49]
	s_waitcnt lgkmcnt(3)
	v_mfma_f32_16x16x32_bf16 v[30:33], v[98:101], v[198:201], v[30:33]
	v_mfma_f32_16x16x32_bf16 v[26:29], v[122:125], v[198:201], v[26:29]
	s_waitcnt lgkmcnt(1)
	v_mfma_f32_16x16x32_bf16 v[10:13], v[122:125], v[206:209], v[10:13]
	v_mfma_f32_16x16x32_bf16 v[14:17], v[98:101], v[206:209], v[14:17]
	v_mfma_f32_16x16x32_bf16 v[62:65], v[110:113], v[170:173], v[62:65]
	v_mfma_f32_16x16x32_bf16 v[58:61], v[134:137], v[170:173], v[58:61]
	v_mfma_f32_16x16x32_bf16 v[42:45], v[134:137], v[178:181], v[42:45]
	v_mfma_f32_16x16x32_bf16 v[46:49], v[110:113], v[178:181], v[46:49]
	v_mfma_f32_16x16x32_bf16 v[30:33], v[110:113], v[202:205], v[30:33]
	v_mfma_f32_16x16x32_bf16 v[26:29], v[134:137], v[202:205], v[26:29]
	s_waitcnt lgkmcnt(0)
	v_mfma_f32_16x16x32_bf16 v[10:13], v[134:137], v[210:213], v[10:13]
	v_mfma_f32_16x16x32_bf16 v[14:17], v[110:113], v[210:213], v[14:17]
	s_setprio 0
	s_setprio 1
	v_mfma_f32_16x16x32_bf16 v[54:57], v[138:141], v[166:169], v[54:57]
	v_mfma_f32_16x16x32_bf16 v[50:53], v[154:157], v[166:169], v[50:53]
	v_mfma_f32_16x16x32_bf16 v[34:37], v[154:157], v[174:177], v[34:37]
	v_mfma_f32_16x16x32_bf16 v[38:41], v[138:141], v[174:177], v[38:41]
	v_mfma_f32_16x16x32_bf16 v[22:25], v[138:141], v[198:201], v[22:25]
	v_mfma_f32_16x16x32_bf16 v[18:21], v[154:157], v[198:201], v[18:21]
	v_mfma_f32_16x16x32_bf16 v[2:5], v[154:157], v[206:209], v[2:5]
	v_mfma_f32_16x16x32_bf16 v[6:9], v[138:141], v[206:209], v[6:9]
	v_mfma_f32_16x16x32_bf16 v[54:57], v[150:153], v[170:173], v[54:57]
	v_mfma_f32_16x16x32_bf16 v[50:53], v[162:165], v[170:173], v[50:53]
	v_mfma_f32_16x16x32_bf16 v[34:37], v[162:165], v[178:181], v[34:37]
	v_mfma_f32_16x16x32_bf16 v[38:41], v[150:153], v[178:181], v[38:41]
	v_mfma_f32_16x16x32_bf16 v[22:25], v[150:153], v[202:205], v[22:25]
	v_mfma_f32_16x16x32_bf16 v[18:21], v[162:165], v[202:205], v[18:21]
	v_mfma_f32_16x16x32_bf16 v[2:5], v[162:165], v[210:213], v[2:5]
	v_mfma_f32_16x16x32_bf16 v[6:9], v[150:153], v[210:213], v[6:9]
	s_setprio 0
	s_barrier
	s_add_i32 vcc_hi, vcc_hi, 2
	s_add_u32 s27, s27, 0x100
	s_addc_u32 s71, s71, 0
	s_add_u32 s73, s73, 0x100
	s_addc_u32 vcc_lo, vcc_lo, 0
	s_add_u32 s80, s80, 0x100
	s_addc_u32 s81, s81, 0
	s_cmp_gt_u32 vcc_hi, 61
	s_cbranch_scc0 .LBB0_789
	s_and_b64 vcc, exec, s[68:69]
	s_cbranch_vccz .LBB0_792
	s_barrier

; #define PG8_STAGE(bufoff, gbase, voff) do { if constexpr (VAR != 1 && VAR != 3) { _Pragma("unroll") for (int _i = 0; _i < 2; ++_i) \
;         asm volatile("s_mov_b32 m0, %2\n\ts_nop 0\n\tglobal_load_lds_dwordx4 %0, %1" :: "v"((voff)[_i]), "s"((const char*)(gbase)), "s"(ldsbase + (unsigned)((bufoff) + _i * 8192)) : "memory", "m0"); } } while (0)
; #define PG8_LDA(dst, b, h) do { if constexpr (VAR < 2) _Pragma("unroll") for (int m = 0; m < 4; ++m) _Pragma("unroll") for (int k = 0; k < 2; ++k) dst[m][k] = *(const LAS bf16x8*)(lds + PG8_SA(b, h) + aoff + m * 2048 + k * 1024); } while (0)
; #define PG8_LDB(dst, b, h) do { if constexpr (VAR < 2) _Pragma("unroll") for (int n = 0; n < 2; ++n) _Pragma("unroll") for (int k = 0; k < 2; ++k) dst[n][k] = *(const LAS bf16x8*)(lds + PG8_SB(b, h) + boff + n * 2048 + k * 1024); } while (0)
; #define PG8_WAIT_V(n) asm volatile("s_waitcnt vmcnt(" #n ")" ::: "memory")
; #define PG8_WAIT_L(n) asm volatile("s_waitcnt lgkmcnt(" #n ")" ::: "memory")
; #define PG8_BAR do { if constexpr (VAR != 3) __builtin_amdgcn_s_barrier(); } while (0)
; #define PG8_SCHED __builtin_amdgcn_sched_barrier(0)
;     ...
;         for (int t = 0; t < nt; t += 2) {
;             const bool last = (t == nt - 2);
;             const char* a1 = cA + (size_t)(t + 1) * kstep;
;             const char* a2 = last ? nA : cA + (size_t)(t + 2) * kstep; const char* b2 = last ? nB : cB + (size_t)(t + 2) * kstep;
;             const char* a3 = a2 + kstep; const char* b3 = b2 + kstep;
;             PG8_LDB(B0, 0, 0); PG8_LDB(B1, 0, 1); PG8_SCHED; PG8_LDA(At, 0, 0); PG8_STAGE(PG8_SA(1, 1), a1 + hstepA, voffA);
;             PG8_WAIT_V(8); PG8_WAIT_L(0); PG8_BAR; PG8_MMA(0, 0, At, B0); PG8_MMA(0, 1, At, B1); PG8_BAR; PG8_SCHED;
;             PG8_LDA(At, 0, 1); PG8_STAGE(PG8_SB(0, 0), b2, voffB); PG8_STAGE(PG8_SB(0, 1), b2 + hstepB, voffB); PG8_STAGE(PG8_SA(0, 0), a2, voffA);
;             PG8_WAIT_V(8); PG8_WAIT_L(0); PG8_BAR; PG8_MMA(1, 0, At, B0); PG8_MMA(1, 1, At, B1); PG8_BAR; PG8_SCHED;
.LBB0_892:
	ds_read_b128 v[134:137], v201
	ds_read_b128 v[138:141], v201 offset:1024
	ds_read_b128 v[142:145], v201 offset:2048
	ds_read_b128 v[146:149], v201 offset:3072
	ds_read_b128 v[150:153], v202
	ds_read_b128 v[154:157], v202 offset:1024
	ds_read_b128 v[158:161], v202 offset:2048
	ds_read_b128 v[162:165], v202 offset:3072
	s_cmp_eq_u32 s85, 60
	s_cselect_b32 s72, s24, s25
	s_cselect_b32 s73, s1, s39
	s_cselect_b32 s70, s60, s59
	s_cselect_b32 s71, s61, s84
	s_add_u32 s68, s72, 0x80
	s_addc_u32 s69, s73, 0
	ds_read_b128 v[166:169], v203
	ds_read_b128 v[210:213], v203 offset:1024
	ds_read_b128 v[214:217], v203 offset:2048
	ds_read_b128 v[218:221], v203 offset:3072
	ds_read_b128 v[222:225], v203 offset:4096
	ds_read_b128 v[226:229], v203 offset:5120
	ds_read_b128 v[230:233], v203 offset:6144
	ds_read_b128 v[234:237], v203 offset:7168
	s_mov_b32 m0, s77
	s_nop 0
	global_load_lds_dwordx4 v1, s[6:7]
	s_nop 0
	s_mov_b32 m0, s79
	s_nop 0
	global_load_lds_dwordx4 v173, s[6:7]
	s_waitcnt vmcnt(8)
	s_waitcnt lgkmcnt(0)
	s_barrier
	s_setprio 1
	s_waitcnt lgkmcnt(7)
	v_mfma_f32_16x16x32_bf16 v[126:129], v[134:137], v[166:169], v[126:129]
	v_mfma_f32_16x16x32_bf16 v[122:125], v[142:145], v[166:169], v[122:125]
	s_waitcnt lgkmcnt(5)
	v_mfma_f32_16x16x32_bf16 v[106:109], v[142:145], v[214:217], v[106:109]
	v_mfma_f32_16x16x32_bf16 v[110:113], v[134:137], v[214:217], v[110:113]
	s_waitcnt lgkmcnt(3)
	v_mfma_f32_16x16x32_bf16 v[94:97], v[134:137], v[222:225], v[94:97]
	v_mfma_f32_16x16x32_bf16 v[90:93], v[142:145], v[222:225], v[90:93]
	s_waitcnt lgkmcnt(1)
	v_mfma_f32_16x16x32_bf16 v[74:77], v[142:145], v[230:233], v[74:77]
	v_mfma_f32_16x16x32_bf16 v[78:81], v[134:137], v[230:233], v[78:81]
	v_mfma_f32_16x16x32_bf16 v[126:129], v[138:141], v[210:213], v[126:129]
	v_mfma_f32_16x16x32_bf16 v[122:125], v[146:149], v[210:213], v[122:125]
	v_mfma_f32_16x16x32_bf16 v[106:109], v[146:149], v[218:221], v[106:109]
	v_mfma_f32_16x16x32_bf16 v[110:113], v[138:141], v[218:221], v[110:113]
	v_mfma_f32_16x16x32_bf16 v[94:97], v[138:141], v[226:229], v[94:97]
	v_mfma_f32_16x16x32_bf16 v[90:93], v[146:149], v[226:229], v[90:93]
	s_waitcnt lgkmcnt(0)
	v_mfma_f32_16x16x32_bf16 v[74:77], v[146:149], v[234:237], v[74:77]
	v_mfma_f32_16x16x32_bf16 v[78:81], v[138:141], v[234:237], v[78:81]
	s_setprio 0
	s_setprio 1
	v_mfma_f32_16x16x32_bf16 v[118:121], v[150:153], v[166:169], v[118:121]
	v_mfma_f32_16x16x32_bf16 v[114:117], v[158:161], v[166:169], v[114:117]
	v_mfma_f32_16x16x32_bf16 v[98:101], v[158:161], v[214:217], v[98:101]
	v_mfma_f32_16x16x32_bf16 v[102:105], v[150:153], v[214:217], v[102:105]
	v_mfma_f32_16x16x32_bf16 v[86:89], v[150:153], v[222:225], v[86:89]
	v_mfma_f32_16x16x32_bf16 v[82:85], v[158:161], v[222:225], v[82:85]
	v_mfma_f32_16x16x32_bf16 v[66:69], v[158:161], v[230:233], v[66:69]
	v_mfma_f32_16x16x32_bf16 v[70:73], v[150:153], v[230:233], v[70:73]
	v_mfma_f32_16x16x32_bf16 v[118:121], v[154:157], v[210:213], v[118:121]
	v_mfma_f32_16x16x32_bf16 v[114:117], v[162:165], v[210:213], v[114:117]
	v_mfma_f32_16x16x32_bf16 v[98:101], v[162:165], v[218:221], v[98:101]
	v_mfma_f32_16x16x32_bf16 v[102:105], v[154:157], v[218:221], v[102:105]
	v_mfma_f32_16x16x32_bf16 v[86:89], v[154:157], v[226:229], v[86:89]
	v_mfma_f32_16x16x32_bf16 v[82:85], v[162:165], v[226:229], v[82:85]
	v_mfma_f32_16x16x32_bf16 v[66:69], v[162:165], v[234:237], v[66:69]
	v_mfma_f32_16x16x32_bf16 v[70:73], v[154:157], v[234:237], v[70:73]
	s_setprio 0
	s_barrier
	ds_read_b128 v[166:169], v203 offset:16384
	ds_read_b128 v[210:213], v203 offset:17408
	ds_read_b128 v[214:217], v203 offset:18432
	ds_read_b128 v[218:221], v203 offset:19456
	ds_read_b128 v[222:225], v203 offset:20480
	ds_read_b128 v[226:229], v203 offset:21504
	ds_read_b128 v[230:233], v203 offset:22528
	ds_read_b128 v[234:237], v203 offset:23552
	s_mov_b32 m0, s17
	s_nop 0
	global_load_lds_dwordx4 v172, s[70:71]
	s_add_u32 s86, s70, 0x100000
	s_mov_b32 m0, s19
	s_nop 0
	global_load_lds_dwordx4 v174, s[70:71]
	s_addc_u32 s87, s71, 0
	s_mov_b32 m0, s23
	s_nop 0
	global_load_lds_dwordx4 v172, s[86:87]
	s_nop 0
	s_mov_b32 m0, s26
	s_nop 0
	global_load_lds_dwordx4 v174, s[86:87]
	s_nop 0
	s_mov_b32 m0, s15
	s_nop 0
	global_load_lds_dwordx4 v1, s[72:73]
	s_nop 0
	s_mov_b32 m0, s27
	s_nop 0
	global_load_lds_dwordx4 v173, s[72:73]
	s_waitcnt vmcnt(8)
	s_waitcnt lgkmcnt(0)
	s_barrier
	s_setprio 1
	s_waitcnt lgkmcnt(7)
	v_mfma_f32_16x16x32_bf16 v[62:65], v[134:137], v[166:169], v[62:65]
	v_mfma_f32_16x16x32_bf16 v[58:61], v[142:145], v[166:169], v[58:61]
	s_waitcnt lgkmcnt(5)
	v_mfma_f32_16x16x32_bf16 v[42:45], v[142:145], v[214:217], v[42:45]
	v_mfma_f32_16x16x32_bf16 v[46:49], v[134:137], v[214:217], v[46:49]
	s_waitcnt lgkmcnt(3)
	v_mfma_f32_16x16x32_bf16 v[30:33], v[134:137], v[222:225], v[30:33]
	v_mfma_f32_16x16x32_bf16 v[26:29], v[142:145], v[222:225], v[26:29]
	s_waitcnt lgkmcnt(1)
	v_mfma_f32_16x16x32_bf16 v[10:13], v[142:145], v[230:233], v[10:13]
	v_mfma_f32_16x16x32_bf16 v[14:17], v[134:137], v[230:233], v[14:17]
	v_mfma_f32_16x16x32_bf16 v[62:65], v[138:141], v[210:213], v[62:65]
	v_mfma_f32_16x16x32_bf16 v[58:61], v[146:149], v[210:213], v[58:61]
	v_mfma_f32_16x16x32_bf16 v[42:45], v[146:149], v[218:221], v[42:45]
	v_mfma_f32_16x16x32_bf16 v[46:49], v[138:141], v[218:221], v[46:49]
	v_mfma_f32_16x16x32_bf16 v[30:33], v[138:141], v[226:229], v[30:33]
	v_mfma_f32_16x16x32_bf16 v[26:29], v[146:149], v[226:229], v[26:29]
	s_waitcnt lgkmcnt(0)
	v_mfma_f32_16x16x32_bf16 v[10:13], v[146:149], v[234:237], v[10:13]
	v_mfma_f32_16x16x32_bf16 v[14:17], v[138:141], v[234:237], v[14:17]
	s_setprio 0
	s_setprio 1
	v_mfma_f32_16x16x32_bf16 v[54:57], v[150:153], v[166:169], v[54:57]
	v_mfma_f32_16x16x32_bf16 v[50:53], v[158:161], v[166:169], v[50:53]
	v_mfma_f32_16x16x32_bf16 v[34:37], v[158:161], v[214:217], v[34:37]
	v_mfma_f32_16x16x32_bf16 v[38:41], v[150:153], v[214:217], v[38:41]
	v_mfma_f32_16x16x32_bf16 v[22:25], v[150:153], v[222:225], v[22:25]
	v_mfma_f32_16x16x32_bf16 v[18:21], v[158:161], v[222:225], v[18:21]
	v_mfma_f32_16x16x32_bf16 v[2:5], v[158:161], v[230:233], v[2:5]
	v_mfma_f32_16x16x32_bf16 v[6:9], v[150:153], v[230:233], v[6:9]
	v_mfma_f32_16x16x32_bf16 v[54:57], v[154:157], v[210:213], v[54:57]
	v_mfma_f32_16x16x32_bf16 v[50:53], v[162:165], v[210:213], v[50:53]
	v_mfma_f32_16x16x32_bf16 v[34:37], v[162:165], v[218:221], v[34:37]
	v_mfma_f32_16x16x32_bf16 v[38:41], v[154:157], v[218:221], v[38:41]
	v_mfma_f32_16x16x32_bf16 v[22:25], v[154:157], v[226:229], v[22:25]
	v_mfma_f32_16x16x32_bf16 v[18:21], v[162:165], v[226:229], v[18:21]
	v_mfma_f32_16x16x32_bf16 v[2:5], v[162:165], v[234:237], v[2:5]
	v_mfma_f32_16x16x32_bf16 v[6:9], v[154:157], v[234:237], v[6:9]
	s_setprio 0
	s_barrier
; #define PG8_STAGE(bufoff, gbase, voff) do { if constexpr (VAR != 1 && VAR != 3) { _Pragma("unroll") for (int _i = 0; _i < 2; ++_i) \
;         asm volatile("s_mov_b32 m0, %2\n\ts_nop 0\n\tglobal_load_lds_dwordx4 %0, %1" :: "v"((voff)[_i]), "s"((const char*)(gbase)), "s"(ldsbase + (unsigned)((bufoff) + _i * 8192)) : "memory", "m0"); } } while (0)
; #define PG8_LDA(dst, b, h) do { if constexpr (VAR < 2) _Pragma("unroll") for (int m = 0; m < 4; ++m) _Pragma("unroll") for (int k = 0; k < 2; ++k) dst[m][k] = *(const LAS bf16x8*)(lds + PG8_SA(b, h) + aoff + m * 2048 + k * 1024); } while (0)
; #define PG8_LDB(dst, b, h) do { if constexpr (VAR < 2) _Pragma("unroll") for (int n = 0; n < 2; ++n) _Pragma("unroll") for (int k = 0; k < 2; ++k) dst[n][k] = *(const LAS bf16x8*)(lds + PG8_SB(b, h) + boff + n * 2048 + k * 1024); } while (0)
; #define PG8_WAIT_V(n) asm volatile("s_waitcnt vmcnt(" #n ")" ::: "memory")
; #define PG8_WAIT_L(n) asm volatile("s_waitcnt lgkmcnt(" #n ")" ::: "memory")
; #define PG8_BAR do { if constexpr (VAR != 3) __builtin_amdgcn_s_barrier(); } while (0)
; #define PG8_SCHED __builtin_amdgcn_sched_barrier(0)
;     ...
;             PG8_LDB(B0, 1, 0); PG8_LDB(B1, 1, 1); PG8_SCHED; PG8_LDA(At, 1, 0); PG8_STAGE(PG8_SA(0, 1), a2 + hstepA, voffA);
;             PG8_WAIT_V(8); PG8_WAIT_L(0); PG8_BAR; PG8_MMA(0, 0, At, B0); PG8_MMA(0, 1, At, B1); PG8_BAR; PG8_SCHED;
;             PG8_LDA(At, 1, 1); PG8_STAGE(PG8_SB(1, 0), b3, voffB); PG8_STAGE(PG8_SB(1, 1), b3 + hstepB, voffB); PG8_STAGE(PG8_SA(1, 0), a3, voffA);
;             PG8_WAIT_V(8); PG8_WAIT_L(0); PG8_BAR; PG8_MMA(1, 0, At, B0); PG8_MMA(1, 1, At, B1); PG8_BAR; PG8_SCHED;
;         }
;         if (wr == 0) PG8_BAR;
	ds_read_b128 v[134:137], v204
	ds_read_b128 v[138:141], v204 offset:1024
	ds_read_b128 v[142:145], v204 offset:2048
	ds_read_b128 v[146:149], v204 offset:3072
	ds_read_b128 v[150:153], v205
	ds_read_b128 v[154:157], v205 offset:1024
	ds_read_b128 v[158:161], v205 offset:2048
	ds_read_b128 v[162:165], v205 offset:3072
	ds_read_b128 v[166:169], v203 offset:32768
	ds_read_b128 v[210:213], v203 offset:33792
	ds_read_b128 v[214:217], v203 offset:34816
	ds_read_b128 v[218:221], v203 offset:35840
	ds_read_b128 v[222:225], v203 offset:36864
	ds_read_b128 v[226:229], v203 offset:37888
	ds_read_b128 v[230:233], v203 offset:38912
	ds_read_b128 v[234:237], v203 offset:39936
	s_add_u32 s72, s72, 0x100000
	s_addc_u32 s73, s73, 0
	s_mov_b32 m0, s28
	s_nop 0
	global_load_lds_dwordx4 v1, s[72:73]
	s_nop 0
	s_mov_b32 m0, s29
	s_nop 0
	global_load_lds_dwordx4 v173, s[72:73]
	s_waitcnt vmcnt(8)
	s_waitcnt lgkmcnt(0)
	s_barrier
	s_setprio 1
	s_waitcnt lgkmcnt(7)
	v_mfma_f32_16x16x32_bf16 v[126:129], v[134:137], v[166:169], v[126:129]
	v_mfma_f32_16x16x32_bf16 v[122:125], v[142:145], v[166:169], v[122:125]
	s_waitcnt lgkmcnt(5)
	v_mfma_f32_16x16x32_bf16 v[106:109], v[142:145], v[214:217], v[106:109]
	v_mfma_f32_16x16x32_bf16 v[110:113], v[134:137], v[214:217], v[110:113]
	s_waitcnt lgkmcnt(3)
	v_mfma_f32_16x16x32_bf16 v[94:97], v[134:137], v[222:225], v[94:97]
	v_mfma_f32_16x16x32_bf16 v[90:93], v[142:145], v[222:225], v[90:93]
	s_waitcnt lgkmcnt(1)
	v_mfma_f32_16x16x32_bf16 v[74:77], v[142:145], v[230:233], v[74:77]
	v_mfma_f32_16x16x32_bf16 v[78:81], v[134:137], v[230:233], v[78:81]
	v_mfma_f32_16x16x32_bf16 v[126:129], v[138:141], v[210:213], v[126:129]
	v_mfma_f32_16x16x32_bf16 v[122:125], v[146:149], v[210:213], v[122:125]
	v_mfma_f32_16x16x32_bf16 v[106:109], v[146:149], v[218:221], v[106:109]
	v_mfma_f32_16x16x32_bf16 v[110:113], v[138:141], v[218:221], v[110:113]
	v_mfma_f32_16x16x32_bf16 v[94:97], v[138:141], v[226:229], v[94:97]
	v_mfma_f32_16x16x32_bf16 v[90:93], v[146:149], v[226:229], v[90:93]
	s_waitcnt lgkmcnt(0)
	v_mfma_f32_16x16x32_bf16 v[74:77], v[146:149], v[234:237], v[74:77]
	v_mfma_f32_16x16x32_bf16 v[78:81], v[138:141], v[234:237], v[78:81]
	s_setprio 0
	s_setprio 1
	v_mfma_f32_16x16x32_bf16 v[118:121], v[150:153], v[166:169], v[118:121]
	v_mfma_f32_16x16x32_bf16 v[114:117], v[158:161], v[166:169], v[114:117]
	v_mfma_f32_16x16x32_bf16 v[98:101], v[158:161], v[214:217], v[98:101]
	v_mfma_f32_16x16x32_bf16 v[102:105], v[150:153], v[214:217], v[102:105]
	v_mfma_f32_16x16x32_bf16 v[86:89], v[150:153], v[222:225], v[86:89]
	v_mfma_f32_16x16x32_bf16 v[82:85], v[158:161], v[222:225], v[82:85]
	v_mfma_f32_16x16x32_bf16 v[66:69], v[158:161], v[230:233], v[66:69]
	v_mfma_f32_16x16x32_bf16 v[70:73], v[150:153], v[230:233], v[70:73]
	v_mfma_f32_16x16x32_bf16 v[118:121], v[154:157], v[210:213], v[118:121]
	v_mfma_f32_16x16x32_bf16 v[114:117], v[162:165], v[210:213], v[114:117]
	v_mfma_f32_16x16x32_bf16 v[98:101], v[162:165], v[218:221], v[98:101]
	v_mfma_f32_16x16x32_bf16 v[102:105], v[154:157], v[218:221], v[102:105]
	v_mfma_f32_16x16x32_bf16 v[86:89], v[154:157], v[226:229], v[86:89]
	v_mfma_f32_16x16x32_bf16 v[82:85], v[162:165], v[226:229], v[82:85]
	v_mfma_f32_16x16x32_bf16 v[66:69], v[162:165], v[234:237], v[66:69]
	v_mfma_f32_16x16x32_bf16 v[70:73], v[154:157], v[234:237], v[70:73]
	s_setprio 0
	s_barrier
	ds_read_b128 v[166:169], v203 offset:49152
	ds_read_b128 v[210:213], v203 offset:50176
	ds_read_b128 v[214:217], v203 offset:51200
	ds_read_b128 v[218:221], v203 offset:52224
	ds_read_b128 v[222:225], v203 offset:53248
	ds_read_b128 v[226:229], v203 offset:54272
	ds_read_b128 v[230:233], v203 offset:55296
	ds_read_b128 v[234:237], v203 offset:56320
	s_add_u32 s72, s70, 0x80
	s_addc_u32 s73, s71, 0
	s_mov_b32 m0, s33
	s_nop 0
	global_load_lds_dwordx4 v172, s[72:73]
	s_add_u32 s70, s70, 0x100080
	s_mov_b32 m0, s35
	s_nop 0
	global_load_lds_dwordx4 v174, s[72:73]
	s_addc_u32 s71, s71, 0
	s_mov_b32 m0, s75
	s_nop 0
	global_load_lds_dwordx4 v172, s[70:71]
	s_nop 0
	s_mov_b32 m0, s76
	s_nop 0
	global_load_lds_dwordx4 v174, s[70:71]
	s_nop 0
	s_mov_b32 m0, s67
	s_nop 0
	global_load_lds_dwordx4 v1, s[68:69]
	s_nop 0
	s_mov_b32 m0, s74
	s_nop 0
	global_load_lds_dwordx4 v173, s[68:69]
	s_waitcnt vmcnt(8)
	s_waitcnt lgkmcnt(0)
	s_barrier
	s_setprio 1
	s_waitcnt lgkmcnt(7)
	v_mfma_f32_16x16x32_bf16 v[62:65], v[134:137], v[166:169], v[62:65]
	v_mfma_f32_16x16x32_bf16 v[58:61], v[142:145], v[166:169], v[58:61]
	s_waitcnt lgkmcnt(5)
	v_mfma_f32_16x16x32_bf16 v[42:45], v[142:145], v[214:217], v[42:45]
	v_mfma_f32_16x16x32_bf16 v[46:49], v[134:137], v[214:217], v[46:49]
	s_waitcnt lgkmcnt(3)
	v_mfma_f32_16x16x32_bf16 v[30:33], v[134:137], v[222:225], v[30:33]
	v_mfma_f32_16x16x32_bf16 v[26:29], v[142:145], v[222:225], v[26:29]
	s_waitcnt lgkmcnt(1)
	v_mfma_f32_16x16x32_bf16 v[10:13], v[142:145], v[230:233], v[10:13]
	v_mfma_f32_16x16x32_bf16 v[14:17], v[134:137], v[230:233], v[14:17]
	v_mfma_f32_16x16x32_bf16 v[62:65], v[138:141], v[210:213], v[62:65]
	v_mfma_f32_16x16x32_bf16 v[58:61], v[146:149], v[210:213], v[58:61]
	v_mfma_f32_16x16x32_bf16 v[42:45], v[146:149], v[218:221], v[42:45]
	v_mfma_f32_16x16x32_bf16 v[46:49], v[138:141], v[218:221], v[46:49]
	v_mfma_f32_16x16x32_bf16 v[30:33], v[138:141], v[226:229], v[30:33]
	v_mfma_f32_16x16x32_bf16 v[26:29], v[146:149], v[226:229], v[26:29]
	s_waitcnt lgkmcnt(0)
	v_mfma_f32_16x16x32_bf16 v[10:13], v[146:149], v[234:237], v[10:13]
	v_mfma_f32_16x16x32_bf16 v[14:17], v[138:141], v[234:237], v[14:17]
	s_setprio 0
	s_setprio 1
	v_mfma_f32_16x16x32_bf16 v[54:57], v[150:153], v[166:169], v[54:57]
	v_mfma_f32_16x16x32_bf16 v[50:53], v[158:161], v[166:169], v[50:53]
	v_mfma_f32_16x16x32_bf16 v[34:37], v[158:161], v[214:217], v[34:37]
	v_mfma_f32_16x16x32_bf16 v[38:41], v[150:153], v[214:217], v[38:41]
	v_mfma_f32_16x16x32_bf16 v[22:25], v[150:153], v[222:225], v[22:25]
	v_mfma_f32_16x16x32_bf16 v[18:21], v[158:161], v[222:225], v[18:21]
	v_mfma_f32_16x16x32_bf16 v[2:5], v[158:161], v[230:233], v[2:5]
	v_mfma_f32_16x16x32_bf16 v[6:9], v[150:153], v[230:233], v[6:9]
	v_mfma_f32_16x16x32_bf16 v[54:57], v[154:157], v[210:213], v[54:57]
	v_mfma_f32_16x16x32_bf16 v[50:53], v[162:165], v[210:213], v[50:53]
	v_mfma_f32_16x16x32_bf16 v[34:37], v[162:165], v[218:221], v[34:37]
	v_mfma_f32_16x16x32_bf16 v[38:41], v[154:157], v[218:221], v[38:41]
	v_mfma_f32_16x16x32_bf16 v[22:25], v[154:157], v[226:229], v[22:25]
	v_mfma_f32_16x16x32_bf16 v[18:21], v[162:165], v[226:229], v[18:21]
	v_mfma_f32_16x16x32_bf16 v[2:5], v[162:165], v[234:237], v[2:5]
	v_mfma_f32_16x16x32_bf16 v[6:9], v[154:157], v[234:237], v[6:9]
	s_setprio 0
	s_barrier
	s_add_i32 s85, s85, 2
	s_add_u32 s25, s25, 0x100
	s_addc_u32 s39, s39, 0
	s_add_u32 s59, s59, 0x100
	s_addc_u32 s84, s84, 0
	s_add_u32 s6, s6, 0x100
	s_addc_u32 s7, s7, 0
	s_cmp_gt_u32 s85, 61
	s_cbranch_scc0 .LBB0_892
	s_and_b64 vcc, exec, s[10:11]
	s_cbranch_vccz .LBB0_895
	s_barrier

; #define PG8_STAGE(bufoff, gbase, voff) do { if constexpr (VAR != 1 && VAR != 3) { _Pragma("unroll") for (int _i = 0; _i < 2; ++_i) \
;         asm volatile("s_mov_b32 m0, %2\n\ts_nop 0\n\tglobal_load_lds_dwordx4 %0, %1" :: "v"((voff)[_i]), "s"((const char*)(gbase)), "s"(ldsbase + (unsigned)((bufoff) + _i * 8192)) : "memory", "m0"); } } while (0)
; #define PG8_LDA(dst, b, h) do { if constexpr (VAR < 2) _Pragma("unroll") for (int m = 0; m < 4; ++m) _Pragma("unroll") for (int k = 0; k < 2; ++k) dst[m][k] = *(const LAS bf16x8*)(lds + PG8_SA(b, h) + aoff + m * 2048 + k * 1024); } while (0)
; #define PG8_LDB(dst, b, h) do { if constexpr (VAR < 2) _Pragma("unroll") for (int n = 0; n < 2; ++n) _Pragma("unroll") for (int k = 0; k < 2; ++k) dst[n][k] = *(const LAS bf16x8*)(lds + PG8_SB(b, h) + boff + n * 2048 + k * 1024); } while (0)
; #define PG8_WAIT_V(n) asm volatile("s_waitcnt vmcnt(" #n ")" ::: "memory")
; #define PG8_WAIT_L(n) asm volatile("s_waitcnt lgkmcnt(" #n ")" ::: "memory")
; #define PG8_BAR do { if constexpr (VAR != 3) __builtin_amdgcn_s_barrier(); } while (0)
; #define PG8_SCHED __builtin_amdgcn_sched_barrier(0)
;     ...
;         for (int t = 0; t < nt; t += 2) {
;             const bool last = (t == nt - 2);
;             const char* a1 = cA + (size_t)(t + 1) * kstep;
;             const char* a2 = last ? nA : cA + (size_t)(t + 2) * kstep; const char* b2 = last ? nB : cB + (size_t)(t + 2) * kstep;
;             const char* a3 = a2 + kstep; const char* b3 = b2 + kstep;
;             PG8_LDB(B0, 0, 0); PG8_LDB(B1, 0, 1); PG8_SCHED; PG8_LDA(At, 0, 0); PG8_STAGE(PG8_SA(1, 1), a1 + hstepA, voffA);
;             PG8_WAIT_V(8); PG8_WAIT_L(0); PG8_BAR; PG8_MMA(0, 0, At, B0); PG8_MMA(0, 1, At, B1); PG8_BAR; PG8_SCHED;
;             PG8_LDA(At, 0, 1); PG8_STAGE(PG8_SB(0, 0), b2, voffB); PG8_STAGE(PG8_SB(0, 1), b2 + hstepB, voffB); PG8_STAGE(PG8_SA(0, 0), a2, voffA);
;             PG8_WAIT_V(8); PG8_WAIT_L(0); PG8_BAR; PG8_MMA(1, 0, At, B0); PG8_MMA(1, 1, At, B1); PG8_BAR; PG8_SCHED;
.LBB0_1002:
	ds_read_b128 v[130:133], v183
	ds_read_b128 v[134:137], v183 offset:1024
	ds_read_b128 v[138:141], v183 offset:2048
	ds_read_b128 v[142:145], v183 offset:3072
	ds_read_b128 v[146:149], v184
	ds_read_b128 v[150:153], v184 offset:1024
	ds_read_b128 v[154:157], v184 offset:2048
	ds_read_b128 v[162:165], v184 offset:3072
	s_cmp_eq_u32 s86, 12
	s_cselect_b32 s78, s25, s63
	s_cselect_b32 s79, s24, s65
	s_cselect_b32 s76, s66, s84
	s_cselect_b32 s77, s67, s85
	s_add_u32 s74, s78, 0x80
	s_addc_u32 s75, s79, 0
	ds_read_b128 v[166:169], v185
	ds_read_b128 v[170:173], v185 offset:1024
	ds_read_b128 v[190:193], v185 offset:2048
	ds_read_b128 v[194:197], v185 offset:3072
	ds_read_b128 v[198:201], v185 offset:4096
	ds_read_b128 v[202:205], v185 offset:5120
	ds_read_b128 v[206:209], v185 offset:6144
	ds_read_b128 v[210:213], v185 offset:7168
	s_mov_b32 m0, s82
	s_nop 0
	global_load_lds_dwordx4 v176, s[12:13]
	s_nop 0
	s_mov_b32 m0, s83
	s_nop 0
	global_load_lds_dwordx4 v178, s[12:13]
	s_waitcnt vmcnt(8)
	s_waitcnt lgkmcnt(0)
	s_barrier
	s_setprio 1
	s_waitcnt lgkmcnt(7)
	v_mfma_f32_16x16x32_bf16 v[126:129], v[130:133], v[166:169], v[126:129]
	v_mfma_f32_16x16x32_bf16 v[122:125], v[138:141], v[166:169], v[122:125]
	s_waitcnt lgkmcnt(5)
	v_mfma_f32_16x16x32_bf16 v[106:109], v[138:141], v[190:193], v[106:109]
	v_mfma_f32_16x16x32_bf16 v[110:113], v[130:133], v[190:193], v[110:113]
	s_waitcnt lgkmcnt(3)
	v_mfma_f32_16x16x32_bf16 v[94:97], v[130:133], v[198:201], v[94:97]
	v_mfma_f32_16x16x32_bf16 v[90:93], v[138:141], v[198:201], v[90:93]
	s_waitcnt lgkmcnt(1)
	v_mfma_f32_16x16x32_bf16 v[74:77], v[138:141], v[206:209], v[74:77]
	v_mfma_f32_16x16x32_bf16 v[78:81], v[130:133], v[206:209], v[78:81]
	v_mfma_f32_16x16x32_bf16 v[126:129], v[134:137], v[170:173], v[126:129]
	v_mfma_f32_16x16x32_bf16 v[122:125], v[142:145], v[170:173], v[122:125]
	v_mfma_f32_16x16x32_bf16 v[106:109], v[142:145], v[194:197], v[106:109]
	v_mfma_f32_16x16x32_bf16 v[110:113], v[134:137], v[194:197], v[110:113]
	v_mfma_f32_16x16x32_bf16 v[94:97], v[134:137], v[202:205], v[94:97]
	v_mfma_f32_16x16x32_bf16 v[90:93], v[142:145], v[202:205], v[90:93]
	s_waitcnt lgkmcnt(0)
	v_mfma_f32_16x16x32_bf16 v[74:77], v[142:145], v[210:213], v[74:77]
	v_mfma_f32_16x16x32_bf16 v[78:81], v[134:137], v[210:213], v[78:81]
	s_setprio 0
	s_setprio 1
	v_mfma_f32_16x16x32_bf16 v[118:121], v[146:149], v[166:169], v[118:121]
	v_mfma_f32_16x16x32_bf16 v[114:117], v[154:157], v[166:169], v[114:117]
	v_mfma_f32_16x16x32_bf16 v[98:101], v[154:157], v[190:193], v[98:101]
	v_mfma_f32_16x16x32_bf16 v[102:105], v[146:149], v[190:193], v[102:105]
	v_mfma_f32_16x16x32_bf16 v[86:89], v[146:149], v[198:201], v[86:89]
	v_mfma_f32_16x16x32_bf16 v[82:85], v[154:157], v[198:201], v[82:85]
	v_mfma_f32_16x16x32_bf16 v[66:69], v[154:157], v[206:209], v[66:69]
	v_mfma_f32_16x16x32_bf16 v[70:73], v[146:149], v[206:209], v[70:73]
	v_mfma_f32_16x16x32_bf16 v[118:121], v[150:153], v[170:173], v[118:121]
	v_mfma_f32_16x16x32_bf16 v[114:117], v[162:165], v[170:173], v[114:117]
	v_mfma_f32_16x16x32_bf16 v[98:101], v[162:165], v[194:197], v[98:101]
	v_mfma_f32_16x16x32_bf16 v[102:105], v[150:153], v[194:197], v[102:105]
	v_mfma_f32_16x16x32_bf16 v[86:89], v[150:153], v[202:205], v[86:89]
	v_mfma_f32_16x16x32_bf16 v[82:85], v[162:165], v[202:205], v[82:85]
	v_mfma_f32_16x16x32_bf16 v[66:69], v[162:165], v[210:213], v[66:69]
	v_mfma_f32_16x16x32_bf16 v[70:73], v[150:153], v[210:213], v[70:73]
	s_setprio 0
	s_barrier
	ds_read_b128 v[166:169], v185 offset:16384
	ds_read_b128 v[170:173], v185 offset:17408
	ds_read_b128 v[190:193], v185 offset:18432
	ds_read_b128 v[194:197], v185 offset:19456
	ds_read_b128 v[198:201], v185 offset:20480
	ds_read_b128 v[202:205], v185 offset:21504
	ds_read_b128 v[206:209], v185 offset:22528
	ds_read_b128 v[210:213], v185 offset:23552
	s_mov_b32 m0, s17
	s_nop 0
	global_load_lds_dwordx4 v177, s[76:77]
	s_add_u32 s88, s76, 0x40000
	s_mov_b32 m0, s19
	s_nop 0
	global_load_lds_dwordx4 v179, s[76:77]
	s_addc_u32 s89, s77, 0
	s_mov_b32 m0, s23
	s_nop 0
	global_load_lds_dwordx4 v177, s[88:89]
	s_nop 0
	s_mov_b32 m0, s26
	s_nop 0
	global_load_lds_dwordx4 v179, s[88:89]
	s_nop 0
	s_mov_b32 m0, s15
	s_nop 0
	global_load_lds_dwordx4 v176, s[78:79]
	s_nop 0
	s_mov_b32 m0, s27
	s_nop 0
	global_load_lds_dwordx4 v178, s[78:79]
	s_waitcnt vmcnt(8)
	s_waitcnt lgkmcnt(0)
	s_barrier
	s_setprio 1
	s_waitcnt lgkmcnt(7)
	v_mfma_f32_16x16x32_bf16 v[62:65], v[130:133], v[166:169], v[62:65]
	v_mfma_f32_16x16x32_bf16 v[58:61], v[138:141], v[166:169], v[58:61]
	s_waitcnt lgkmcnt(5)
	v_mfma_f32_16x16x32_bf16 v[42:45], v[138:141], v[190:193], v[42:45]
	v_mfma_f32_16x16x32_bf16 v[46:49], v[130:133], v[190:193], v[46:49]
	s_waitcnt lgkmcnt(3)
	v_mfma_f32_16x16x32_bf16 v[30:33], v[130:133], v[198:201], v[30:33]
	v_mfma_f32_16x16x32_bf16 v[26:29], v[138:141], v[198:201], v[26:29]
	s_waitcnt lgkmcnt(1)
	v_mfma_f32_16x16x32_bf16 v[10:13], v[138:141], v[206:209], v[10:13]
	v_mfma_f32_16x16x32_bf16 v[14:17], v[130:133], v[206:209], v[14:17]
	v_mfma_f32_16x16x32_bf16 v[62:65], v[134:137], v[170:173], v[62:65]
	v_mfma_f32_16x16x32_bf16 v[58:61], v[142:145], v[170:173], v[58:61]
	v_mfma_f32_16x16x32_bf16 v[42:45], v[142:145], v[194:197], v[42:45]
	v_mfma_f32_16x16x32_bf16 v[46:49], v[134:137], v[194:197], v[46:49]
	v_mfma_f32_16x16x32_bf16 v[30:33], v[134:137], v[202:205], v[30:33]
	v_mfma_f32_16x16x32_bf16 v[26:29], v[142:145], v[202:205], v[26:29]
	s_waitcnt lgkmcnt(0)
	v_mfma_f32_16x16x32_bf16 v[10:13], v[142:145], v[210:213], v[10:13]
	v_mfma_f32_16x16x32_bf16 v[14:17], v[134:137], v[210:213], v[14:17]
	s_setprio 0
	s_setprio 1
	v_mfma_f32_16x16x32_bf16 v[54:57], v[146:149], v[166:169], v[54:57]
	v_mfma_f32_16x16x32_bf16 v[50:53], v[154:157], v[166:169], v[50:53]
	v_mfma_f32_16x16x32_bf16 v[34:37], v[154:157], v[190:193], v[34:37]
	v_mfma_f32_16x16x32_bf16 v[38:41], v[146:149], v[190:193], v[38:41]
	v_mfma_f32_16x16x32_bf16 v[22:25], v[146:149], v[198:201], v[22:25]
	v_mfma_f32_16x16x32_bf16 v[18:21], v[154:157], v[198:201], v[18:21]
	v_mfma_f32_16x16x32_bf16 v[2:5], v[154:157], v[206:209], v[2:5]
	v_mfma_f32_16x16x32_bf16 v[6:9], v[146:149], v[206:209], v[6:9]
	v_mfma_f32_16x16x32_bf16 v[54:57], v[150:153], v[170:173], v[54:57]
	v_mfma_f32_16x16x32_bf16 v[50:53], v[162:165], v[170:173], v[50:53]
	v_mfma_f32_16x16x32_bf16 v[34:37], v[162:165], v[194:197], v[34:37]
	v_mfma_f32_16x16x32_bf16 v[38:41], v[150:153], v[194:197], v[38:41]
	v_mfma_f32_16x16x32_bf16 v[22:25], v[150:153], v[202:205], v[22:25]
	v_mfma_f32_16x16x32_bf16 v[18:21], v[162:165], v[202:205], v[18:21]
	v_mfma_f32_16x16x32_bf16 v[2:5], v[162:165], v[210:213], v[2:5]
	v_mfma_f32_16x16x32_bf16 v[6:9], v[150:153], v[210:213], v[6:9]
	s_setprio 0
	s_barrier
; #define PG8_STAGE(bufoff, gbase, voff) do { if constexpr (VAR != 1 && VAR != 3) { _Pragma("unroll") for (int _i = 0; _i < 2; ++_i) \
;         asm volatile("s_mov_b32 m0, %2\n\ts_nop 0\n\tglobal_load_lds_dwordx4 %0, %1" :: "v"((voff)[_i]), "s"((const char*)(gbase)), "s"(ldsbase + (unsigned)((bufoff) + _i * 8192)) : "memory", "m0"); } } while (0)
; #define PG8_LDA(dst, b, h) do { if constexpr (VAR < 2) _Pragma("unroll") for (int m = 0; m < 4; ++m) _Pragma("unroll") for (int k = 0; k < 2; ++k) dst[m][k] = *(const LAS bf16x8*)(lds + PG8_SA(b, h) + aoff + m * 2048 + k * 1024); } while (0)
; #define PG8_LDB(dst, b, h) do { if constexpr (VAR < 2) _Pragma("unroll") for (int n = 0; n < 2; ++n) _Pragma("unroll") for (int k = 0; k < 2; ++k) dst[n][k] = *(const LAS bf16x8*)(lds + PG8_SB(b, h) + boff + n * 2048 + k * 1024); } while (0)
; #define PG8_WAIT_V(n) asm volatile("s_waitcnt vmcnt(" #n ")" ::: "memory")
; #define PG8_WAIT_L(n) asm volatile("s_waitcnt lgkmcnt(" #n ")" ::: "memory")
; #define PG8_BAR do { if constexpr (VAR != 3) __builtin_amdgcn_s_barrier(); } while (0)
; #define PG8_SCHED __builtin_amdgcn_sched_barrier(0)
;     ...
;             PG8_LDB(B0, 1, 0); PG8_LDB(B1, 1, 1); PG8_SCHED; PG8_LDA(At, 1, 0); PG8_STAGE(PG8_SA(0, 1), a2 + hstepA, voffA);
;             PG8_WAIT_V(8); PG8_WAIT_L(0); PG8_BAR; PG8_MMA(0, 0, At, B0); PG8_MMA(0, 1, At, B1); PG8_BAR; PG8_SCHED;
;             PG8_LDA(At, 1, 1); PG8_STAGE(PG8_SB(1, 0), b3, voffB); PG8_STAGE(PG8_SB(1, 1), b3 + hstepB, voffB); PG8_STAGE(PG8_SA(1, 0), a3, voffA);
;             PG8_WAIT_V(8); PG8_WAIT_L(0); PG8_BAR; PG8_MMA(1, 0, At, B0); PG8_MMA(1, 1, At, B1); PG8_BAR; PG8_SCHED;
;         }
;         if (wr == 0) PG8_BAR;
	ds_read_b128 v[130:133], v186
	ds_read_b128 v[134:137], v186 offset:1024
	ds_read_b128 v[138:141], v186 offset:2048
	ds_read_b128 v[142:145], v186 offset:3072
	ds_read_b128 v[146:149], v187
	ds_read_b128 v[150:153], v187 offset:1024
	ds_read_b128 v[154:157], v187 offset:2048
	ds_read_b128 v[162:165], v187 offset:3072
	ds_read_b128 v[166:169], v185 offset:32768
	ds_read_b128 v[170:173], v185 offset:33792
	ds_read_b128 v[190:193], v185 offset:34816
	ds_read_b128 v[194:197], v185 offset:35840
	ds_read_b128 v[198:201], v185 offset:36864
	ds_read_b128 v[202:205], v185 offset:37888
	ds_read_b128 v[206:209], v185 offset:38912
	ds_read_b128 v[210:213], v185 offset:39936
	s_add_u32 s78, s78, 0x40000
	s_addc_u32 s79, s79, 0
	s_mov_b32 m0, s28
	s_nop 0
	global_load_lds_dwordx4 v176, s[78:79]
	s_nop 0
	s_mov_b32 m0, s29
	s_nop 0
	global_load_lds_dwordx4 v178, s[78:79]
	s_waitcnt vmcnt(8)
	s_waitcnt lgkmcnt(0)
	s_barrier
	s_setprio 1
	s_waitcnt lgkmcnt(7)
	v_mfma_f32_16x16x32_bf16 v[126:129], v[130:133], v[166:169], v[126:129]
	v_mfma_f32_16x16x32_bf16 v[122:125], v[138:141], v[166:169], v[122:125]
	s_waitcnt lgkmcnt(5)
	v_mfma_f32_16x16x32_bf16 v[106:109], v[138:141], v[190:193], v[106:109]
	v_mfma_f32_16x16x32_bf16 v[110:113], v[130:133], v[190:193], v[110:113]
	s_waitcnt lgkmcnt(3)
	v_mfma_f32_16x16x32_bf16 v[94:97], v[130:133], v[198:201], v[94:97]
	v_mfma_f32_16x16x32_bf16 v[90:93], v[138:141], v[198:201], v[90:93]
	s_waitcnt lgkmcnt(1)
	v_mfma_f32_16x16x32_bf16 v[74:77], v[138:141], v[206:209], v[74:77]
	v_mfma_f32_16x16x32_bf16 v[78:81], v[130:133], v[206:209], v[78:81]
	v_mfma_f32_16x16x32_bf16 v[126:129], v[134:137], v[170:173], v[126:129]
	v_mfma_f32_16x16x32_bf16 v[122:125], v[142:145], v[170:173], v[122:125]
	v_mfma_f32_16x16x32_bf16 v[106:109], v[142:145], v[194:197], v[106:109]
	v_mfma_f32_16x16x32_bf16 v[110:113], v[134:137], v[194:197], v[110:113]
	v_mfma_f32_16x16x32_bf16 v[94:97], v[134:137], v[202:205], v[94:97]
	v_mfma_f32_16x16x32_bf16 v[90:93], v[142:145], v[202:205], v[90:93]
	s_waitcnt lgkmcnt(0)
	v_mfma_f32_16x16x32_bf16 v[74:77], v[142:145], v[210:213], v[74:77]
	v_mfma_f32_16x16x32_bf16 v[78:81], v[134:137], v[210:213], v[78:81]
	s_setprio 0
	s_setprio 1
	v_mfma_f32_16x16x32_bf16 v[118:121], v[146:149], v[166:169], v[118:121]
	v_mfma_f32_16x16x32_bf16 v[114:117], v[154:157], v[166:169], v[114:117]
	v_mfma_f32_16x16x32_bf16 v[98:101], v[154:157], v[190:193], v[98:101]
	v_mfma_f32_16x16x32_bf16 v[102:105], v[146:149], v[190:193], v[102:105]
	v_mfma_f32_16x16x32_bf16 v[86:89], v[146:149], v[198:201], v[86:89]
	v_mfma_f32_16x16x32_bf16 v[82:85], v[154:157], v[198:201], v[82:85]
	v_mfma_f32_16x16x32_bf16 v[66:69], v[154:157], v[206:209], v[66:69]
	v_mfma_f32_16x16x32_bf16 v[70:73], v[146:149], v[206:209], v[70:73]
	v_mfma_f32_16x16x32_bf16 v[118:121], v[150:153], v[170:173], v[118:121]
	v_mfma_f32_16x16x32_bf16 v[114:117], v[162:165], v[170:173], v[114:117]
	v_mfma_f32_16x16x32_bf16 v[98:101], v[162:165], v[194:197], v[98:101]
	v_mfma_f32_16x16x32_bf16 v[102:105], v[150:153], v[194:197], v[102:105]
	v_mfma_f32_16x16x32_bf16 v[86:89], v[150:153], v[202:205], v[86:89]
	v_mfma_f32_16x16x32_bf16 v[82:85], v[162:165], v[202:205], v[82:85]
	v_mfma_f32_16x16x32_bf16 v[66:69], v[162:165], v[210:213], v[66:69]
	v_mfma_f32_16x16x32_bf16 v[70:73], v[150:153], v[210:213], v[70:73]
	s_setprio 0
	s_barrier
	ds_read_b128 v[166:169], v185 offset:49152
	ds_read_b128 v[170:173], v185 offset:50176
	ds_read_b128 v[190:193], v185 offset:51200
	ds_read_b128 v[194:197], v185 offset:52224
	ds_read_b128 v[198:201], v185 offset:53248
	ds_read_b128 v[202:205], v185 offset:54272
	ds_read_b128 v[206:209], v185 offset:55296
	ds_read_b128 v[210:213], v185 offset:56320
	s_add_u32 s78, s76, 0x80
	s_addc_u32 s79, s77, 0
	s_mov_b32 m0, s33
	s_nop 0
	global_load_lds_dwordx4 v177, s[78:79]
	s_add_u32 s76, s76, 0x40080
	s_mov_b32 m0, s35
	s_nop 0
	global_load_lds_dwordx4 v179, s[78:79]
	s_addc_u32 s77, s77, 0
	s_mov_b32 m0, s80
	s_nop 0
	global_load_lds_dwordx4 v177, s[76:77]
	s_nop 0
	s_mov_b32 m0, s81
	s_nop 0
	global_load_lds_dwordx4 v179, s[76:77]
	s_nop 0
	s_mov_b32 m0, s71
	s_nop 0
	global_load_lds_dwordx4 v176, s[74:75]
	s_nop 0
	s_mov_b32 m0, s73
	s_nop 0
	global_load_lds_dwordx4 v178, s[74:75]
	s_waitcnt vmcnt(8)
	s_waitcnt lgkmcnt(0)
	s_barrier
	s_setprio 1
	s_waitcnt lgkmcnt(7)
	v_mfma_f32_16x16x32_bf16 v[62:65], v[130:133], v[166:169], v[62:65]
	v_mfma_f32_16x16x32_bf16 v[58:61], v[138:141], v[166:169], v[58:61]
	s_waitcnt lgkmcnt(5)
	v_mfma_f32_16x16x32_bf16 v[42:45], v[138:141], v[190:193], v[42:45]
	v_mfma_f32_16x16x32_bf16 v[46:49], v[130:133], v[190:193], v[46:49]
	s_waitcnt lgkmcnt(3)
	v_mfma_f32_16x16x32_bf16 v[30:33], v[130:133], v[198:201], v[30:33]
	v_mfma_f32_16x16x32_bf16 v[26:29], v[138:141], v[198:201], v[26:29]
	s_waitcnt lgkmcnt(1)
	v_mfma_f32_16x16x32_bf16 v[10:13], v[138:141], v[206:209], v[10:13]
	v_mfma_f32_16x16x32_bf16 v[14:17], v[130:133], v[206:209], v[14:17]
	v_mfma_f32_16x16x32_bf16 v[62:65], v[134:137], v[170:173], v[62:65]
	v_mfma_f32_16x16x32_bf16 v[58:61], v[142:145], v[170:173], v[58:61]
	v_mfma_f32_16x16x32_bf16 v[42:45], v[142:145], v[194:197], v[42:45]
	v_mfma_f32_16x16x32_bf16 v[46:49], v[134:137], v[194:197], v[46:49]
	v_mfma_f32_16x16x32_bf16 v[30:33], v[134:137], v[202:205], v[30:33]
	v_mfma_f32_16x16x32_bf16 v[26:29], v[142:145], v[202:205], v[26:29]
	s_waitcnt lgkmcnt(0)
	v_mfma_f32_16x16x32_bf16 v[10:13], v[142:145], v[210:213], v[10:13]
	v_mfma_f32_16x16x32_bf16 v[14:17], v[134:137], v[210:213], v[14:17]
	s_setprio 0
	s_setprio 1
	v_mfma_f32_16x16x32_bf16 v[54:57], v[146:149], v[166:169], v[54:57]
	v_mfma_f32_16x16x32_bf16 v[50:53], v[154:157], v[166:169], v[50:53]
	v_mfma_f32_16x16x32_bf16 v[34:37], v[154:157], v[190:193], v[34:37]
	v_mfma_f32_16x16x32_bf16 v[38:41], v[146:149], v[190:193], v[38:41]
	v_mfma_f32_16x16x32_bf16 v[22:25], v[146:149], v[198:201], v[22:25]
	v_mfma_f32_16x16x32_bf16 v[18:21], v[154:157], v[198:201], v[18:21]
	v_mfma_f32_16x16x32_bf16 v[2:5], v[154:157], v[206:209], v[2:5]
	v_mfma_f32_16x16x32_bf16 v[6:9], v[146:149], v[206:209], v[6:9]
	v_mfma_f32_16x16x32_bf16 v[54:57], v[150:153], v[170:173], v[54:57]
	v_mfma_f32_16x16x32_bf16 v[50:53], v[162:165], v[170:173], v[50:53]
	v_mfma_f32_16x16x32_bf16 v[34:37], v[162:165], v[194:197], v[34:37]
	v_mfma_f32_16x16x32_bf16 v[38:41], v[150:153], v[194:197], v[38:41]
	v_mfma_f32_16x16x32_bf16 v[22:25], v[150:153], v[202:205], v[22:25]
	v_mfma_f32_16x16x32_bf16 v[18:21], v[162:165], v[202:205], v[18:21]
	v_mfma_f32_16x16x32_bf16 v[2:5], v[162:165], v[210:213], v[2:5]
	v_mfma_f32_16x16x32_bf16 v[6:9], v[150:153], v[210:213], v[6:9]
	s_setprio 0
	s_barrier
	s_add_i32 s86, s86, 2
	s_add_u32 s63, s63, 0x100
	s_addc_u32 s65, s65, 0
	s_add_u32 s84, s84, 0x100
	s_addc_u32 s85, s85, 0
	s_add_u32 s12, s12, 0x100
	s_addc_u32 s13, s13, 0
	s_cmp_gt_u32 s86, 13
	s_cbranch_scc0 .LBB0_1002
	s_and_b64 vcc, exec, s[60:61]
	s_cbranch_vccz .LBB0_1005
	s_barrier

; #define PG8_STAGE(bufoff, gbase, voff) do { if constexpr (VAR != 1 && VAR != 3) { _Pragma("unroll") for (int _i = 0; _i < 2; ++_i) \
;         asm volatile("s_mov_b32 m0, %2\n\ts_nop 0\n\tglobal_load_lds_dwordx4 %0, %1" :: "v"((voff)[_i]), "s"((const char*)(gbase)), "s"(ldsbase + (unsigned)((bufoff) + _i * 8192)) : "memory", "m0"); } } while (0)
; #define PG8_LDA(dst, b, h) do { if constexpr (VAR < 2) _Pragma("unroll") for (int m = 0; m < 4; ++m) _Pragma("unroll") for (int k = 0; k < 2; ++k) dst[m][k] = *(const LAS bf16x8*)(lds + PG8_SA(b, h) + aoff + m * 2048 + k * 1024); } while (0)
; #define PG8_LDB(dst, b, h) do { if constexpr (VAR < 2) _Pragma("unroll") for (int n = 0; n < 2; ++n) _Pragma("unroll") for (int k = 0; k < 2; ++k) dst[n][k] = *(const LAS bf16x8*)(lds + PG8_SB(b, h) + boff + n * 2048 + k * 1024); } while (0)
; #define PG8_WAIT_V(n) asm volatile("s_waitcnt vmcnt(" #n ")" ::: "memory")
; #define PG8_WAIT_L(n) asm volatile("s_waitcnt lgkmcnt(" #n ")" ::: "memory")
; #define PG8_BAR do { if constexpr (VAR != 3) __builtin_amdgcn_s_barrier(); } while (0)
; #define PG8_SCHED __builtin_amdgcn_sched_barrier(0)
;     ...
;         for (int t = 0; t < nt; t += 2) {
;             const bool last = (t == nt - 2);
;             const char* a1 = cA + (size_t)(t + 1) * kstep;
;             const char* a2 = last ? nA : cA + (size_t)(t + 2) * kstep; const char* b2 = last ? nB : cB + (size_t)(t + 2) * kstep;
;             const char* a3 = a2 + kstep; const char* b3 = b2 + kstep;
;             PG8_LDB(B0, 0, 0); PG8_LDB(B1, 0, 1); PG8_SCHED; PG8_LDA(At, 0, 0); PG8_STAGE(PG8_SA(1, 1), a1 + hstepA, voffA);
;             PG8_WAIT_V(8); PG8_WAIT_L(0); PG8_BAR; PG8_MMA(0, 0, At, B0); PG8_MMA(0, 1, At, B1); PG8_BAR; PG8_SCHED;
;             PG8_LDA(At, 0, 1); PG8_STAGE(PG8_SB(0, 0), b2, voffB); PG8_STAGE(PG8_SB(0, 1), b2 + hstepB, voffB); PG8_STAGE(PG8_SA(0, 0), a2, voffA);
;             PG8_WAIT_V(8); PG8_WAIT_L(0); PG8_BAR; PG8_MMA(1, 0, At, B0); PG8_MMA(1, 1, At, B1); PG8_BAR; PG8_SCHED;
.LBB0_1191:
	ds_read_b128 v[2:5], v231
	ds_read_b128 v[6:9], v231 offset:1024
	ds_read_b128 v[10:13], v231 offset:2048
	ds_read_b128 v[14:17], v231 offset:3072
	ds_read_b128 v[18:21], v232
	ds_read_b128 v[26:29], v232 offset:1024
	ds_read_b128 v[154:157], v232 offset:2048
	ds_read_b128 v[158:161], v232 offset:3072
	s_cmp_eq_u32 s71, 28
	s_cselect_b32 s82, s72, s25
	s_cselect_b32 s83, s73, s26
	s_cselect_b32 s80, s24, s27
	s_cselect_b32 s81, s11, s69
	s_add_u32 s78, s82, 0x80
	s_addc_u32 s79, s83, 0
	ds_read_b128 v[162:165], v233
	ds_read_b128 v[166:169], v233 offset:1024
	ds_read_b128 v[178:181], v233 offset:2048
	ds_read_b128 v[182:185], v233 offset:3072
	ds_read_b128 v[186:189], v233 offset:4096
	ds_read_b128 v[190:193], v233 offset:5120
	ds_read_b128 v[194:197], v233 offset:6144
	ds_read_b128 v[198:201], v233 offset:7168
	s_mov_b32 m0, s90
	s_nop 0
	global_load_lds_dwordx4 v208, s[0:1]
	s_nop 0
	s_mov_b32 m0, s91
	s_nop 0
	global_load_lds_dwordx4 v210, s[0:1]
	s_waitcnt vmcnt(8)
	s_waitcnt lgkmcnt(0)
	s_barrier
	s_setprio 1
	s_waitcnt lgkmcnt(7)
	v_mfma_i32_16x16x64_i8 v[150:153], v[2:5], v[162:165], v[150:153]
	v_mfma_i32_16x16x64_i8 v[142:145], v[10:13], v[162:165], v[142:145]
	s_waitcnt lgkmcnt(5)
	v_mfma_i32_16x16x64_i8 v[122:125], v[10:13], v[178:181], v[122:125]
	v_mfma_i32_16x16x64_i8 v[126:129], v[2:5], v[178:181], v[126:129]
	s_waitcnt lgkmcnt(3)
	v_mfma_i32_16x16x64_i8 v[114:117], v[2:5], v[186:189], v[114:117]
	v_mfma_i32_16x16x64_i8 v[106:109], v[10:13], v[186:189], v[106:109]
	s_waitcnt lgkmcnt(1)
	v_mfma_i32_16x16x64_i8 v[138:141], v[10:13], v[194:197], v[138:141]
	v_mfma_i32_16x16x64_i8 v[146:149], v[2:5], v[194:197], v[146:149]
	v_mfma_i32_16x16x64_i8 v[150:153], v[6:9], v[166:169], v[150:153]
	v_mfma_i32_16x16x64_i8 v[142:145], v[14:17], v[166:169], v[142:145]
	v_mfma_i32_16x16x64_i8 v[122:125], v[14:17], v[182:185], v[122:125]
	v_mfma_i32_16x16x64_i8 v[126:129], v[6:9], v[182:185], v[126:129]
	v_mfma_i32_16x16x64_i8 v[114:117], v[6:9], v[190:193], v[114:117]
	v_mfma_i32_16x16x64_i8 v[106:109], v[14:17], v[190:193], v[106:109]
	s_waitcnt lgkmcnt(0)
	v_mfma_i32_16x16x64_i8 v[138:141], v[14:17], v[198:201], v[138:141]
	v_mfma_i32_16x16x64_i8 v[146:149], v[6:9], v[198:201], v[146:149]
	s_setprio 0
	s_setprio 1
	v_mfma_i32_16x16x64_i8 v[134:137], v[18:21], v[162:165], v[134:137]
	v_mfma_i32_16x16x64_i8 v[130:133], v[154:157], v[162:165], v[130:133]
	v_mfma_i32_16x16x64_i8 v[110:113], v[154:157], v[178:181], v[110:113]
	v_mfma_i32_16x16x64_i8 v[118:121], v[18:21], v[178:181], v[118:121]
	v_mfma_i32_16x16x64_i8 v[102:105], v[18:21], v[186:189], v[102:105]
	v_mfma_i32_16x16x64_i8 v[98:101], v[154:157], v[186:189], v[98:101]
	v_mfma_i32_16x16x64_i8 v[90:93], v[154:157], v[194:197], v[90:93]
	v_mfma_i32_16x16x64_i8 v[94:97], v[18:21], v[194:197], v[94:97]
	v_mfma_i32_16x16x64_i8 v[134:137], v[26:29], v[166:169], v[134:137]
	v_mfma_i32_16x16x64_i8 v[130:133], v[158:161], v[166:169], v[130:133]
	v_mfma_i32_16x16x64_i8 v[110:113], v[158:161], v[182:185], v[110:113]
	v_mfma_i32_16x16x64_i8 v[118:121], v[26:29], v[182:185], v[118:121]
	v_mfma_i32_16x16x64_i8 v[102:105], v[26:29], v[190:193], v[102:105]
	v_mfma_i32_16x16x64_i8 v[98:101], v[158:161], v[190:193], v[98:101]
	v_mfma_i32_16x16x64_i8 v[90:93], v[158:161], v[198:201], v[90:93]
	v_mfma_i32_16x16x64_i8 v[94:97], v[26:29], v[198:201], v[94:97]
	s_setprio 0
	s_barrier
	ds_read_b128 v[162:165], v233 offset:16384
	ds_read_b128 v[166:169], v233 offset:17408
	ds_read_b128 v[178:181], v233 offset:18432
	ds_read_b128 v[182:185], v233 offset:19456
	ds_read_b128 v[186:189], v233 offset:20480
	ds_read_b128 v[190:193], v233 offset:21504
	ds_read_b128 v[194:197], v233 offset:22528
	ds_read_b128 v[198:201], v233 offset:23552
	s_mov_b32 m0, s21
	s_nop 0
	global_load_lds_dwordx4 v209, s[80:81]
	s_add_u32 s96, s80, 0x80000
	s_mov_b32 m0, s23
	s_nop 0
	global_load_lds_dwordx4 v211, s[80:81]
	s_addc_u32 s97, s81, 0
	s_mov_b32 m0, s28
	s_nop 0
	global_load_lds_dwordx4 v209, s[96:97]
	s_nop 0
	s_mov_b32 m0, s29
	s_nop 0
	global_load_lds_dwordx4 v211, s[96:97]
	s_nop 0
	s_mov_b32 m0, s15
	s_nop 0
	global_load_lds_dwordx4 v208, s[82:83]
	s_nop 0
	s_mov_b32 m0, s30
	s_nop 0
	global_load_lds_dwordx4 v210, s[82:83]
	s_waitcnt vmcnt(8)
	s_waitcnt lgkmcnt(0)
	s_barrier
	s_setprio 1
	s_waitcnt lgkmcnt(7)
	v_mfma_i32_16x16x64_i8 v[86:89], v[2:5], v[162:165], v[86:89]
	v_mfma_i32_16x16x64_i8 v[82:85], v[10:13], v[162:165], v[82:85]
	s_waitcnt lgkmcnt(5)
	v_mfma_i32_16x16x64_i8 v[66:69], v[10:13], v[178:181], v[66:69]
	v_mfma_i32_16x16x64_i8 v[74:77], v[2:5], v[178:181], v[74:77]
	s_waitcnt lgkmcnt(3)
	v_mfma_i32_16x16x64_i8 v[58:61], v[2:5], v[186:189], v[58:61]
	v_mfma_i32_16x16x64_i8 v[50:53], v[10:13], v[186:189], v[50:53]
	s_waitcnt lgkmcnt(1)
	v_mfma_i32_16x16x64_i8 v[2:5], v[2:5], v[194:197], v[30:33]
	v_mfma_i32_16x16x64_i8 v[86:89], v[6:9], v[166:169], v[86:89]
	v_mfma_i32_16x16x64_i8 v[82:85], v[14:17], v[166:169], v[82:85]
	v_mfma_i32_16x16x64_i8 v[74:77], v[6:9], v[182:185], v[74:77]
	v_mfma_i32_16x16x64_i8 v[66:69], v[14:17], v[182:185], v[66:69]
	v_mfma_i32_16x16x64_i8 v[58:61], v[6:9], v[190:193], v[58:61]
	v_mfma_i32_16x16x64_i8 v[50:53], v[14:17], v[190:193], v[50:53]
	s_waitcnt lgkmcnt(0)
	v_mfma_i32_16x16x64_i8 v[2:5], v[6:9], v[198:201], v[2:5]
	v_mfma_i32_16x16x64_i8 v[6:9], v[10:13], v[194:197], v[22:25]
	v_mfma_i32_16x16x64_i8 v[6:9], v[14:17], v[198:201], v[6:9]
	s_setprio 0
	s_setprio 1
	v_mfma_i32_16x16x64_i8 v[22:25], v[18:21], v[178:181], v[62:65]
	v_mfma_i32_16x16x64_i8 v[62:65], v[26:29], v[182:185], v[22:25]
	v_mfma_i32_16x16x64_i8 v[22:25], v[154:157], v[178:181], v[54:57]
	v_mfma_i32_16x16x64_i8 v[54:57], v[158:161], v[182:185], v[22:25]
	v_mfma_i32_16x16x64_i8 v[22:25], v[18:21], v[186:189], v[46:49]
	v_mfma_i32_16x16x64_i8 v[46:49], v[26:29], v[190:193], v[22:25]
	v_mfma_i32_16x16x64_i8 v[22:25], v[154:157], v[186:189], v[42:45]
	v_mfma_i32_16x16x64_i8 v[10:13], v[18:21], v[162:165], v[78:81]
	v_mfma_i32_16x16x64_i8 v[14:17], v[154:157], v[162:165], v[70:73]
	v_mfma_i32_16x16x64_i8 v[42:45], v[158:161], v[190:193], v[22:25]
	v_mfma_i32_16x16x64_i8 v[18:21], v[18:21], v[194:197], v[38:41]
	v_mfma_i32_16x16x64_i8 v[22:25], v[154:157], v[194:197], v[34:37]
	v_mfma_i32_16x16x64_i8 v[10:13], v[26:29], v[166:169], v[10:13]
	v_mfma_i32_16x16x64_i8 v[14:17], v[158:161], v[166:169], v[14:17]
	v_mfma_i32_16x16x64_i8 v[26:29], v[158:161], v[198:201], v[22:25]
	v_mfma_i32_16x16x64_i8 v[18:21], v[26:29], v[198:201], v[18:21]
	s_setprio 0
	s_barrier
; #define PG8_STAGE(bufoff, gbase, voff) do { if constexpr (VAR != 1 && VAR != 3) { _Pragma("unroll") for (int _i = 0; _i < 2; ++_i) \
;         asm volatile("s_mov_b32 m0, %2\n\ts_nop 0\n\tglobal_load_lds_dwordx4 %0, %1" :: "v"((voff)[_i]), "s"((const char*)(gbase)), "s"(ldsbase + (unsigned)((bufoff) + _i * 8192)) : "memory", "m0"); } } while (0)
; #define PG8_LDA(dst, b, h) do { if constexpr (VAR < 2) _Pragma("unroll") for (int m = 0; m < 4; ++m) _Pragma("unroll") for (int k = 0; k < 2; ++k) dst[m][k] = *(const LAS bf16x8*)(lds + PG8_SA(b, h) + aoff + m * 2048 + k * 1024); } while (0)
; #define PG8_LDB(dst, b, h) do { if constexpr (VAR < 2) _Pragma("unroll") for (int n = 0; n < 2; ++n) _Pragma("unroll") for (int k = 0; k < 2; ++k) dst[n][k] = *(const LAS bf16x8*)(lds + PG8_SB(b, h) + boff + n * 2048 + k * 1024); } while (0)
; #define PG8_WAIT_V(n) asm volatile("s_waitcnt vmcnt(" #n ")" ::: "memory")
; #define PG8_WAIT_L(n) asm volatile("s_waitcnt lgkmcnt(" #n ")" ::: "memory")
; #define PG8_BAR do { if constexpr (VAR != 3) __builtin_amdgcn_s_barrier(); } while (0)
; #define PG8_SCHED __builtin_amdgcn_sched_barrier(0)
;     ...
;             PG8_LDB(B0, 1, 0); PG8_LDB(B1, 1, 1); PG8_SCHED; PG8_LDA(At, 1, 0); PG8_STAGE(PG8_SA(0, 1), a2 + hstepA, voffA);
;             PG8_WAIT_V(8); PG8_WAIT_L(0); PG8_BAR; PG8_MMA(0, 0, At, B0); PG8_MMA(0, 1, At, B1); PG8_BAR; PG8_SCHED;
;             PG8_LDA(At, 1, 1); PG8_STAGE(PG8_SB(1, 0), b3, voffB); PG8_STAGE(PG8_SB(1, 1), b3 + hstepB, voffB); PG8_STAGE(PG8_SA(1, 0), a3, voffA);
;             PG8_WAIT_V(8); PG8_WAIT_L(0); PG8_BAR; PG8_MMA(1, 0, At, B0); PG8_MMA(1, 1, At, B1); PG8_BAR; PG8_SCHED;
;         }
;         if (wr == 0) PG8_BAR;
	s_nop 1
	ds_read_b128 v[22:25], v234
	ds_read_b128 v[30:33], v234 offset:1024
	ds_read_b128 v[34:37], v234 offset:2048
	ds_read_b128 v[38:41], v234 offset:3072
	ds_read_b128 v[154:157], v235
	ds_read_b128 v[158:161], v235 offset:1024
	ds_read_b128 v[162:165], v235 offset:2048
	ds_read_b128 v[166:169], v235 offset:3072
	ds_read_b128 v[70:73], v233 offset:32768
	ds_read_b128 v[78:81], v233 offset:33792
	ds_read_b128 v[178:181], v233 offset:34816
	ds_read_b128 v[182:185], v233 offset:35840
	ds_read_b128 v[186:189], v233 offset:36864
	ds_read_b128 v[190:193], v233 offset:37888
	ds_read_b128 v[194:197], v233 offset:38912
	ds_read_b128 v[198:201], v233 offset:39936
	s_add_u32 s82, s82, 0x80000
	s_addc_u32 s83, s83, 0
	s_mov_b32 m0, s31
	s_nop 0
	global_load_lds_dwordx4 v208, s[82:83]
	s_nop 0
	s_mov_b32 m0, s33
	s_nop 0
	global_load_lds_dwordx4 v210, s[82:83]
	s_waitcnt vmcnt(8)
	s_waitcnt lgkmcnt(0)
	s_barrier
	s_setprio 1
	s_waitcnt lgkmcnt(7)
	v_mfma_i32_16x16x64_i8 v[150:153], v[22:25], v[70:73], v[150:153]
	v_mfma_i32_16x16x64_i8 v[142:145], v[34:37], v[70:73], v[142:145]
	s_waitcnt lgkmcnt(5)
	v_mfma_i32_16x16x64_i8 v[122:125], v[34:37], v[178:181], v[122:125]
	v_mfma_i32_16x16x64_i8 v[126:129], v[22:25], v[178:181], v[126:129]
	s_waitcnt lgkmcnt(3)
	v_mfma_i32_16x16x64_i8 v[114:117], v[22:25], v[186:189], v[114:117]
	v_mfma_i32_16x16x64_i8 v[106:109], v[34:37], v[186:189], v[106:109]
	s_waitcnt lgkmcnt(1)
	v_mfma_i32_16x16x64_i8 v[138:141], v[34:37], v[194:197], v[138:141]
	v_mfma_i32_16x16x64_i8 v[146:149], v[22:25], v[194:197], v[146:149]
	v_mfma_i32_16x16x64_i8 v[150:153], v[30:33], v[78:81], v[150:153]
	v_mfma_i32_16x16x64_i8 v[142:145], v[38:41], v[78:81], v[142:145]
	v_mfma_i32_16x16x64_i8 v[122:125], v[38:41], v[182:185], v[122:125]
	v_mfma_i32_16x16x64_i8 v[126:129], v[30:33], v[182:185], v[126:129]
	v_mfma_i32_16x16x64_i8 v[114:117], v[30:33], v[190:193], v[114:117]
	v_mfma_i32_16x16x64_i8 v[106:109], v[38:41], v[190:193], v[106:109]
	s_waitcnt lgkmcnt(0)
	v_mfma_i32_16x16x64_i8 v[138:141], v[38:41], v[198:201], v[138:141]
	v_mfma_i32_16x16x64_i8 v[146:149], v[30:33], v[198:201], v[146:149]
	s_setprio 0
	s_setprio 1
	v_mfma_i32_16x16x64_i8 v[134:137], v[154:157], v[70:73], v[134:137]
	v_mfma_i32_16x16x64_i8 v[70:73], v[162:165], v[70:73], v[130:133]
	v_mfma_i32_16x16x64_i8 v[130:133], v[166:169], v[78:81], v[70:73]
	v_mfma_i32_16x16x64_i8 v[70:73], v[154:157], v[178:181], v[118:121]
	v_mfma_i32_16x16x64_i8 v[118:121], v[158:161], v[182:185], v[70:73]
	v_mfma_i32_16x16x64_i8 v[70:73], v[162:165], v[178:181], v[110:113]
	v_mfma_i32_16x16x64_i8 v[110:113], v[166:169], v[182:185], v[70:73]
	v_mfma_i32_16x16x64_i8 v[70:73], v[154:157], v[186:189], v[102:105]
	v_mfma_i32_16x16x64_i8 v[102:105], v[158:161], v[190:193], v[70:73]
	v_mfma_i32_16x16x64_i8 v[70:73], v[162:165], v[186:189], v[98:101]
	v_mfma_i32_16x16x64_i8 v[98:101], v[166:169], v[190:193], v[70:73]
	v_mfma_i32_16x16x64_i8 v[70:73], v[154:157], v[194:197], v[94:97]
	v_mfma_i32_16x16x64_i8 v[94:97], v[158:161], v[198:201], v[70:73]
	v_mfma_i32_16x16x64_i8 v[70:73], v[162:165], v[194:197], v[90:93]
	v_mfma_i32_16x16x64_i8 v[134:137], v[158:161], v[78:81], v[134:137]
	v_mfma_i32_16x16x64_i8 v[90:93], v[166:169], v[198:201], v[70:73]
	s_setprio 0
	s_barrier
	s_nop 3
	ds_read_b128 v[70:73], v233 offset:49152
	ds_read_b128 v[178:181], v233 offset:50176
	ds_read_b128 v[182:185], v233 offset:51200
	ds_read_b128 v[186:189], v233 offset:52224
	ds_read_b128 v[190:193], v233 offset:53248
	ds_read_b128 v[194:197], v233 offset:54272
	ds_read_b128 v[198:201], v233 offset:55296
	ds_read_b128 v[202:205], v233 offset:56320
	s_add_u32 s82, s80, 0x80
	s_addc_u32 s83, s81, 0
	s_mov_b32 m0, s84
	s_nop 0
	global_load_lds_dwordx4 v209, s[82:83]
	s_add_u32 s80, s80, 0x80080
	s_mov_b32 m0, s85
	s_nop 0
	global_load_lds_dwordx4 v211, s[82:83]
	s_addc_u32 s81, s81, 0
	s_mov_b32 m0, s88
	s_nop 0
	global_load_lds_dwordx4 v209, s[80:81]
	s_nop 0
	s_mov_b32 m0, s89
	s_nop 0
	global_load_lds_dwordx4 v211, s[80:81]
	s_nop 0
	s_mov_b32 m0, s86
	s_nop 0
	global_load_lds_dwordx4 v208, s[78:79]
	s_nop 0
	s_mov_b32 m0, s87
	s_nop 0
	global_load_lds_dwordx4 v210, s[78:79]
	s_waitcnt vmcnt(8)
	s_waitcnt lgkmcnt(0)
	s_barrier
	s_setprio 1
	s_waitcnt lgkmcnt(7)
	v_mfma_i32_16x16x64_i8 v[78:81], v[22:25], v[70:73], v[86:89]
	s_waitcnt lgkmcnt(5)
	v_mfma_i32_16x16x64_i8 v[74:77], v[22:25], v[182:185], v[74:77]
	s_waitcnt lgkmcnt(3)
	v_mfma_i32_16x16x64_i8 v[58:61], v[22:25], v[190:193], v[58:61]
	s_waitcnt lgkmcnt(1)
	v_mfma_i32_16x16x64_i8 v[2:5], v[22:25], v[198:201], v[2:5]
	v_mfma_i32_16x16x64_i8 v[86:89], v[30:33], v[178:181], v[78:81]
	v_mfma_i32_16x16x64_i8 v[78:81], v[34:37], v[70:73], v[82:85]
	v_mfma_i32_16x16x64_i8 v[74:77], v[30:33], v[186:189], v[74:77]
	v_mfma_i32_16x16x64_i8 v[66:69], v[34:37], v[182:185], v[66:69]
	v_mfma_i32_16x16x64_i8 v[58:61], v[30:33], v[194:197], v[58:61]
	v_mfma_i32_16x16x64_i8 v[50:53], v[34:37], v[190:193], v[50:53]
	s_waitcnt lgkmcnt(0)
	v_mfma_i32_16x16x64_i8 v[30:33], v[30:33], v[202:205], v[2:5]
	v_mfma_i32_16x16x64_i8 v[2:5], v[34:37], v[198:201], v[6:9]
	v_mfma_i32_16x16x64_i8 v[82:85], v[38:41], v[178:181], v[78:81]
	v_mfma_i32_16x16x64_i8 v[66:69], v[38:41], v[186:189], v[66:69]
	v_mfma_i32_16x16x64_i8 v[50:53], v[38:41], v[194:197], v[50:53]
	v_mfma_i32_16x16x64_i8 v[22:25], v[38:41], v[202:205], v[2:5]
	s_setprio 0
	s_setprio 1
	v_mfma_i32_16x16x64_i8 v[2:5], v[154:157], v[70:73], v[10:13]
	v_mfma_i32_16x16x64_i8 v[78:81], v[158:161], v[178:181], v[2:5]
	v_mfma_i32_16x16x64_i8 v[2:5], v[162:165], v[70:73], v[14:17]
	v_mfma_i32_16x16x64_i8 v[70:73], v[166:169], v[178:181], v[2:5]
	v_mfma_i32_16x16x64_i8 v[2:5], v[154:157], v[182:185], v[62:65]
	v_mfma_i32_16x16x64_i8 v[62:65], v[158:161], v[186:189], v[2:5]
	v_mfma_i32_16x16x64_i8 v[2:5], v[162:165], v[182:185], v[54:57]
	v_mfma_i32_16x16x64_i8 v[54:57], v[166:169], v[186:189], v[2:5]
	v_mfma_i32_16x16x64_i8 v[2:5], v[154:157], v[190:193], v[46:49]
	v_mfma_i32_16x16x64_i8 v[46:49], v[158:161], v[194:197], v[2:5]
	v_mfma_i32_16x16x64_i8 v[2:5], v[162:165], v[190:193], v[42:45]
	v_mfma_i32_16x16x64_i8 v[42:45], v[166:169], v[194:197], v[2:5]
	v_mfma_i32_16x16x64_i8 v[2:5], v[154:157], v[198:201], v[18:21]
	v_mfma_i32_16x16x64_i8 v[38:41], v[158:161], v[202:205], v[2:5]
	v_mfma_i32_16x16x64_i8 v[2:5], v[162:165], v[198:201], v[26:29]
	v_mfma_i32_16x16x64_i8 v[34:37], v[166:169], v[202:205], v[2:5]
	s_setprio 0
	s_barrier
	s_add_i32 s71, s71, 2
	s_add_u32 s25, s25, 0x100
	s_addc_u32 s26, s26, 0
	s_add_u32 s27, s27, 0x100
	s_addc_u32 s69, s69, 0
	s_add_u32 s0, s0, 0x100
	s_addc_u32 s1, s1, 0
	s_cmp_gt_u32 s71, 29
	s_cbranch_scc0 .LBB0_1191
	s_and_b64 vcc, exec, s[64:65]
	s_cbranch_vccz .LBB0_1194
	s_barrier

; #define PG8_STAGE(bufoff, gbase, voff) do { if constexpr (VAR != 1 && VAR != 3) { _Pragma("unroll") for (int _i = 0; _i < 2; ++_i) \
;         asm volatile("s_mov_b32 m0, %2\n\ts_nop 0\n\tglobal_load_lds_dwordx4 %0, %1" :: "v"((voff)[_i]), "s"((const char*)(gbase)), "s"(ldsbase + (unsigned)((bufoff) + _i * 8192)) : "memory", "m0"); } } while (0)
; #define PG8_LDA(dst, b, h) do { if constexpr (VAR < 2) _Pragma("unroll") for (int m = 0; m < 4; ++m) _Pragma("unroll") for (int k = 0; k < 2; ++k) dst[m][k] = *(const LAS bf16x8*)(lds + PG8_SA(b, h) + aoff + m * 2048 + k * 1024); } while (0)
; #define PG8_LDB(dst, b, h) do { if constexpr (VAR < 2) _Pragma("unroll") for (int n = 0; n < 2; ++n) _Pragma("unroll") for (int k = 0; k < 2; ++k) dst[n][k] = *(const LAS bf16x8*)(lds + PG8_SB(b, h) + boff + n * 2048 + k * 1024); } while (0)
; #define PG8_WAIT_V(n) asm volatile("s_waitcnt vmcnt(" #n ")" ::: "memory")
; #define PG8_WAIT_L(n) asm volatile("s_waitcnt lgkmcnt(" #n ")" ::: "memory")
; #define PG8_BAR do { if constexpr (VAR != 3) __builtin_amdgcn_s_barrier(); } while (0)
; #define PG8_SCHED __builtin_amdgcn_sched_barrier(0)
;     ...
;         for (int t = 0; t < nt; t += 2) {
;             const bool last = (t == nt - 2);
;             const char* a1 = cA + (size_t)(t + 1) * kstep;
;             const char* a2 = last ? nA : cA + (size_t)(t + 2) * kstep; const char* b2 = last ? nB : cB + (size_t)(t + 2) * kstep;
;             const char* a3 = a2 + kstep; const char* b3 = b2 + kstep;
;             PG8_LDB(B0, 0, 0); PG8_LDB(B1, 0, 1); PG8_SCHED; PG8_LDA(At, 0, 0); PG8_STAGE(PG8_SA(1, 1), a1 + hstepA, voffA);
;             PG8_WAIT_V(8); PG8_WAIT_L(0); PG8_BAR; PG8_MMA(0, 0, At, B0); PG8_MMA(0, 1, At, B1); PG8_BAR; PG8_SCHED;
;             PG8_LDA(At, 0, 1); PG8_STAGE(PG8_SB(0, 0), b2, voffB); PG8_STAGE(PG8_SB(0, 1), b2 + hstepB, voffB); PG8_STAGE(PG8_SA(0, 0), a2, voffA);
;             PG8_WAIT_V(8); PG8_WAIT_L(0); PG8_BAR; PG8_MMA(1, 0, At, B0); PG8_MMA(1, 1, At, B1); PG8_BAR; PG8_SCHED;
.LBB0_1361:
	ds_read_b128 v[130:133], v160
	ds_read_b128 v[134:137], v160 offset:1024
	ds_read_b128 v[142:145], v160 offset:2048
	ds_read_b128 v[146:149], v160 offset:3072
	ds_read_b128 v[150:153], v161
	ds_read_b128 v[166:169], v161 offset:1024
	ds_read_b128 v[170:173], v161 offset:2048
	ds_read_b128 v[174:177], v161 offset:3072
	s_cmpk_eq_i32 s78, 0xa8
	s_cselect_b32 s64, s12, s74
	s_cselect_b32 s65, s13, s75
	s_cselect_b32 s62, s56, s76
	s_cselect_b32 s63, s57, s77
	s_add_u32 s60, s64, 0x80
	s_addc_u32 s61, s65, 0
	ds_read_b128 v[178:181], v162
	ds_read_b128 v[182:185], v162 offset:1024
	ds_read_b128 v[186:189], v162 offset:2048
	ds_read_b128 v[190:193], v162 offset:3072
	ds_read_b128 v[194:197], v162 offset:4096
	ds_read_b128 v[198:201], v162 offset:5120
	ds_read_b128 v[202:205], v162 offset:6144
	ds_read_b128 v[206:209], v162 offset:7168
	s_mov_b32 m0, s69
	s_nop 0
	global_load_lds_dwordx4 v1, s[58:59]
	s_nop 0
	s_mov_b32 m0, s70
	s_nop 0
	global_load_lds_dwordx4 v155, s[58:59]
	s_waitcnt vmcnt(8)
	s_waitcnt lgkmcnt(0)
	s_barrier
	s_setprio 1
	s_waitcnt lgkmcnt(7)
	v_mfma_f32_16x16x32_bf16 v[126:129], v[130:133], v[178:181], v[126:129]
	v_mfma_f32_16x16x32_bf16 v[122:125], v[142:145], v[178:181], v[122:125]
	s_waitcnt lgkmcnt(5)
	v_mfma_f32_16x16x32_bf16 v[106:109], v[142:145], v[186:189], v[106:109]
	v_mfma_f32_16x16x32_bf16 v[110:113], v[130:133], v[186:189], v[110:113]
	s_waitcnt lgkmcnt(3)
	v_mfma_f32_16x16x32_bf16 v[94:97], v[130:133], v[194:197], v[94:97]
	v_mfma_f32_16x16x32_bf16 v[90:93], v[142:145], v[194:197], v[90:93]
	s_waitcnt lgkmcnt(1)
	v_mfma_f32_16x16x32_bf16 v[74:77], v[142:145], v[202:205], v[74:77]
	v_mfma_f32_16x16x32_bf16 v[78:81], v[130:133], v[202:205], v[78:81]
	v_mfma_f32_16x16x32_bf16 v[126:129], v[134:137], v[182:185], v[126:129]
	v_mfma_f32_16x16x32_bf16 v[122:125], v[146:149], v[182:185], v[122:125]
	v_mfma_f32_16x16x32_bf16 v[106:109], v[146:149], v[190:193], v[106:109]
	v_mfma_f32_16x16x32_bf16 v[110:113], v[134:137], v[190:193], v[110:113]
	v_mfma_f32_16x16x32_bf16 v[94:97], v[134:137], v[198:201], v[94:97]
	v_mfma_f32_16x16x32_bf16 v[90:93], v[146:149], v[198:201], v[90:93]
	s_waitcnt lgkmcnt(0)
	v_mfma_f32_16x16x32_bf16 v[74:77], v[146:149], v[206:209], v[74:77]
	v_mfma_f32_16x16x32_bf16 v[78:81], v[134:137], v[206:209], v[78:81]
	s_setprio 0
	s_setprio 1
	v_mfma_f32_16x16x32_bf16 v[118:121], v[150:153], v[178:181], v[118:121]
	v_mfma_f32_16x16x32_bf16 v[114:117], v[170:173], v[178:181], v[114:117]
	v_mfma_f32_16x16x32_bf16 v[98:101], v[170:173], v[186:189], v[98:101]
	v_mfma_f32_16x16x32_bf16 v[102:105], v[150:153], v[186:189], v[102:105]
	v_mfma_f32_16x16x32_bf16 v[86:89], v[150:153], v[194:197], v[86:89]
	v_mfma_f32_16x16x32_bf16 v[82:85], v[170:173], v[194:197], v[82:85]
	v_mfma_f32_16x16x32_bf16 v[66:69], v[170:173], v[202:205], v[66:69]
	v_mfma_f32_16x16x32_bf16 v[70:73], v[150:153], v[202:205], v[70:73]
	v_mfma_f32_16x16x32_bf16 v[118:121], v[166:169], v[182:185], v[118:121]
	v_mfma_f32_16x16x32_bf16 v[114:117], v[174:177], v[182:185], v[114:117]
	v_mfma_f32_16x16x32_bf16 v[98:101], v[174:177], v[190:193], v[98:101]
	v_mfma_f32_16x16x32_bf16 v[102:105], v[166:169], v[190:193], v[102:105]
	v_mfma_f32_16x16x32_bf16 v[86:89], v[166:169], v[198:201], v[86:89]
	v_mfma_f32_16x16x32_bf16 v[82:85], v[174:177], v[198:201], v[82:85]
	v_mfma_f32_16x16x32_bf16 v[66:69], v[174:177], v[206:209], v[66:69]
	v_mfma_f32_16x16x32_bf16 v[70:73], v[166:169], v[206:209], v[70:73]
	s_setprio 0
	s_barrier
	ds_read_b128 v[178:181], v162 offset:16384
	ds_read_b128 v[182:185], v162 offset:17408
	ds_read_b128 v[186:189], v162 offset:18432
	ds_read_b128 v[190:193], v162 offset:19456
	ds_read_b128 v[194:197], v162 offset:20480
	ds_read_b128 v[198:201], v162 offset:21504
	ds_read_b128 v[202:205], v162 offset:22528
	ds_read_b128 v[206:209], v162 offset:23552
	s_mov_b32 m0, s19
	s_nop 0
	global_load_lds_dwordx4 v154, s[62:63]
	s_add_u32 s80, s62, 0x2b0000
	s_mov_b32 m0, s21
	s_nop 0
	global_load_lds_dwordx4 v156, s[62:63]
	s_addc_u32 s81, s63, 0
	s_mov_b32 m0, s23
	s_nop 0
	global_load_lds_dwordx4 v154, s[80:81]
	s_nop 0
	s_mov_b32 m0, s26
	s_nop 0
	global_load_lds_dwordx4 v156, s[80:81]
	s_nop 0
	s_mov_b32 m0, s17
	s_nop 0
	global_load_lds_dwordx4 v1, s[64:65]
	s_nop 0
	s_mov_b32 m0, s27
	s_nop 0
	global_load_lds_dwordx4 v155, s[64:65]
	s_waitcnt vmcnt(8)
	s_waitcnt lgkmcnt(0)
	s_barrier
	s_setprio 1
	s_waitcnt lgkmcnt(7)
	v_mfma_f32_16x16x32_bf16 v[62:65], v[130:133], v[178:181], v[62:65]
	v_mfma_f32_16x16x32_bf16 v[58:61], v[142:145], v[178:181], v[58:61]
	s_waitcnt lgkmcnt(5)
	v_mfma_f32_16x16x32_bf16 v[42:45], v[142:145], v[186:189], v[42:45]
	v_mfma_f32_16x16x32_bf16 v[46:49], v[130:133], v[186:189], v[46:49]
	s_waitcnt lgkmcnt(3)
	v_mfma_f32_16x16x32_bf16 v[30:33], v[130:133], v[194:197], v[30:33]
	v_mfma_f32_16x16x32_bf16 v[26:29], v[142:145], v[194:197], v[26:29]
	s_waitcnt lgkmcnt(1)
	v_mfma_f32_16x16x32_bf16 v[10:13], v[142:145], v[202:205], v[10:13]
	v_mfma_f32_16x16x32_bf16 v[14:17], v[130:133], v[202:205], v[14:17]
	v_mfma_f32_16x16x32_bf16 v[62:65], v[134:137], v[182:185], v[62:65]
	v_mfma_f32_16x16x32_bf16 v[58:61], v[146:149], v[182:185], v[58:61]
	v_mfma_f32_16x16x32_bf16 v[42:45], v[146:149], v[190:193], v[42:45]
	v_mfma_f32_16x16x32_bf16 v[46:49], v[134:137], v[190:193], v[46:49]
	v_mfma_f32_16x16x32_bf16 v[30:33], v[134:137], v[198:201], v[30:33]
	v_mfma_f32_16x16x32_bf16 v[26:29], v[146:149], v[198:201], v[26:29]
	s_waitcnt lgkmcnt(0)
	v_mfma_f32_16x16x32_bf16 v[10:13], v[146:149], v[206:209], v[10:13]
	v_mfma_f32_16x16x32_bf16 v[14:17], v[134:137], v[206:209], v[14:17]
	s_setprio 0
	s_setprio 1
	v_mfma_f32_16x16x32_bf16 v[54:57], v[150:153], v[178:181], v[54:57]
	v_mfma_f32_16x16x32_bf16 v[50:53], v[170:173], v[178:181], v[50:53]
	v_mfma_f32_16x16x32_bf16 v[34:37], v[170:173], v[186:189], v[34:37]
	v_mfma_f32_16x16x32_bf16 v[38:41], v[150:153], v[186:189], v[38:41]
	v_mfma_f32_16x16x32_bf16 v[22:25], v[150:153], v[194:197], v[22:25]
	v_mfma_f32_16x16x32_bf16 v[18:21], v[170:173], v[194:197], v[18:21]
	v_mfma_f32_16x16x32_bf16 v[2:5], v[170:173], v[202:205], v[2:5]
	v_mfma_f32_16x16x32_bf16 v[6:9], v[150:153], v[202:205], v[6:9]
	v_mfma_f32_16x16x32_bf16 v[54:57], v[166:169], v[182:185], v[54:57]
	v_mfma_f32_16x16x32_bf16 v[50:53], v[174:177], v[182:185], v[50:53]
	v_mfma_f32_16x16x32_bf16 v[34:37], v[174:177], v[190:193], v[34:37]
	v_mfma_f32_16x16x32_bf16 v[38:41], v[166:169], v[190:193], v[38:41]
	v_mfma_f32_16x16x32_bf16 v[22:25], v[166:169], v[198:201], v[22:25]
	v_mfma_f32_16x16x32_bf16 v[18:21], v[174:177], v[198:201], v[18:21]
	v_mfma_f32_16x16x32_bf16 v[2:5], v[174:177], v[206:209], v[2:5]
	v_mfma_f32_16x16x32_bf16 v[6:9], v[166:169], v[206:209], v[6:9]
	s_setprio 0
	s_barrier
; #define PG8_STAGE(bufoff, gbase, voff) do { if constexpr (VAR != 1 && VAR != 3) { _Pragma("unroll") for (int _i = 0; _i < 2; ++_i) \
;         asm volatile("s_mov_b32 m0, %2\n\ts_nop 0\n\tglobal_load_lds_dwordx4 %0, %1" :: "v"((voff)[_i]), "s"((const char*)(gbase)), "s"(ldsbase + (unsigned)((bufoff) + _i * 8192)) : "memory", "m0"); } } while (0)
; #define PG8_LDA(dst, b, h) do { if constexpr (VAR < 2) _Pragma("unroll") for (int m = 0; m < 4; ++m) _Pragma("unroll") for (int k = 0; k < 2; ++k) dst[m][k] = *(const LAS bf16x8*)(lds + PG8_SA(b, h) + aoff + m * 2048 + k * 1024); } while (0)
; #define PG8_LDB(dst, b, h) do { if constexpr (VAR < 2) _Pragma("unroll") for (int n = 0; n < 2; ++n) _Pragma("unroll") for (int k = 0; k < 2; ++k) dst[n][k] = *(const LAS bf16x8*)(lds + PG8_SB(b, h) + boff + n * 2048 + k * 1024); } while (0)
; #define PG8_WAIT_V(n) asm volatile("s_waitcnt vmcnt(" #n ")" ::: "memory")
; #define PG8_WAIT_L(n) asm volatile("s_waitcnt lgkmcnt(" #n ")" ::: "memory")
; #define PG8_BAR do { if constexpr (VAR != 3) __builtin_amdgcn_s_barrier(); } while (0)
; #define PG8_SCHED __builtin_amdgcn_sched_barrier(0)
;     ...
;             PG8_LDB(B0, 1, 0); PG8_LDB(B1, 1, 1); PG8_SCHED; PG8_LDA(At, 1, 0); PG8_STAGE(PG8_SA(0, 1), a2 + hstepA, voffA);
;             PG8_WAIT_V(8); PG8_WAIT_L(0); PG8_BAR; PG8_MMA(0, 0, At, B0); PG8_MMA(0, 1, At, B1); PG8_BAR; PG8_SCHED;
;             PG8_LDA(At, 1, 1); PG8_STAGE(PG8_SB(1, 0), b3, voffB); PG8_STAGE(PG8_SB(1, 1), b3 + hstepB, voffB); PG8_STAGE(PG8_SA(1, 0), a3, voffA);
;             PG8_WAIT_V(8); PG8_WAIT_L(0); PG8_BAR; PG8_MMA(1, 0, At, B0); PG8_MMA(1, 1, At, B1); PG8_BAR; PG8_SCHED;
;         }
;         if (wr == 0) PG8_BAR;
	ds_read_b128 v[130:133], v163
	ds_read_b128 v[134:137], v163 offset:1024
	ds_read_b128 v[142:145], v163 offset:2048
	ds_read_b128 v[146:149], v163 offset:3072
	ds_read_b128 v[150:153], v164
	ds_read_b128 v[166:169], v164 offset:1024
	ds_read_b128 v[170:173], v164 offset:2048
	ds_read_b128 v[174:177], v164 offset:3072
	ds_read_b128 v[178:181], v162 offset:32768
	ds_read_b128 v[182:185], v162 offset:33792
	ds_read_b128 v[186:189], v162 offset:34816
	ds_read_b128 v[190:193], v162 offset:35840
	ds_read_b128 v[194:197], v162 offset:36864
	ds_read_b128 v[198:201], v162 offset:37888
	ds_read_b128 v[202:205], v162 offset:38912
	ds_read_b128 v[206:209], v162 offset:39936
	s_add_u32 s64, s64, 0x2b0000
	s_addc_u32 s65, s65, 0
	s_mov_b32 m0, s28
	s_nop 0
	global_load_lds_dwordx4 v1, s[64:65]
	s_nop 0
	s_mov_b32 m0, s29
	s_nop 0
	global_load_lds_dwordx4 v155, s[64:65]
	s_waitcnt vmcnt(8)
	s_waitcnt lgkmcnt(0)
	s_barrier
	s_setprio 1
	s_waitcnt lgkmcnt(7)
	v_mfma_f32_16x16x32_bf16 v[126:129], v[130:133], v[178:181], v[126:129]
	v_mfma_f32_16x16x32_bf16 v[122:125], v[142:145], v[178:181], v[122:125]
	s_waitcnt lgkmcnt(5)
	v_mfma_f32_16x16x32_bf16 v[106:109], v[142:145], v[186:189], v[106:109]
	v_mfma_f32_16x16x32_bf16 v[110:113], v[130:133], v[186:189], v[110:113]
	s_waitcnt lgkmcnt(3)
	v_mfma_f32_16x16x32_bf16 v[94:97], v[130:133], v[194:197], v[94:97]
	v_mfma_f32_16x16x32_bf16 v[90:93], v[142:145], v[194:197], v[90:93]
	s_waitcnt lgkmcnt(1)
	v_mfma_f32_16x16x32_bf16 v[74:77], v[142:145], v[202:205], v[74:77]
	v_mfma_f32_16x16x32_bf16 v[78:81], v[130:133], v[202:205], v[78:81]
	v_mfma_f32_16x16x32_bf16 v[126:129], v[134:137], v[182:185], v[126:129]
	v_mfma_f32_16x16x32_bf16 v[122:125], v[146:149], v[182:185], v[122:125]
	v_mfma_f32_16x16x32_bf16 v[106:109], v[146:149], v[190:193], v[106:109]
	v_mfma_f32_16x16x32_bf16 v[110:113], v[134:137], v[190:193], v[110:113]
	v_mfma_f32_16x16x32_bf16 v[94:97], v[134:137], v[198:201], v[94:97]
	v_mfma_f32_16x16x32_bf16 v[90:93], v[146:149], v[198:201], v[90:93]
	s_waitcnt lgkmcnt(0)
	v_mfma_f32_16x16x32_bf16 v[74:77], v[146:149], v[206:209], v[74:77]
	v_mfma_f32_16x16x32_bf16 v[78:81], v[134:137], v[206:209], v[78:81]
	s_setprio 0
	s_setprio 1
	v_mfma_f32_16x16x32_bf16 v[118:121], v[150:153], v[178:181], v[118:121]
	v_mfma_f32_16x16x32_bf16 v[114:117], v[170:173], v[178:181], v[114:117]
	v_mfma_f32_16x16x32_bf16 v[98:101], v[170:173], v[186:189], v[98:101]
	v_mfma_f32_16x16x32_bf16 v[102:105], v[150:153], v[186:189], v[102:105]
	v_mfma_f32_16x16x32_bf16 v[86:89], v[150:153], v[194:197], v[86:89]
	v_mfma_f32_16x16x32_bf16 v[82:85], v[170:173], v[194:197], v[82:85]
	v_mfma_f32_16x16x32_bf16 v[66:69], v[170:173], v[202:205], v[66:69]
	v_mfma_f32_16x16x32_bf16 v[70:73], v[150:153], v[202:205], v[70:73]
	v_mfma_f32_16x16x32_bf16 v[118:121], v[166:169], v[182:185], v[118:121]
	v_mfma_f32_16x16x32_bf16 v[114:117], v[174:177], v[182:185], v[114:117]
	v_mfma_f32_16x16x32_bf16 v[98:101], v[174:177], v[190:193], v[98:101]
	v_mfma_f32_16x16x32_bf16 v[102:105], v[166:169], v[190:193], v[102:105]
	v_mfma_f32_16x16x32_bf16 v[86:89], v[166:169], v[198:201], v[86:89]
	v_mfma_f32_16x16x32_bf16 v[82:85], v[174:177], v[198:201], v[82:85]
	v_mfma_f32_16x16x32_bf16 v[66:69], v[174:177], v[206:209], v[66:69]
	v_mfma_f32_16x16x32_bf16 v[70:73], v[166:169], v[206:209], v[70:73]
	s_setprio 0
	s_barrier
	ds_read_b128 v[178:181], v162 offset:49152
	ds_read_b128 v[182:185], v162 offset:50176
	ds_read_b128 v[186:189], v162 offset:51200
	ds_read_b128 v[190:193], v162 offset:52224
	ds_read_b128 v[194:197], v162 offset:53248
	ds_read_b128 v[198:201], v162 offset:54272
	ds_read_b128 v[202:205], v162 offset:55296
	ds_read_b128 v[206:209], v162 offset:56320
	s_add_u32 s64, s62, 0x80
	s_addc_u32 s65, s63, 0
	s_mov_b32 m0, s30
	s_nop 0
	global_load_lds_dwordx4 v154, s[64:65]
	s_add_u32 s62, s62, 0x2b0080
	s_mov_b32 m0, s31
	s_nop 0
	global_load_lds_dwordx4 v156, s[64:65]
	s_addc_u32 s63, s63, 0
	s_mov_b32 m0, s67
	s_nop 0
	global_load_lds_dwordx4 v154, s[62:63]
	s_nop 0
	s_mov_b32 m0, s68
	s_nop 0
	global_load_lds_dwordx4 v156, s[62:63]
	s_nop 0
	s_mov_b32 m0, s33
	s_nop 0
	global_load_lds_dwordx4 v1, s[60:61]
	s_nop 0
	s_mov_b32 m0, s66
	s_nop 0
	global_load_lds_dwordx4 v155, s[60:61]
	s_waitcnt vmcnt(8)
	s_waitcnt lgkmcnt(0)
	s_barrier
	s_setprio 1
	s_waitcnt lgkmcnt(7)
	v_mfma_f32_16x16x32_bf16 v[62:65], v[130:133], v[178:181], v[62:65]
	v_mfma_f32_16x16x32_bf16 v[58:61], v[142:145], v[178:181], v[58:61]
	s_waitcnt lgkmcnt(5)
	v_mfma_f32_16x16x32_bf16 v[42:45], v[142:145], v[186:189], v[42:45]
	v_mfma_f32_16x16x32_bf16 v[46:49], v[130:133], v[186:189], v[46:49]
	s_waitcnt lgkmcnt(3)
	v_mfma_f32_16x16x32_bf16 v[30:33], v[130:133], v[194:197], v[30:33]
	v_mfma_f32_16x16x32_bf16 v[26:29], v[142:145], v[194:197], v[26:29]
	s_waitcnt lgkmcnt(1)
	v_mfma_f32_16x16x32_bf16 v[10:13], v[142:145], v[202:205], v[10:13]
	v_mfma_f32_16x16x32_bf16 v[14:17], v[130:133], v[202:205], v[14:17]
	v_mfma_f32_16x16x32_bf16 v[62:65], v[134:137], v[182:185], v[62:65]
	v_mfma_f32_16x16x32_bf16 v[58:61], v[146:149], v[182:185], v[58:61]
	v_mfma_f32_16x16x32_bf16 v[42:45], v[146:149], v[190:193], v[42:45]
	v_mfma_f32_16x16x32_bf16 v[46:49], v[134:137], v[190:193], v[46:49]
	v_mfma_f32_16x16x32_bf16 v[30:33], v[134:137], v[198:201], v[30:33]
	v_mfma_f32_16x16x32_bf16 v[26:29], v[146:149], v[198:201], v[26:29]
	s_waitcnt lgkmcnt(0)
	v_mfma_f32_16x16x32_bf16 v[10:13], v[146:149], v[206:209], v[10:13]
	v_mfma_f32_16x16x32_bf16 v[14:17], v[134:137], v[206:209], v[14:17]
	s_setprio 0
	s_setprio 1
	v_mfma_f32_16x16x32_bf16 v[54:57], v[150:153], v[178:181], v[54:57]
	v_mfma_f32_16x16x32_bf16 v[50:53], v[170:173], v[178:181], v[50:53]
	v_mfma_f32_16x16x32_bf16 v[34:37], v[170:173], v[186:189], v[34:37]
	v_mfma_f32_16x16x32_bf16 v[38:41], v[150:153], v[186:189], v[38:41]
	v_mfma_f32_16x16x32_bf16 v[22:25], v[150:153], v[194:197], v[22:25]
	v_mfma_f32_16x16x32_bf16 v[18:21], v[170:173], v[194:197], v[18:21]
	v_mfma_f32_16x16x32_bf16 v[2:5], v[170:173], v[202:205], v[2:5]
	v_mfma_f32_16x16x32_bf16 v[6:9], v[150:153], v[202:205], v[6:9]
	v_mfma_f32_16x16x32_bf16 v[54:57], v[166:169], v[182:185], v[54:57]
	v_mfma_f32_16x16x32_bf16 v[50:53], v[174:177], v[182:185], v[50:53]
	v_mfma_f32_16x16x32_bf16 v[34:37], v[174:177], v[190:193], v[34:37]
	v_mfma_f32_16x16x32_bf16 v[38:41], v[166:169], v[190:193], v[38:41]
	v_mfma_f32_16x16x32_bf16 v[22:25], v[166:169], v[198:201], v[22:25]
	v_mfma_f32_16x16x32_bf16 v[18:21], v[174:177], v[198:201], v[18:21]
	v_mfma_f32_16x16x32_bf16 v[2:5], v[174:177], v[206:209], v[2:5]
	v_mfma_f32_16x16x32_bf16 v[6:9], v[166:169], v[206:209], v[6:9]
	s_setprio 0
	s_barrier
	s_add_i32 s78, s78, 2
	s_add_u32 s74, s74, 0x100
	s_addc_u32 s75, s75, 0
	s_add_u32 s76, s76, 0x100
	s_addc_u32 s77, s77, 0
	s_add_u32 s58, s58, 0x100
	s_addc_u32 s59, s59, 0
	s_cmpk_gt_u32 s78, 0xa9
	s_cbranch_scc0 .LBB0_1361
	s_and_b64 vcc, exec, s[36:37]
	s_cbranch_vccz .LBB0_1364
	s_barrier
